# Barrier ending each MFMA burst signalled three MFMAs early with the tail at priority 2
# speedup vs baseline: 1.0060x; 1.0060x over previous
; #define PG8_STAGE(bufoff, gbase, voff) do { _Pragma("unroll") for (int _i = 0; _i < 2; ++_i) \
;         __builtin_amdgcn_global_load_lds((const unsigned*)((const char*)(gbase) + (voff)[_i]), (PG8_LAS unsigned*)(lds + (bufoff) + ldsw + _i * 8192), 16, 0, 0); } while (0)
; #define PG8_LDA(dst, b, h) do { _Pragma("unroll") for (int m = 0; m < 4; ++m) _Pragma("unroll") for (int k = 0; k < 2; ++k) dst[m][k] = *(const PG8_LAS bf16x8*)(lds + PG8_SA(b, h) + aoff + m * 2048 + k * 1024); } while (0)
; #define PG8_LDB(dst, b, h) do { _Pragma("unroll") for (int n = 0; n < 2; ++n) _Pragma("unroll") for (int k = 0; k < 2; ++k) dst[n][k] = *(const PG8_LAS bf16x8*)(lds + PG8_SB(b, h) + boff + n * 2048 + k * 1024); } while (0)
; #define PG8_MMA(ai, bj, At, Bt) do { __builtin_amdgcn_s_setprio(1); _Pragma("unroll") for (int m = 0; m < 4; ++m) _Pragma("unroll") for (int n = 0; n < 2; ++n) _Pragma("unroll") for (int k = 0; k < 2; ++k) \
;         acc[ai][bj][m][n] = __builtin_amdgcn_mfma_f32_16x16x32_bf16(Bt[n][k], At[m][k], acc[ai][bj][m][n], 0, 0, 0); __builtin_amdgcn_s_setprio(0); } while (0)
; #define PG8_WAIT_V(n) asm volatile("s_waitcnt vmcnt(" #n ")" ::: "memory")
; #define PG8_WAIT_L(n) asm volatile("s_waitcnt lgkmcnt(" #n ")" ::: "memory")
; #define PG8_BAR __builtin_amdgcn_s_barrier()
; template <class Epi, class Sched, bool ALIGN_EPI = false, bool SP2 = false>
; __device__ __forceinline__ void gemm_phase(PG8_LAS unsigned char* lds, const Gemm g, const Sched& S, const Epi& E) {
;     ...
;             const bool last = (t == nt - 2);
;             const char* a1 = cA + (size_t)(t + 1) * kstep;
;             const char* a2 = last ? nA : cA + (size_t)(t + 2) * kstep; const char* b2 = last ? nB : cB + (size_t)(t + 2) * kstep;
;             const char* a3 = a2 + kstep; const char* b3 = b2 + kstep;
;             if constexpr (SP2) {
;             PG8_LDB(B0, 0, 0); PG8_LDB(B1, 0, 1); PG8_SCHED; PG8_LDA(At, 0, 0); PG8_STAGE(PG8_SA(1, 1), a1 + hstep, voffA);
;             PG8_WAIT_V(8); PG8_WAIT_L(0); PG8_BAR; PG8_MMA(0, 0, At, B0); PG8_MMA(0, 1, At, B1); PG8_BAR; PG8_SCHED;
;             PG8_LDA(At, 0, 1); PG8_STAGE(PG8_SB(0, 0), b2, voffB); PG8_STAGE(PG8_SB(0, 1), b2 + hstep, voffB); PG8_STAGE(PG8_SA(0, 0), a2, voffA);
;             PG8_WAIT_V(8); PG8_WAIT_L(0); PG8_BAR; PG8_MMA(1, 0, At, B0); PG8_MMA(1, 1, At, B1); PG8_BAR; PG8_SCHED;
.LBB0_200:
	ds_read_b128 v[148:151], v164
	ds_read_b128 v[152:155], v164 offset:1024
	ds_read_b128 v[156:159], v164 offset:2048
	ds_read_b128 v[168:171], v164 offset:3072
	ds_read_b128 v[172:175], v165
	ds_read_b128 v[176:179], v165 offset:1024
	ds_read_b128 v[180:183], v165 offset:2048
	ds_read_b128 v[184:187], v165 offset:3072
	s_add_u32 s52, s70, 0xfff80080
	s_addc_u32 s53, s71, -1
	s_cmp_eq_u32 s93, 28
	s_cselect_b32 s75, s39, s53
	s_cselect_b32 s74, s69, s52
	s_cselect_b32 s73, s35, s92
	s_cselect_b32 s72, s90, s91
	v_lshl_add_u64 v[220:221], s[70:71], 0, v[138:139]
	s_add_i32 m0, s33, 0xc000
	ds_read_b128 v[188:191], v166
	ds_read_b128 v[192:195], v166 offset:1024
	ds_read_b128 v[196:199], v166 offset:2048
	ds_read_b128 v[200:203], v166 offset:3072
	ds_read_b128 v[204:207], v166 offset:4096
	ds_read_b128 v[208:211], v166 offset:5120
	ds_read_b128 v[212:215], v166 offset:6144
	ds_read_b128 v[216:219], v166 offset:7168
	global_load_lds_dwordx4 v[220:221], off
	v_lshl_add_u64 v[220:221], s[70:71], 0, v[140:141]
	s_add_i32 m0, s33, 0xe000
	s_nop 0
	global_load_lds_dwordx4 v[220:221], off
	s_waitcnt vmcnt(8)
	s_waitcnt lgkmcnt(0)
	s_barrier
	s_setprio 1
	s_waitcnt lgkmcnt(0)
	v_mfma_f32_16x16x32_bf16 v[124:127], v[148:151], v[188:191], v[124:127]
	v_mfma_f32_16x16x32_bf16 v[120:123], v[156:159], v[188:191], v[120:123]
	v_mfma_f32_16x16x32_bf16 v[116:119], v[148:151], v[196:199], v[116:119]
	v_mfma_f32_16x16x32_bf16 v[108:111], v[156:159], v[196:199], v[108:111]
	v_mfma_f32_16x16x32_bf16 v[100:103], v[148:151], v[204:207], v[100:103]
	v_mfma_f32_16x16x32_bf16 v[92:95], v[156:159], v[204:207], v[92:95]
	v_mfma_f32_16x16x32_bf16 v[84:87], v[148:151], v[212:215], v[84:87]
	v_mfma_f32_16x16x32_bf16 v[76:79], v[156:159], v[212:215], v[76:79]
	v_mfma_f32_16x16x32_bf16 v[124:127], v[152:155], v[192:195], v[124:127]
	v_mfma_f32_16x16x32_bf16 v[120:123], v[168:171], v[192:195], v[120:123]
	v_mfma_f32_16x16x32_bf16 v[116:119], v[152:155], v[200:203], v[116:119]
	v_mfma_f32_16x16x32_bf16 v[108:111], v[168:171], v[200:203], v[108:111]
	v_mfma_f32_16x16x32_bf16 v[100:103], v[152:155], v[208:211], v[100:103]
	v_mfma_f32_16x16x32_bf16 v[92:95], v[168:171], v[208:211], v[92:95]
	v_mfma_f32_16x16x32_bf16 v[84:87], v[152:155], v[216:219], v[84:87]
	v_mfma_f32_16x16x32_bf16 v[76:79], v[168:171], v[216:219], v[76:79]
	s_setprio 0
	s_setprio 1
	v_mfma_f32_16x16x32_bf16 v[112:115], v[172:175], v[188:191], v[112:115]
	v_mfma_f32_16x16x32_bf16 v[104:107], v[180:183], v[188:191], v[104:107]
	v_mfma_f32_16x16x32_bf16 v[96:99], v[172:175], v[196:199], v[96:99]
	v_mfma_f32_16x16x32_bf16 v[88:91], v[180:183], v[196:199], v[88:91]
	v_mfma_f32_16x16x32_bf16 v[80:83], v[172:175], v[204:207], v[80:83]
	v_mfma_f32_16x16x32_bf16 v[72:75], v[180:183], v[204:207], v[72:75]
	v_mfma_f32_16x16x32_bf16 v[68:71], v[172:175], v[212:215], v[68:71]
	v_mfma_f32_16x16x32_bf16 v[64:67], v[180:183], v[212:215], v[64:67]
	v_mfma_f32_16x16x32_bf16 v[112:115], v[176:179], v[192:195], v[112:115]
	v_mfma_f32_16x16x32_bf16 v[104:107], v[184:187], v[192:195], v[104:107]
	v_mfma_f32_16x16x32_bf16 v[96:99], v[176:179], v[200:203], v[96:99]
	v_mfma_f32_16x16x32_bf16 v[88:91], v[184:187], v[200:203], v[88:91]
	v_mfma_f32_16x16x32_bf16 v[80:83], v[176:179], v[208:211], v[80:83]
	s_setprio 2
	s_barrier
	v_mfma_f32_16x16x32_bf16 v[72:75], v[184:187], v[208:211], v[72:75]
	v_mfma_f32_16x16x32_bf16 v[68:71], v[176:179], v[216:219], v[68:71]
	v_mfma_f32_16x16x32_bf16 v[64:67], v[184:187], v[216:219], v[64:67]
	s_setprio 0
	s_add_i32 s52, s84, s3
	v_lshl_add_u64 v[220:221], s[72:73], 0, v[132:133]
	s_mov_b32 m0, s52
	ds_read_b128 v[188:191], v166 offset:16384
	ds_read_b128 v[192:195], v166 offset:17408
	ds_read_b128 v[196:199], v166 offset:18432
	ds_read_b128 v[200:203], v166 offset:19456
	ds_read_b128 v[204:207], v166 offset:20480
	ds_read_b128 v[208:211], v166 offset:21504
	ds_read_b128 v[212:215], v166 offset:22528
	ds_read_b128 v[216:219], v166 offset:23552
	global_load_lds_dwordx4 v[220:221], off
	s_add_i32 m0, s52, 0x2000
	s_add_u32 s96, s72, 0x80000
	v_lshl_add_u64 v[222:223], s[72:73], 0, v[128:129]
	s_addc_u32 s97, s73, 0
	s_add_i32 s52, s85, s3
	global_load_lds_dwordx4 v[222:223], off
	v_lshl_add_u64 v[224:225], s[96:97], 0, v[132:133]
	s_mov_b32 m0, s52
	v_lshl_add_u64 v[226:227], s[74:75], 0, v[130:131]
	global_load_lds_dwordx4 v[224:225], off
	v_lshl_add_u64 v[224:225], s[96:97], 0, v[128:129]
	s_add_i32 m0, s52, 0x2000
	s_nop 0
	global_load_lds_dwordx4 v[224:225], off
	v_lshl_add_u64 v[224:225], s[74:75], 0, v[134:135]
	s_mov_b32 m0, s33
	s_nop 0
	global_load_lds_dwordx4 v[224:225], off
	s_mov_b32 m0, s76
	s_nop 0
	global_load_lds_dwordx4 v[226:227], off
	s_waitcnt vmcnt(8)
	s_waitcnt lgkmcnt(0)
	s_barrier
; #define PG8_STAGE(bufoff, gbase, voff) do { _Pragma("unroll") for (int _i = 0; _i < 2; ++_i) \
;         __builtin_amdgcn_global_load_lds((const unsigned*)((const char*)(gbase) + (voff)[_i]), (PG8_LAS unsigned*)(lds + (bufoff) + ldsw + _i * 8192), 16, 0, 0); } while (0)
; #define PG8_LDA(dst, b, h) do { _Pragma("unroll") for (int m = 0; m < 4; ++m) _Pragma("unroll") for (int k = 0; k < 2; ++k) dst[m][k] = *(const PG8_LAS bf16x8*)(lds + PG8_SA(b, h) + aoff + m * 2048 + k * 1024); } while (0)
; #define PG8_LDB(dst, b, h) do { _Pragma("unroll") for (int n = 0; n < 2; ++n) _Pragma("unroll") for (int k = 0; k < 2; ++k) dst[n][k] = *(const PG8_LAS bf16x8*)(lds + PG8_SB(b, h) + boff + n * 2048 + k * 1024); } while (0)
; #define PG8_MMA(ai, bj, At, Bt) do { __builtin_amdgcn_s_setprio(1); _Pragma("unroll") for (int m = 0; m < 4; ++m) _Pragma("unroll") for (int n = 0; n < 2; ++n) _Pragma("unroll") for (int k = 0; k < 2; ++k) \
;         acc[ai][bj][m][n] = __builtin_amdgcn_mfma_f32_16x16x32_bf16(Bt[n][k], At[m][k], acc[ai][bj][m][n], 0, 0, 0); __builtin_amdgcn_s_setprio(0); } while (0)
; #define PG8_WAIT_V(n) asm volatile("s_waitcnt vmcnt(" #n ")" ::: "memory")
; #define PG8_WAIT_L(n) asm volatile("s_waitcnt lgkmcnt(" #n ")" ::: "memory")
; #define PG8_BAR __builtin_amdgcn_s_barrier()
; #define PG8_SCHED __builtin_amdgcn_sched_barrier(0)
; template <class Epi, class Sched, bool ALIGN_EPI = false, bool SP2 = false>
; __device__ __forceinline__ void gemm_phase(PG8_LAS unsigned char* lds, const Gemm g, const Sched& S, const Epi& E) {
;     ...
;             PG8_WAIT_V(8); PG8_WAIT_L(0); PG8_BAR; PG8_MMA(1, 0, At, B0); PG8_MMA(1, 1, At, B1); PG8_BAR; PG8_SCHED;
;             PG8_LDB(B0, 1, 0); PG8_LDB(B1, 1, 1); PG8_SCHED; PG8_LDA(At, 1, 0); PG8_STAGE(PG8_SA(0, 1), a2 + hstep, voffA);
;             PG8_WAIT_V(8); PG8_WAIT_L(0); PG8_BAR; PG8_MMA(0, 0, At, B0); PG8_MMA(0, 1, At, B1); PG8_BAR; PG8_SCHED;
	s_setprio 1
	s_waitcnt lgkmcnt(0)
	v_mfma_f32_16x16x32_bf16 v[60:63], v[148:151], v[188:191], v[60:63]
	v_mfma_f32_16x16x32_bf16 v[56:59], v[156:159], v[188:191], v[56:59]
	v_mfma_f32_16x16x32_bf16 v[52:55], v[148:151], v[196:199], v[52:55]
	v_mfma_f32_16x16x32_bf16 v[44:47], v[156:159], v[196:199], v[44:47]
	v_mfma_f32_16x16x32_bf16 v[36:39], v[148:151], v[204:207], v[36:39]
	v_mfma_f32_16x16x32_bf16 v[28:31], v[156:159], v[204:207], v[28:31]
	v_mfma_f32_16x16x32_bf16 v[20:23], v[148:151], v[212:215], v[20:23]
	v_mfma_f32_16x16x32_bf16 v[12:15], v[156:159], v[212:215], v[12:15]
	v_mfma_f32_16x16x32_bf16 v[60:63], v[152:155], v[192:195], v[60:63]
	v_mfma_f32_16x16x32_bf16 v[56:59], v[168:171], v[192:195], v[56:59]
	v_mfma_f32_16x16x32_bf16 v[52:55], v[152:155], v[200:203], v[52:55]
	v_mfma_f32_16x16x32_bf16 v[44:47], v[168:171], v[200:203], v[44:47]
	v_mfma_f32_16x16x32_bf16 v[36:39], v[152:155], v[208:211], v[36:39]
	v_mfma_f32_16x16x32_bf16 v[28:31], v[168:171], v[208:211], v[28:31]
	v_mfma_f32_16x16x32_bf16 v[20:23], v[152:155], v[216:219], v[20:23]
	v_mfma_f32_16x16x32_bf16 v[12:15], v[168:171], v[216:219], v[12:15]
	s_setprio 0
	s_setprio 1
	v_mfma_f32_16x16x32_bf16 v[48:51], v[172:175], v[188:191], v[48:51]
	v_mfma_f32_16x16x32_bf16 v[40:43], v[180:183], v[188:191], v[40:43]
	v_mfma_f32_16x16x32_bf16 v[32:35], v[172:175], v[196:199], v[32:35]
	v_mfma_f32_16x16x32_bf16 v[24:27], v[180:183], v[196:199], v[24:27]
	v_mfma_f32_16x16x32_bf16 v[16:19], v[172:175], v[204:207], v[16:19]
	v_mfma_f32_16x16x32_bf16 v[8:11], v[180:183], v[204:207], v[8:11]
	v_mfma_f32_16x16x32_bf16 v[4:7], v[172:175], v[212:215], v[4:7]
	v_mfma_f32_16x16x32_bf16 v[0:3], v[180:183], v[212:215], v[0:3]
	v_mfma_f32_16x16x32_bf16 v[48:51], v[176:179], v[192:195], v[48:51]
	v_mfma_f32_16x16x32_bf16 v[40:43], v[184:187], v[192:195], v[40:43]
	v_mfma_f32_16x16x32_bf16 v[32:35], v[176:179], v[200:203], v[32:35]
	v_mfma_f32_16x16x32_bf16 v[24:27], v[184:187], v[200:203], v[24:27]
	v_mfma_f32_16x16x32_bf16 v[16:19], v[176:179], v[208:211], v[16:19]
	s_setprio 2
	s_barrier
	v_mfma_f32_16x16x32_bf16 v[8:11], v[184:187], v[208:211], v[8:11]
	v_mfma_f32_16x16x32_bf16 v[4:7], v[176:179], v[216:219], v[4:7]
	v_mfma_f32_16x16x32_bf16 v[0:3], v[184:187], v[216:219], v[0:3]
	s_setprio 0
	s_add_i32 s52, 0, 0x18000
	v_add_u32_e32 v136, s52, v161
	s_add_i32 s53, 0, 0x1c000
	ds_read_b128 v[148:151], v136
	ds_read_b128 v[152:155], v136 offset:1024
	ds_read_b128 v[156:159], v136 offset:2048
	ds_read_b128 v[168:171], v136 offset:3072
	v_add_u32_e32 v136, s53, v161
	ds_read_b128 v[172:175], v136
	ds_read_b128 v[176:179], v136 offset:1024
	ds_read_b128 v[180:183], v136 offset:2048
	ds_read_b128 v[184:187], v136 offset:3072
	s_add_u32 s74, s74, 0x80000
	s_addc_u32 s75, s75, 0
	s_mov_b32 m0, s77
	v_lshl_add_u64 v[228:229], s[74:75], 0, v[134:135]
	ds_read_b128 v[188:191], v166 offset:32768
	ds_read_b128 v[192:195], v166 offset:33792
	ds_read_b128 v[196:199], v166 offset:34816
	ds_read_b128 v[200:203], v166 offset:35840
	ds_read_b128 v[204:207], v166 offset:36864
	ds_read_b128 v[208:211], v166 offset:37888
	ds_read_b128 v[212:215], v166 offset:38912
	ds_read_b128 v[216:219], v166 offset:39936
	global_load_lds_dwordx4 v[228:229], off
	v_lshl_add_u64 v[228:229], s[74:75], 0, v[130:131]
	s_mov_b32 m0, s78
	s_nop 0
	global_load_lds_dwordx4 v[228:229], off
	s_waitcnt vmcnt(8)
	s_waitcnt lgkmcnt(0)
	s_barrier
	s_setprio 1
	s_waitcnt lgkmcnt(0)
	v_mfma_f32_16x16x32_bf16 v[124:127], v[148:151], v[188:191], v[124:127]
	v_mfma_f32_16x16x32_bf16 v[120:123], v[156:159], v[188:191], v[120:123]
	v_mfma_f32_16x16x32_bf16 v[116:119], v[148:151], v[196:199], v[116:119]
	v_mfma_f32_16x16x32_bf16 v[108:111], v[156:159], v[196:199], v[108:111]
	v_mfma_f32_16x16x32_bf16 v[100:103], v[148:151], v[204:207], v[100:103]
	v_mfma_f32_16x16x32_bf16 v[92:95], v[156:159], v[204:207], v[92:95]
	v_mfma_f32_16x16x32_bf16 v[84:87], v[148:151], v[212:215], v[84:87]
	v_mfma_f32_16x16x32_bf16 v[76:79], v[156:159], v[212:215], v[76:79]
	v_mfma_f32_16x16x32_bf16 v[124:127], v[152:155], v[192:195], v[124:127]
	v_mfma_f32_16x16x32_bf16 v[120:123], v[168:171], v[192:195], v[120:123]
	v_mfma_f32_16x16x32_bf16 v[116:119], v[152:155], v[200:203], v[116:119]
	v_mfma_f32_16x16x32_bf16 v[108:111], v[168:171], v[200:203], v[108:111]
	v_mfma_f32_16x16x32_bf16 v[100:103], v[152:155], v[208:211], v[100:103]
	v_mfma_f32_16x16x32_bf16 v[92:95], v[168:171], v[208:211], v[92:95]
	v_mfma_f32_16x16x32_bf16 v[84:87], v[152:155], v[216:219], v[84:87]
	v_mfma_f32_16x16x32_bf16 v[76:79], v[168:171], v[216:219], v[76:79]
	s_setprio 0
	s_setprio 1
	v_mfma_f32_16x16x32_bf16 v[112:115], v[172:175], v[188:191], v[112:115]
	v_mfma_f32_16x16x32_bf16 v[104:107], v[180:183], v[188:191], v[104:107]
	v_mfma_f32_16x16x32_bf16 v[96:99], v[172:175], v[196:199], v[96:99]
	v_mfma_f32_16x16x32_bf16 v[88:91], v[180:183], v[196:199], v[88:91]
	v_mfma_f32_16x16x32_bf16 v[80:83], v[172:175], v[204:207], v[80:83]
	v_mfma_f32_16x16x32_bf16 v[72:75], v[180:183], v[204:207], v[72:75]
	v_mfma_f32_16x16x32_bf16 v[68:71], v[172:175], v[212:215], v[68:71]
	v_mfma_f32_16x16x32_bf16 v[64:67], v[180:183], v[212:215], v[64:67]
	v_mfma_f32_16x16x32_bf16 v[112:115], v[176:179], v[192:195], v[112:115]
	v_mfma_f32_16x16x32_bf16 v[104:107], v[184:187], v[192:195], v[104:107]
	v_mfma_f32_16x16x32_bf16 v[96:99], v[176:179], v[200:203], v[96:99]
	v_mfma_f32_16x16x32_bf16 v[88:91], v[184:187], v[200:203], v[88:91]
	v_mfma_f32_16x16x32_bf16 v[80:83], v[176:179], v[208:211], v[80:83]
	s_setprio 2
	s_barrier
; #define PG8_STAGE(bufoff, gbase, voff) do { _Pragma("unroll") for (int _i = 0; _i < 2; ++_i) \
;         __builtin_amdgcn_global_load_lds((const unsigned*)((const char*)(gbase) + (voff)[_i]), (PG8_LAS unsigned*)(lds + (bufoff) + ldsw + _i * 8192), 16, 0, 0); } while (0)
; #define PG8_LDA(dst, b, h) do { _Pragma("unroll") for (int m = 0; m < 4; ++m) _Pragma("unroll") for (int k = 0; k < 2; ++k) dst[m][k] = *(const PG8_LAS bf16x8*)(lds + PG8_SA(b, h) + aoff + m * 2048 + k * 1024); } while (0)
; #define PG8_MMA(ai, bj, At, Bt) do { __builtin_amdgcn_s_setprio(1); _Pragma("unroll") for (int m = 0; m < 4; ++m) _Pragma("unroll") for (int n = 0; n < 2; ++n) _Pragma("unroll") for (int k = 0; k < 2; ++k) \
;         acc[ai][bj][m][n] = __builtin_amdgcn_mfma_f32_16x16x32_bf16(Bt[n][k], At[m][k], acc[ai][bj][m][n], 0, 0, 0); __builtin_amdgcn_s_setprio(0); } while (0)
; #define PG8_WAIT_V(n) asm volatile("s_waitcnt vmcnt(" #n ")" ::: "memory")
; #define PG8_WAIT_L(n) asm volatile("s_waitcnt lgkmcnt(" #n ")" ::: "memory")
; #define PG8_BAR __builtin_amdgcn_s_barrier()
; #define PG8_SCHED __builtin_amdgcn_sched_barrier(0)
; template <class Epi, class Sched, bool ALIGN_EPI = false, bool SP2 = false>
; __device__ __forceinline__ void gemm_phase(PG8_LAS unsigned char* lds, const Gemm g, const Sched& S, const Epi& E) {
;     ...
;             PG8_WAIT_V(8); PG8_WAIT_L(0); PG8_BAR; PG8_MMA(0, 0, At, B0); PG8_MMA(0, 1, At, B1); PG8_BAR; PG8_SCHED;
;             PG8_LDA(At, 1, 1); PG8_STAGE(PG8_SB(1, 0), b3, voffB); PG8_STAGE(PG8_SB(1, 1), b3 + hstep, voffB); PG8_STAGE(PG8_SA(1, 0), a3, voffA);
;             PG8_WAIT_V(8); PG8_WAIT_L(0); PG8_BAR; PG8_MMA(1, 0, At, B0); PG8_MMA(1, 1, At, B1); PG8_BAR; PG8_SCHED;
	v_mfma_f32_16x16x32_bf16 v[72:75], v[184:187], v[208:211], v[72:75]
	v_mfma_f32_16x16x32_bf16 v[68:71], v[176:179], v[216:219], v[68:71]
	v_mfma_f32_16x16x32_bf16 v[64:67], v[184:187], v[216:219], v[64:67]
	s_setprio 0
	s_add_i32 s52, s52, s3
	v_lshl_add_u64 v[220:221], v[220:221], 0, s[12:13]
	s_mov_b32 m0, s52
	ds_read_b128 v[188:191], v166 offset:49152
	ds_read_b128 v[192:195], v166 offset:50176
	ds_read_b128 v[196:199], v166 offset:51200
	ds_read_b128 v[200:203], v166 offset:52224
	ds_read_b128 v[204:207], v166 offset:53248
	ds_read_b128 v[208:211], v166 offset:54272
	ds_read_b128 v[212:215], v166 offset:55296
	ds_read_b128 v[216:219], v166 offset:56320
	global_load_lds_dwordx4 v[220:221], off
	s_add_i32 m0, s52, 0x2000
	s_add_u32 s72, s72, 0x80080
	v_lshl_add_u64 v[220:221], v[222:223], 0, s[12:13]
	s_addc_u32 s73, s73, 0
	s_add_i32 s52, s53, s3
	global_load_lds_dwordx4 v[220:221], off
	v_lshl_add_u64 v[220:221], s[72:73], 0, v[132:133]
	s_mov_b32 m0, s52
	s_nop 0
	global_load_lds_dwordx4 v[220:221], off
	v_lshl_add_u64 v[220:221], s[72:73], 0, v[128:129]
	s_add_i32 m0, s52, 0x2000
	s_nop 0
	global_load_lds_dwordx4 v[220:221], off
	v_lshl_add_u64 v[220:221], v[224:225], 0, s[12:13]
	s_mov_b32 m0, s80
	s_nop 0
	global_load_lds_dwordx4 v[220:221], off
	v_lshl_add_u64 v[220:221], v[226:227], 0, s[12:13]
	s_mov_b32 m0, s81
	s_nop 0
	global_load_lds_dwordx4 v[220:221], off
	s_waitcnt vmcnt(8)
	s_waitcnt lgkmcnt(0)
	s_barrier
	s_setprio 1
	s_waitcnt lgkmcnt(0)
	v_mfma_f32_16x16x32_bf16 v[60:63], v[148:151], v[188:191], v[60:63]
	v_mfma_f32_16x16x32_bf16 v[56:59], v[156:159], v[188:191], v[56:59]
	v_mfma_f32_16x16x32_bf16 v[52:55], v[148:151], v[196:199], v[52:55]
	v_mfma_f32_16x16x32_bf16 v[44:47], v[156:159], v[196:199], v[44:47]
	v_mfma_f32_16x16x32_bf16 v[36:39], v[148:151], v[204:207], v[36:39]
	v_mfma_f32_16x16x32_bf16 v[28:31], v[156:159], v[204:207], v[28:31]
	v_mfma_f32_16x16x32_bf16 v[20:23], v[148:151], v[212:215], v[20:23]
	v_mfma_f32_16x16x32_bf16 v[12:15], v[156:159], v[212:215], v[12:15]
	v_mfma_f32_16x16x32_bf16 v[60:63], v[152:155], v[192:195], v[60:63]
	v_mfma_f32_16x16x32_bf16 v[56:59], v[168:171], v[192:195], v[56:59]
	v_mfma_f32_16x16x32_bf16 v[52:55], v[152:155], v[200:203], v[52:55]
	v_mfma_f32_16x16x32_bf16 v[44:47], v[168:171], v[200:203], v[44:47]
	v_mfma_f32_16x16x32_bf16 v[36:39], v[152:155], v[208:211], v[36:39]
	v_mfma_f32_16x16x32_bf16 v[28:31], v[168:171], v[208:211], v[28:31]
	v_mfma_f32_16x16x32_bf16 v[20:23], v[152:155], v[216:219], v[20:23]
	v_mfma_f32_16x16x32_bf16 v[12:15], v[168:171], v[216:219], v[12:15]
	s_setprio 0
	s_setprio 1
	v_mfma_f32_16x16x32_bf16 v[48:51], v[172:175], v[188:191], v[48:51]
	v_mfma_f32_16x16x32_bf16 v[40:43], v[180:183], v[188:191], v[40:43]
	v_mfma_f32_16x16x32_bf16 v[32:35], v[172:175], v[196:199], v[32:35]
	v_mfma_f32_16x16x32_bf16 v[24:27], v[180:183], v[196:199], v[24:27]
	v_mfma_f32_16x16x32_bf16 v[16:19], v[172:175], v[204:207], v[16:19]
	v_mfma_f32_16x16x32_bf16 v[8:11], v[180:183], v[204:207], v[8:11]
	v_mfma_f32_16x16x32_bf16 v[4:7], v[172:175], v[212:215], v[4:7]
	v_mfma_f32_16x16x32_bf16 v[0:3], v[180:183], v[212:215], v[0:3]
	v_mfma_f32_16x16x32_bf16 v[48:51], v[176:179], v[192:195], v[48:51]
	v_mfma_f32_16x16x32_bf16 v[40:43], v[184:187], v[192:195], v[40:43]
	v_mfma_f32_16x16x32_bf16 v[32:35], v[176:179], v[200:203], v[32:35]
	v_mfma_f32_16x16x32_bf16 v[24:27], v[184:187], v[200:203], v[24:27]
	v_mfma_f32_16x16x32_bf16 v[16:19], v[176:179], v[208:211], v[16:19]
	s_setprio 2
	s_barrier
	v_mfma_f32_16x16x32_bf16 v[8:11], v[184:187], v[208:211], v[8:11]
	v_mfma_f32_16x16x32_bf16 v[4:7], v[176:179], v[216:219], v[4:7]
	v_mfma_f32_16x16x32_bf16 v[0:3], v[184:187], v[216:219], v[0:3]
	s_setprio 0
	s_add_i32 s93, s93, 2
	s_add_u32 s70, s70, 0x100
	s_addc_u32 s71, s71, 0
	s_add_u32 s91, s91, 0x100
	s_addc_u32 s92, s92, 0
	s_cmp_gt_u32 s93, 29
	s_cbranch_scc0 .LBB0_200
	s_and_b64 vcc, exec, s[14:15]
	s_cbranch_vccz .LBB0_203
	s_barrier

; #define PG8_STAGE(bufoff, gbase, voff) do { _Pragma("unroll") for (int _i = 0; _i < 2; ++_i) \
;         __builtin_amdgcn_global_load_lds((const unsigned*)((const char*)(gbase) + (voff)[_i]), (PG8_LAS unsigned*)(lds + (bufoff) + ldsw + _i * 8192), 16, 0, 0); } while (0)
; #define PG8_LDA(dst, b, h) do { _Pragma("unroll") for (int m = 0; m < 4; ++m) _Pragma("unroll") for (int k = 0; k < 2; ++k) dst[m][k] = *(const PG8_LAS bf16x8*)(lds + PG8_SA(b, h) + aoff + m * 2048 + k * 1024); } while (0)
; #define PG8_LDB(dst, b, h) do { _Pragma("unroll") for (int n = 0; n < 2; ++n) _Pragma("unroll") for (int k = 0; k < 2; ++k) dst[n][k] = *(const PG8_LAS bf16x8*)(lds + PG8_SB(b, h) + boff + n * 2048 + k * 1024); } while (0)
; #define PG8_MMA(ai, bj, At, Bt) do { __builtin_amdgcn_s_setprio(1); _Pragma("unroll") for (int m = 0; m < 4; ++m) _Pragma("unroll") for (int n = 0; n < 2; ++n) _Pragma("unroll") for (int k = 0; k < 2; ++k) \
;         acc[ai][bj][m][n] = __builtin_amdgcn_mfma_f32_16x16x32_bf16(Bt[n][k], At[m][k], acc[ai][bj][m][n], 0, 0, 0); __builtin_amdgcn_s_setprio(0); } while (0)
; #define PG8_WAIT_V(n) asm volatile("s_waitcnt vmcnt(" #n ")" ::: "memory")
; #define PG8_WAIT_L(n) asm volatile("s_waitcnt lgkmcnt(" #n ")" ::: "memory")
; #define PG8_BAR __builtin_amdgcn_s_barrier()
; template <class Epi, class Sched, bool ALIGN_EPI = false, bool SP2 = false>
; __device__ __forceinline__ void gemm_phase(PG8_LAS unsigned char* lds, const Gemm g, const Sched& S, const Epi& E) {
;     ...
;             const bool last = (t == nt - 2);
;             const char* a1 = cA + (size_t)(t + 1) * kstep;
;             const char* a2 = last ? nA : cA + (size_t)(t + 2) * kstep; const char* b2 = last ? nB : cB + (size_t)(t + 2) * kstep;
;             const char* a3 = a2 + kstep; const char* b3 = b2 + kstep;
;             if constexpr (SP2) {
;             PG8_LDB(B0, 0, 0); PG8_LDB(B1, 0, 1); PG8_SCHED; PG8_LDA(At, 0, 0); PG8_STAGE(PG8_SA(1, 1), a1 + hstep, voffA);
;             PG8_WAIT_V(8); PG8_WAIT_L(0); PG8_BAR; PG8_MMA(0, 0, At, B0); PG8_MMA(0, 1, At, B1); PG8_BAR; PG8_SCHED;
;             PG8_LDA(At, 0, 1); PG8_STAGE(PG8_SB(0, 0), b2, voffB); PG8_STAGE(PG8_SB(0, 1), b2 + hstep, voffB); PG8_STAGE(PG8_SA(0, 0), a2, voffA);
;             PG8_WAIT_V(8); PG8_WAIT_L(0); PG8_BAR; PG8_MMA(1, 0, At, B0); PG8_MMA(1, 1, At, B1); PG8_BAR; PG8_SCHED;
.LBB0_374:
	ds_read_b128 v[128:131], v230
	ds_read_b128 v[132:135], v230 offset:1024
	ds_read_b128 v[158:161], v230 offset:2048
	ds_read_b128 v[162:165], v230 offset:3072
	ds_read_b128 v[166:169], v231
	ds_read_b128 v[170:173], v231 offset:1024
	ds_read_b128 v[174:177], v231 offset:2048
	ds_read_b128 v[178:181], v231 offset:3072
	s_add_u32 s52, s76, 0xfff80080
	s_addc_u32 s53, s77, -1
	s_cmp_eq_u32 vcc_hi, 28
	s_cselect_b32 s81, s11, s53
	s_cselect_b32 s80, s55, s52
	s_cselect_b32 s79, s51, vcc_lo
	s_cselect_b32 s78, s73, s75
	v_lshl_add_u64 v[214:215], s[76:77], 0, v[150:151]
	s_add_i32 m0, s28, 0xc000
	ds_read_b128 v[182:185], v232
	ds_read_b128 v[186:189], v232 offset:1024
	ds_read_b128 v[190:193], v232 offset:2048
	ds_read_b128 v[194:197], v232 offset:3072
	ds_read_b128 v[198:201], v232 offset:4096
	ds_read_b128 v[202:205], v232 offset:5120
	ds_read_b128 v[206:209], v232 offset:6144
	ds_read_b128 v[210:213], v232 offset:7168
	global_load_lds_dwordx4 v[214:215], off
	v_lshl_add_u64 v[214:215], s[76:77], 0, v[152:153]
	s_add_i32 m0, s28, 0xe000
	s_nop 0
	global_load_lds_dwordx4 v[214:215], off
	s_waitcnt vmcnt(8)
	s_waitcnt lgkmcnt(0)
	s_barrier
	s_setprio 1
	s_waitcnt lgkmcnt(0)
	v_mfma_f32_16x16x32_bf16 v[124:127], v[128:131], v[182:185], v[124:127]
	v_mfma_f32_16x16x32_bf16 v[120:123], v[158:161], v[182:185], v[120:123]
	v_mfma_f32_16x16x32_bf16 v[116:119], v[128:131], v[190:193], v[116:119]
	v_mfma_f32_16x16x32_bf16 v[112:115], v[158:161], v[190:193], v[112:115]
	v_mfma_f32_16x16x32_bf16 v[108:111], v[128:131], v[198:201], v[108:111]
	v_mfma_f32_16x16x32_bf16 v[104:107], v[158:161], v[198:201], v[104:107]
	v_mfma_f32_16x16x32_bf16 v[100:103], v[128:131], v[206:209], v[100:103]
	v_mfma_f32_16x16x32_bf16 v[96:99], v[158:161], v[206:209], v[96:99]
	v_mfma_f32_16x16x32_bf16 v[124:127], v[132:135], v[186:189], v[124:127]
	v_mfma_f32_16x16x32_bf16 v[120:123], v[162:165], v[186:189], v[120:123]
	v_mfma_f32_16x16x32_bf16 v[116:119], v[132:135], v[194:197], v[116:119]
	v_mfma_f32_16x16x32_bf16 v[112:115], v[162:165], v[194:197], v[112:115]
	v_mfma_f32_16x16x32_bf16 v[108:111], v[132:135], v[202:205], v[108:111]
	v_mfma_f32_16x16x32_bf16 v[104:107], v[162:165], v[202:205], v[104:107]
	v_mfma_f32_16x16x32_bf16 v[100:103], v[132:135], v[210:213], v[100:103]
	v_mfma_f32_16x16x32_bf16 v[96:99], v[162:165], v[210:213], v[96:99]
	s_setprio 0
	s_setprio 1
	v_mfma_f32_16x16x32_bf16 v[60:63], v[166:169], v[182:185], v[60:63]
	v_mfma_f32_16x16x32_bf16 v[56:59], v[174:177], v[182:185], v[56:59]
	v_mfma_f32_16x16x32_bf16 v[52:55], v[166:169], v[190:193], v[52:55]
	v_mfma_f32_16x16x32_bf16 v[48:51], v[174:177], v[190:193], v[48:51]
	v_mfma_f32_16x16x32_bf16 v[44:47], v[166:169], v[198:201], v[44:47]
	v_mfma_f32_16x16x32_bf16 v[40:43], v[174:177], v[198:201], v[40:43]
	v_mfma_f32_16x16x32_bf16 v[36:39], v[166:169], v[206:209], v[36:39]
	v_mfma_f32_16x16x32_bf16 v[32:35], v[174:177], v[206:209], v[32:35]
	v_mfma_f32_16x16x32_bf16 v[60:63], v[170:173], v[186:189], v[60:63]
	v_mfma_f32_16x16x32_bf16 v[56:59], v[178:181], v[186:189], v[56:59]
	v_mfma_f32_16x16x32_bf16 v[52:55], v[170:173], v[194:197], v[52:55]
	v_mfma_f32_16x16x32_bf16 v[48:51], v[178:181], v[194:197], v[48:51]
	v_mfma_f32_16x16x32_bf16 v[44:47], v[170:173], v[202:205], v[44:47]
	s_setprio 2
	s_barrier
	v_mfma_f32_16x16x32_bf16 v[40:43], v[178:181], v[202:205], v[40:43]
	v_mfma_f32_16x16x32_bf16 v[36:39], v[170:173], v[210:213], v[36:39]
	v_mfma_f32_16x16x32_bf16 v[32:35], v[178:181], v[210:213], v[32:35]
	s_setprio 0
	s_add_i32 s52, s93, s3
	v_lshl_add_u64 v[214:215], s[78:79], 0, v[138:139]
	s_mov_b32 m0, s52
	ds_read_b128 v[182:185], v232 offset:16384
	ds_read_b128 v[186:189], v232 offset:17408
	ds_read_b128 v[190:193], v232 offset:18432
	ds_read_b128 v[194:197], v232 offset:19456
	ds_read_b128 v[198:201], v232 offset:20480
	ds_read_b128 v[202:205], v232 offset:21504
	ds_read_b128 v[206:209], v232 offset:22528
	ds_read_b128 v[210:213], v232 offset:23552
	global_load_lds_dwordx4 v[214:215], off
	s_add_i32 m0, s52, 0x2000
	s_add_u32 s52, s78, 0x80000
	v_lshl_add_u64 v[216:217], s[78:79], 0, v[142:143]
	s_addc_u32 s53, s79, 0
	s_add_i32 s56, s10, s3
	global_load_lds_dwordx4 v[216:217], off
	v_lshl_add_u64 v[218:219], s[52:53], 0, v[138:139]
	s_mov_b32 m0, s56
	v_lshl_add_u64 v[220:221], s[80:81], 0, v[140:141]
	global_load_lds_dwordx4 v[218:219], off
	v_lshl_add_u64 v[218:219], s[52:53], 0, v[142:143]
	s_add_i32 m0, s56, 0x2000
	s_nop 0
	global_load_lds_dwordx4 v[218:219], off
	v_lshl_add_u64 v[218:219], s[80:81], 0, v[136:137]
	s_mov_b32 m0, s28
	s_nop 0
	global_load_lds_dwordx4 v[218:219], off
	s_mov_b32 m0, s29
	s_nop 0
	global_load_lds_dwordx4 v[220:221], off
	s_waitcnt vmcnt(8)
	s_waitcnt lgkmcnt(0)
	s_barrier
; #define PG8_STAGE(bufoff, gbase, voff) do { _Pragma("unroll") for (int _i = 0; _i < 2; ++_i) \
;         __builtin_amdgcn_global_load_lds((const unsigned*)((const char*)(gbase) + (voff)[_i]), (PG8_LAS unsigned*)(lds + (bufoff) + ldsw + _i * 8192), 16, 0, 0); } while (0)
; #define PG8_LDA(dst, b, h) do { _Pragma("unroll") for (int m = 0; m < 4; ++m) _Pragma("unroll") for (int k = 0; k < 2; ++k) dst[m][k] = *(const PG8_LAS bf16x8*)(lds + PG8_SA(b, h) + aoff + m * 2048 + k * 1024); } while (0)
; #define PG8_LDB(dst, b, h) do { _Pragma("unroll") for (int n = 0; n < 2; ++n) _Pragma("unroll") for (int k = 0; k < 2; ++k) dst[n][k] = *(const PG8_LAS bf16x8*)(lds + PG8_SB(b, h) + boff + n * 2048 + k * 1024); } while (0)
; #define PG8_MMA(ai, bj, At, Bt) do { __builtin_amdgcn_s_setprio(1); _Pragma("unroll") for (int m = 0; m < 4; ++m) _Pragma("unroll") for (int n = 0; n < 2; ++n) _Pragma("unroll") for (int k = 0; k < 2; ++k) \
;         acc[ai][bj][m][n] = __builtin_amdgcn_mfma_f32_16x16x32_bf16(Bt[n][k], At[m][k], acc[ai][bj][m][n], 0, 0, 0); __builtin_amdgcn_s_setprio(0); } while (0)
; #define PG8_WAIT_V(n) asm volatile("s_waitcnt vmcnt(" #n ")" ::: "memory")
; #define PG8_WAIT_L(n) asm volatile("s_waitcnt lgkmcnt(" #n ")" ::: "memory")
; #define PG8_BAR __builtin_amdgcn_s_barrier()
; #define PG8_SCHED __builtin_amdgcn_sched_barrier(0)
; template <class Epi, class Sched, bool ALIGN_EPI = false, bool SP2 = false>
; __device__ __forceinline__ void gemm_phase(PG8_LAS unsigned char* lds, const Gemm g, const Sched& S, const Epi& E) {
;     ...
;             PG8_WAIT_V(8); PG8_WAIT_L(0); PG8_BAR; PG8_MMA(1, 0, At, B0); PG8_MMA(1, 1, At, B1); PG8_BAR; PG8_SCHED;
;             PG8_LDB(B0, 1, 0); PG8_LDB(B1, 1, 1); PG8_SCHED; PG8_LDA(At, 1, 0); PG8_STAGE(PG8_SA(0, 1), a2 + hstep, voffA);
;             PG8_WAIT_V(8); PG8_WAIT_L(0); PG8_BAR; PG8_MMA(0, 0, At, B0); PG8_MMA(0, 1, At, B1); PG8_BAR; PG8_SCHED;
	s_setprio 1
	s_waitcnt lgkmcnt(0)
	v_mfma_f32_16x16x32_bf16 v[92:95], v[128:131], v[182:185], v[92:95]
	v_mfma_f32_16x16x32_bf16 v[88:91], v[158:161], v[182:185], v[88:91]
	v_mfma_f32_16x16x32_bf16 v[84:87], v[128:131], v[190:193], v[84:87]
	v_mfma_f32_16x16x32_bf16 v[80:83], v[158:161], v[190:193], v[80:83]
	v_mfma_f32_16x16x32_bf16 v[76:79], v[128:131], v[198:201], v[76:79]
	v_mfma_f32_16x16x32_bf16 v[72:75], v[158:161], v[198:201], v[72:75]
	v_mfma_f32_16x16x32_bf16 v[68:71], v[128:131], v[206:209], v[68:71]
	v_mfma_f32_16x16x32_bf16 v[64:67], v[158:161], v[206:209], v[64:67]
	v_mfma_f32_16x16x32_bf16 v[92:95], v[132:135], v[186:189], v[92:95]
	v_mfma_f32_16x16x32_bf16 v[88:91], v[162:165], v[186:189], v[88:91]
	v_mfma_f32_16x16x32_bf16 v[84:87], v[132:135], v[194:197], v[84:87]
	v_mfma_f32_16x16x32_bf16 v[80:83], v[162:165], v[194:197], v[80:83]
	v_mfma_f32_16x16x32_bf16 v[76:79], v[132:135], v[202:205], v[76:79]
	v_mfma_f32_16x16x32_bf16 v[72:75], v[162:165], v[202:205], v[72:75]
	v_mfma_f32_16x16x32_bf16 v[68:71], v[132:135], v[210:213], v[68:71]
	v_mfma_f32_16x16x32_bf16 v[64:67], v[162:165], v[210:213], v[64:67]
	s_setprio 0
	s_setprio 1
	v_mfma_f32_16x16x32_bf16 v[28:31], v[166:169], v[182:185], v[28:31]
	v_mfma_f32_16x16x32_bf16 v[24:27], v[174:177], v[182:185], v[24:27]
	v_mfma_f32_16x16x32_bf16 v[20:23], v[166:169], v[190:193], v[20:23]
	v_mfma_f32_16x16x32_bf16 v[16:19], v[174:177], v[190:193], v[16:19]
	v_mfma_f32_16x16x32_bf16 v[12:15], v[166:169], v[198:201], v[12:15]
	v_mfma_f32_16x16x32_bf16 v[8:11], v[174:177], v[198:201], v[8:11]
	v_mfma_f32_16x16x32_bf16 v[4:7], v[166:169], v[206:209], v[4:7]
	v_mfma_f32_16x16x32_bf16 v[0:3], v[174:177], v[206:209], v[0:3]
	v_mfma_f32_16x16x32_bf16 v[28:31], v[170:173], v[186:189], v[28:31]
	v_mfma_f32_16x16x32_bf16 v[24:27], v[178:181], v[186:189], v[24:27]
	v_mfma_f32_16x16x32_bf16 v[20:23], v[170:173], v[194:197], v[20:23]
	v_mfma_f32_16x16x32_bf16 v[16:19], v[178:181], v[194:197], v[16:19]
	v_mfma_f32_16x16x32_bf16 v[12:15], v[170:173], v[202:205], v[12:15]
	s_setprio 2
	s_barrier
	v_mfma_f32_16x16x32_bf16 v[8:11], v[178:181], v[202:205], v[8:11]
	v_mfma_f32_16x16x32_bf16 v[4:7], v[170:173], v[210:213], v[4:7]
	v_mfma_f32_16x16x32_bf16 v[0:3], v[178:181], v[210:213], v[0:3]
	s_setprio 0
	s_add_i32 s56, 0, 0x18000
	s_add_i32 s57, 0, 0x1c000
	v_add_u32_e32 v162, s56, v228
	v_add_u32_e32 v178, s57, v228
	ds_read_b128 v[128:131], v162
	ds_read_b128 v[132:135], v162 offset:1024
	ds_read_b128 v[158:161], v162 offset:2048
	ds_read_b128 v[162:165], v162 offset:3072
	ds_read_b128 v[166:169], v178
	ds_read_b128 v[170:173], v178 offset:1024
	ds_read_b128 v[174:177], v178 offset:2048
	ds_read_b128 v[178:181], v178 offset:3072
	s_add_u32 s52, s80, 0x80000
	s_addc_u32 s53, s81, 0
	s_mov_b32 m0, s33
	v_lshl_add_u64 v[234:235], s[52:53], 0, v[136:137]
	ds_read_b128 v[182:185], v232 offset:32768
	ds_read_b128 v[186:189], v232 offset:33792
	ds_read_b128 v[190:193], v232 offset:34816
	ds_read_b128 v[194:197], v232 offset:35840
	ds_read_b128 v[198:201], v232 offset:36864
	ds_read_b128 v[202:205], v232 offset:37888
	ds_read_b128 v[206:209], v232 offset:38912
	ds_read_b128 v[210:213], v232 offset:39936
	global_load_lds_dwordx4 v[234:235], off
	v_lshl_add_u64 v[234:235], s[52:53], 0, v[140:141]
	s_mov_b32 m0, s38
	s_nop 0
	global_load_lds_dwordx4 v[234:235], off
	s_waitcnt vmcnt(8)
	s_waitcnt lgkmcnt(0)
	s_barrier
	s_setprio 1
	s_waitcnt lgkmcnt(0)
	v_mfma_f32_16x16x32_bf16 v[124:127], v[128:131], v[182:185], v[124:127]
	v_mfma_f32_16x16x32_bf16 v[120:123], v[158:161], v[182:185], v[120:123]
	v_mfma_f32_16x16x32_bf16 v[116:119], v[128:131], v[190:193], v[116:119]
	v_mfma_f32_16x16x32_bf16 v[112:115], v[158:161], v[190:193], v[112:115]
	v_mfma_f32_16x16x32_bf16 v[108:111], v[128:131], v[198:201], v[108:111]
	v_mfma_f32_16x16x32_bf16 v[104:107], v[158:161], v[198:201], v[104:107]
	v_mfma_f32_16x16x32_bf16 v[100:103], v[128:131], v[206:209], v[100:103]
	v_mfma_f32_16x16x32_bf16 v[96:99], v[158:161], v[206:209], v[96:99]
	v_mfma_f32_16x16x32_bf16 v[124:127], v[132:135], v[186:189], v[124:127]
	v_mfma_f32_16x16x32_bf16 v[120:123], v[162:165], v[186:189], v[120:123]
	v_mfma_f32_16x16x32_bf16 v[116:119], v[132:135], v[194:197], v[116:119]
	v_mfma_f32_16x16x32_bf16 v[112:115], v[162:165], v[194:197], v[112:115]
	v_mfma_f32_16x16x32_bf16 v[108:111], v[132:135], v[202:205], v[108:111]
	v_mfma_f32_16x16x32_bf16 v[104:107], v[162:165], v[202:205], v[104:107]
	v_mfma_f32_16x16x32_bf16 v[100:103], v[132:135], v[210:213], v[100:103]
	v_mfma_f32_16x16x32_bf16 v[96:99], v[162:165], v[210:213], v[96:99]
	s_setprio 0
	s_setprio 1
	v_mfma_f32_16x16x32_bf16 v[60:63], v[166:169], v[182:185], v[60:63]
	v_mfma_f32_16x16x32_bf16 v[56:59], v[174:177], v[182:185], v[56:59]
	v_mfma_f32_16x16x32_bf16 v[52:55], v[166:169], v[190:193], v[52:55]
	v_mfma_f32_16x16x32_bf16 v[48:51], v[174:177], v[190:193], v[48:51]
	v_mfma_f32_16x16x32_bf16 v[44:47], v[166:169], v[198:201], v[44:47]
	v_mfma_f32_16x16x32_bf16 v[40:43], v[174:177], v[198:201], v[40:43]
	v_mfma_f32_16x16x32_bf16 v[36:39], v[166:169], v[206:209], v[36:39]
	v_mfma_f32_16x16x32_bf16 v[32:35], v[174:177], v[206:209], v[32:35]
	v_mfma_f32_16x16x32_bf16 v[60:63], v[170:173], v[186:189], v[60:63]
	v_mfma_f32_16x16x32_bf16 v[56:59], v[178:181], v[186:189], v[56:59]
	v_mfma_f32_16x16x32_bf16 v[52:55], v[170:173], v[194:197], v[52:55]
	v_mfma_f32_16x16x32_bf16 v[48:51], v[178:181], v[194:197], v[48:51]
	v_mfma_f32_16x16x32_bf16 v[44:47], v[170:173], v[202:205], v[44:47]
	s_setprio 2
	s_barrier
; #define PG8_STAGE(bufoff, gbase, voff) do { _Pragma("unroll") for (int _i = 0; _i < 2; ++_i) \
;         __builtin_amdgcn_global_load_lds((const unsigned*)((const char*)(gbase) + (voff)[_i]), (PG8_LAS unsigned*)(lds + (bufoff) + ldsw + _i * 8192), 16, 0, 0); } while (0)
; #define PG8_LDA(dst, b, h) do { _Pragma("unroll") for (int m = 0; m < 4; ++m) _Pragma("unroll") for (int k = 0; k < 2; ++k) dst[m][k] = *(const PG8_LAS bf16x8*)(lds + PG8_SA(b, h) + aoff + m * 2048 + k * 1024); } while (0)
; #define PG8_MMA(ai, bj, At, Bt) do { __builtin_amdgcn_s_setprio(1); _Pragma("unroll") for (int m = 0; m < 4; ++m) _Pragma("unroll") for (int n = 0; n < 2; ++n) _Pragma("unroll") for (int k = 0; k < 2; ++k) \
;         acc[ai][bj][m][n] = __builtin_amdgcn_mfma_f32_16x16x32_bf16(Bt[n][k], At[m][k], acc[ai][bj][m][n], 0, 0, 0); __builtin_amdgcn_s_setprio(0); } while (0)
; #define PG8_WAIT_V(n) asm volatile("s_waitcnt vmcnt(" #n ")" ::: "memory")
; #define PG8_WAIT_L(n) asm volatile("s_waitcnt lgkmcnt(" #n ")" ::: "memory")
; #define PG8_BAR __builtin_amdgcn_s_barrier()
; #define PG8_SCHED __builtin_amdgcn_sched_barrier(0)
; template <class Epi, class Sched, bool ALIGN_EPI = false, bool SP2 = false>
; __device__ __forceinline__ void gemm_phase(PG8_LAS unsigned char* lds, const Gemm g, const Sched& S, const Epi& E) {
;     ...
;             PG8_WAIT_V(8); PG8_WAIT_L(0); PG8_BAR; PG8_MMA(0, 0, At, B0); PG8_MMA(0, 1, At, B1); PG8_BAR; PG8_SCHED;
;             PG8_LDA(At, 1, 1); PG8_STAGE(PG8_SB(1, 0), b3, voffB); PG8_STAGE(PG8_SB(1, 1), b3 + hstep, voffB); PG8_STAGE(PG8_SA(1, 0), a3, voffA);
;             PG8_WAIT_V(8); PG8_WAIT_L(0); PG8_BAR; PG8_MMA(1, 0, At, B0); PG8_MMA(1, 1, At, B1); PG8_BAR; PG8_SCHED;
	v_mfma_f32_16x16x32_bf16 v[40:43], v[178:181], v[202:205], v[40:43]
	v_mfma_f32_16x16x32_bf16 v[36:39], v[170:173], v[210:213], v[36:39]
	v_mfma_f32_16x16x32_bf16 v[32:35], v[178:181], v[210:213], v[32:35]
	s_setprio 0
	s_add_i32 s52, s56, s3
	v_lshl_add_u64 v[214:215], v[214:215], 0, s[14:15]
	s_mov_b32 m0, s52
	ds_read_b128 v[182:185], v232 offset:49152
	ds_read_b128 v[186:189], v232 offset:50176
	ds_read_b128 v[190:193], v232 offset:51200
	ds_read_b128 v[194:197], v232 offset:52224
	ds_read_b128 v[198:201], v232 offset:53248
	ds_read_b128 v[202:205], v232 offset:54272
	ds_read_b128 v[206:209], v232 offset:55296
	ds_read_b128 v[210:213], v232 offset:56320
	global_load_lds_dwordx4 v[214:215], off
	s_add_i32 m0, s52, 0x2000
	s_add_u32 s52, s78, 0x80080
	v_lshl_add_u64 v[214:215], v[216:217], 0, s[14:15]
	s_addc_u32 s53, s79, 0
	s_add_i32 s56, s57, s3
	global_load_lds_dwordx4 v[214:215], off
	v_lshl_add_u64 v[214:215], s[52:53], 0, v[138:139]
	s_mov_b32 m0, s56
	s_nop 0
	global_load_lds_dwordx4 v[214:215], off
	v_lshl_add_u64 v[214:215], s[52:53], 0, v[142:143]
	s_add_i32 m0, s56, 0x2000
	s_nop 0
	global_load_lds_dwordx4 v[214:215], off
	v_lshl_add_u64 v[214:215], v[218:219], 0, s[14:15]
	s_mov_b32 m0, s88
	s_nop 0
	global_load_lds_dwordx4 v[214:215], off
	v_lshl_add_u64 v[214:215], v[220:221], 0, s[14:15]
	s_mov_b32 m0, s89
	s_nop 0
	global_load_lds_dwordx4 v[214:215], off
	s_waitcnt vmcnt(8)
	s_waitcnt lgkmcnt(0)
	s_barrier
	s_setprio 1
	s_waitcnt lgkmcnt(0)
	v_mfma_f32_16x16x32_bf16 v[92:95], v[128:131], v[182:185], v[92:95]
	v_mfma_f32_16x16x32_bf16 v[88:91], v[158:161], v[182:185], v[88:91]
	v_mfma_f32_16x16x32_bf16 v[84:87], v[128:131], v[190:193], v[84:87]
	v_mfma_f32_16x16x32_bf16 v[80:83], v[158:161], v[190:193], v[80:83]
	v_mfma_f32_16x16x32_bf16 v[76:79], v[128:131], v[198:201], v[76:79]
	v_mfma_f32_16x16x32_bf16 v[72:75], v[158:161], v[198:201], v[72:75]
	v_mfma_f32_16x16x32_bf16 v[68:71], v[128:131], v[206:209], v[68:71]
	v_mfma_f32_16x16x32_bf16 v[64:67], v[158:161], v[206:209], v[64:67]
	v_mfma_f32_16x16x32_bf16 v[92:95], v[132:135], v[186:189], v[92:95]
	v_mfma_f32_16x16x32_bf16 v[88:91], v[162:165], v[186:189], v[88:91]
	v_mfma_f32_16x16x32_bf16 v[84:87], v[132:135], v[194:197], v[84:87]
	v_mfma_f32_16x16x32_bf16 v[80:83], v[162:165], v[194:197], v[80:83]
	v_mfma_f32_16x16x32_bf16 v[76:79], v[132:135], v[202:205], v[76:79]
	v_mfma_f32_16x16x32_bf16 v[72:75], v[162:165], v[202:205], v[72:75]
	v_mfma_f32_16x16x32_bf16 v[68:71], v[132:135], v[210:213], v[68:71]
	v_mfma_f32_16x16x32_bf16 v[64:67], v[162:165], v[210:213], v[64:67]
	s_setprio 0
	s_setprio 1
	v_mfma_f32_16x16x32_bf16 v[28:31], v[166:169], v[182:185], v[28:31]
	v_mfma_f32_16x16x32_bf16 v[24:27], v[174:177], v[182:185], v[24:27]
	v_mfma_f32_16x16x32_bf16 v[20:23], v[166:169], v[190:193], v[20:23]
	v_mfma_f32_16x16x32_bf16 v[16:19], v[174:177], v[190:193], v[16:19]
	v_mfma_f32_16x16x32_bf16 v[12:15], v[166:169], v[198:201], v[12:15]
	v_mfma_f32_16x16x32_bf16 v[8:11], v[174:177], v[198:201], v[8:11]
	v_mfma_f32_16x16x32_bf16 v[4:7], v[166:169], v[206:209], v[4:7]
	v_mfma_f32_16x16x32_bf16 v[0:3], v[174:177], v[206:209], v[0:3]
	v_mfma_f32_16x16x32_bf16 v[28:31], v[170:173], v[186:189], v[28:31]
	v_mfma_f32_16x16x32_bf16 v[24:27], v[178:181], v[186:189], v[24:27]
	v_mfma_f32_16x16x32_bf16 v[20:23], v[170:173], v[194:197], v[20:23]
	v_mfma_f32_16x16x32_bf16 v[16:19], v[178:181], v[194:197], v[16:19]
	v_mfma_f32_16x16x32_bf16 v[12:15], v[170:173], v[202:205], v[12:15]
	s_setprio 2
	s_barrier
	v_mfma_f32_16x16x32_bf16 v[8:11], v[178:181], v[202:205], v[8:11]
	v_mfma_f32_16x16x32_bf16 v[4:7], v[170:173], v[210:213], v[4:7]
	v_mfma_f32_16x16x32_bf16 v[0:3], v[178:181], v[210:213], v[0:3]
	s_setprio 0
	s_add_i32 vcc_hi, vcc_hi, 2
	s_add_u32 s76, s76, 0x100
	s_addc_u32 s77, s77, 0
	s_add_u32 s75, s75, 0x100
	s_addc_u32 vcc_lo, vcc_lo, 0
	s_cmp_gt_u32 vcc_hi, 29
	s_cbranch_scc0 .LBB0_374
	s_and_b64 vcc, exec, s[48:49]
	s_cbranch_vccz .LBB0_377
	s_barrier

; #define PG8_STAGE(bufoff, gbase, voff) do { _Pragma("unroll") for (int _i = 0; _i < 2; ++_i) \
;         __builtin_amdgcn_global_load_lds((const unsigned*)((const char*)(gbase) + (voff)[_i]), (PG8_LAS unsigned*)(lds + (bufoff) + ldsw + _i * 8192), 16, 0, 0); } while (0)
; #define PG8_LDA(dst, b, h) do { _Pragma("unroll") for (int m = 0; m < 4; ++m) _Pragma("unroll") for (int k = 0; k < 2; ++k) dst[m][k] = *(const PG8_LAS bf16x8*)(lds + PG8_SA(b, h) + aoff + m * 2048 + k * 1024); } while (0)
; #define PG8_LDB(dst, b, h) do { _Pragma("unroll") for (int n = 0; n < 2; ++n) _Pragma("unroll") for (int k = 0; k < 2; ++k) dst[n][k] = *(const PG8_LAS bf16x8*)(lds + PG8_SB(b, h) + boff + n * 2048 + k * 1024); } while (0)
; #define PG8_MMA(ai, bj, At, Bt) do { __builtin_amdgcn_s_setprio(1); _Pragma("unroll") for (int m = 0; m < 4; ++m) _Pragma("unroll") for (int n = 0; n < 2; ++n) _Pragma("unroll") for (int k = 0; k < 2; ++k) \
;         acc[ai][bj][m][n] = __builtin_amdgcn_mfma_f32_16x16x32_bf16(Bt[n][k], At[m][k], acc[ai][bj][m][n], 0, 0, 0); __builtin_amdgcn_s_setprio(0); } while (0)
; #define PG8_WAIT_V(n) asm volatile("s_waitcnt vmcnt(" #n ")" ::: "memory")
; #define PG8_WAIT_L(n) asm volatile("s_waitcnt lgkmcnt(" #n ")" ::: "memory")
; #define PG8_BAR __builtin_amdgcn_s_barrier()
; template <class Epi, class Sched, bool ALIGN_EPI = false, bool SP2 = false>
; __device__ __forceinline__ void gemm_phase(PG8_LAS unsigned char* lds, const Gemm g, const Sched& S, const Epi& E) {
;     ...
;             const bool last = (t == nt - 2);
;             const char* a1 = cA + (size_t)(t + 1) * kstep;
;             const char* a2 = last ? nA : cA + (size_t)(t + 2) * kstep; const char* b2 = last ? nB : cB + (size_t)(t + 2) * kstep;
;             const char* a3 = a2 + kstep; const char* b3 = b2 + kstep;
;             if constexpr (SP2) {
;             PG8_LDB(B0, 0, 0); PG8_LDB(B1, 0, 1); PG8_SCHED; PG8_LDA(At, 0, 0); PG8_STAGE(PG8_SA(1, 1), a1 + hstep, voffA);
;             PG8_WAIT_V(8); PG8_WAIT_L(0); PG8_BAR; PG8_MMA(0, 0, At, B0); PG8_MMA(0, 1, At, B1); PG8_BAR; PG8_SCHED;
;             PG8_LDA(At, 0, 1); PG8_STAGE(PG8_SB(0, 0), b2, voffB); PG8_STAGE(PG8_SB(0, 1), b2 + hstep, voffB); PG8_STAGE(PG8_SA(0, 0), a2, voffA);
;             PG8_WAIT_V(8); PG8_WAIT_L(0); PG8_BAR; PG8_MMA(1, 0, At, B0); PG8_MMA(1, 1, At, B1); PG8_BAR; PG8_SCHED;
.LBB0_410:
	ds_read_b128 v[166:169], v145
	ds_read_b128 v[170:173], v145 offset:1024
	ds_read_b128 v[174:177], v145 offset:2048
	ds_read_b128 v[178:181], v145 offset:3072
	ds_read_b128 v[182:185], v149
	ds_read_b128 v[186:189], v149 offset:1024
	ds_read_b128 v[190:193], v149 offset:2048
	ds_read_b128 v[194:197], v149 offset:3072
	s_add_u32 s52, s74, 0xfff80080
	s_addc_u32 s53, s75, -1
	s_cmp_eq_u32 s51, 4
	s_cselect_b32 s79, s55, s53
	s_cselect_b32 s78, s54, s52
	s_cselect_b32 s77, s69, s49
	s_cselect_b32 s76, s68, s37
	s_mov_b32 m0, s80
	v_lshl_add_u64 v[230:231], s[74:75], 0, v[160:161]
	ds_read_b128 v[198:201], v164
	ds_read_b128 v[202:205], v164 offset:1024
	ds_read_b128 v[206:209], v164 offset:2048
	ds_read_b128 v[210:213], v164 offset:3072
	ds_read_b128 v[214:217], v164 offset:4096
	ds_read_b128 v[218:221], v164 offset:5120
	ds_read_b128 v[222:225], v164 offset:6144
	ds_read_b128 v[226:229], v164 offset:7168
	global_load_lds_dwordx4 v[230:231], off
	v_lshl_add_u64 v[230:231], s[74:75], 0, v[162:163]
	s_mov_b32 m0, s81
	s_nop 0
	global_load_lds_dwordx4 v[230:231], off
	s_waitcnt vmcnt(8)
	s_waitcnt lgkmcnt(0)
	s_barrier
	s_setprio 1
	s_waitcnt lgkmcnt(0)
	v_mfma_f32_16x16x32_bf16 v[124:127], v[166:169], v[198:201], v[124:127]
	v_mfma_f32_16x16x32_bf16 v[120:123], v[174:177], v[198:201], v[120:123]
	v_mfma_f32_16x16x32_bf16 v[116:119], v[166:169], v[206:209], v[116:119]
	v_mfma_f32_16x16x32_bf16 v[108:111], v[174:177], v[206:209], v[108:111]
	v_mfma_f32_16x16x32_bf16 v[100:103], v[166:169], v[214:217], v[100:103]
	v_mfma_f32_16x16x32_bf16 v[92:95], v[174:177], v[214:217], v[92:95]
	v_mfma_f32_16x16x32_bf16 v[84:87], v[166:169], v[222:225], v[84:87]
	v_mfma_f32_16x16x32_bf16 v[76:79], v[174:177], v[222:225], v[76:79]
	v_mfma_f32_16x16x32_bf16 v[124:127], v[170:173], v[202:205], v[124:127]
	v_mfma_f32_16x16x32_bf16 v[120:123], v[178:181], v[202:205], v[120:123]
	v_mfma_f32_16x16x32_bf16 v[116:119], v[170:173], v[210:213], v[116:119]
	v_mfma_f32_16x16x32_bf16 v[108:111], v[178:181], v[210:213], v[108:111]
	v_mfma_f32_16x16x32_bf16 v[100:103], v[170:173], v[218:221], v[100:103]
	v_mfma_f32_16x16x32_bf16 v[92:95], v[178:181], v[218:221], v[92:95]
	v_mfma_f32_16x16x32_bf16 v[84:87], v[170:173], v[226:229], v[84:87]
	v_mfma_f32_16x16x32_bf16 v[76:79], v[178:181], v[226:229], v[76:79]
	s_setprio 0
	s_setprio 1
	v_mfma_f32_16x16x32_bf16 v[112:115], v[182:185], v[198:201], v[112:115]
	v_mfma_f32_16x16x32_bf16 v[104:107], v[190:193], v[198:201], v[104:107]
	v_mfma_f32_16x16x32_bf16 v[96:99], v[182:185], v[206:209], v[96:99]
	v_mfma_f32_16x16x32_bf16 v[88:91], v[190:193], v[206:209], v[88:91]
	v_mfma_f32_16x16x32_bf16 v[80:83], v[182:185], v[214:217], v[80:83]
	v_mfma_f32_16x16x32_bf16 v[72:75], v[190:193], v[214:217], v[72:75]
	v_mfma_f32_16x16x32_bf16 v[68:71], v[182:185], v[222:225], v[68:71]
	v_mfma_f32_16x16x32_bf16 v[64:67], v[190:193], v[222:225], v[64:67]
	v_mfma_f32_16x16x32_bf16 v[112:115], v[186:189], v[202:205], v[112:115]
	v_mfma_f32_16x16x32_bf16 v[104:107], v[194:197], v[202:205], v[104:107]
	v_mfma_f32_16x16x32_bf16 v[96:99], v[186:189], v[210:213], v[96:99]
	v_mfma_f32_16x16x32_bf16 v[88:91], v[194:197], v[210:213], v[88:91]
	v_mfma_f32_16x16x32_bf16 v[80:83], v[186:189], v[218:221], v[80:83]
	s_setprio 2
	s_barrier
	v_mfma_f32_16x16x32_bf16 v[72:75], v[194:197], v[218:221], v[72:75]
	v_mfma_f32_16x16x32_bf16 v[68:71], v[186:189], v[226:229], v[68:71]
	v_mfma_f32_16x16x32_bf16 v[64:67], v[194:197], v[226:229], v[64:67]
	s_setprio 0
	s_mov_b32 m0, s84
	v_lshl_add_u64 v[230:231], s[76:77], 0, v[138:139]
	s_add_u32 s52, s76, 0x80000
	ds_read_b128 v[198:201], v164 offset:16384
	ds_read_b128 v[202:205], v164 offset:17408
	ds_read_b128 v[206:209], v164 offset:18432
	ds_read_b128 v[210:213], v164 offset:19456
	ds_read_b128 v[214:217], v164 offset:20480
	ds_read_b128 v[218:221], v164 offset:21504
	ds_read_b128 v[222:225], v164 offset:22528
	ds_read_b128 v[226:229], v164 offset:23552
	global_load_lds_dwordx4 v[230:231], off
	v_lshl_add_u64 v[232:233], s[76:77], 0, v[142:143]
	s_mov_b32 m0, s85
	s_addc_u32 s53, s77, 0
	global_load_lds_dwordx4 v[232:233], off
	v_lshl_add_u64 v[234:235], s[52:53], 0, v[138:139]
	s_mov_b32 m0, s86
	v_lshl_add_u64 v[236:237], s[78:79], 0, v[140:141]
	global_load_lds_dwordx4 v[234:235], off
	v_lshl_add_u64 v[234:235], s[52:53], 0, v[142:143]
	s_mov_b32 m0, s87
	s_nop 0
	global_load_lds_dwordx4 v[234:235], off
	v_lshl_add_u64 v[234:235], s[78:79], 0, v[136:137]
	s_mov_b32 m0, s10
	s_nop 0
	global_load_lds_dwordx4 v[234:235], off
	s_mov_b32 m0, s11
	s_nop 0
	global_load_lds_dwordx4 v[236:237], off
	s_waitcnt vmcnt(8)
	s_waitcnt lgkmcnt(0)
	s_barrier
; #define PG8_STAGE(bufoff, gbase, voff) do { _Pragma("unroll") for (int _i = 0; _i < 2; ++_i) \
;         __builtin_amdgcn_global_load_lds((const unsigned*)((const char*)(gbase) + (voff)[_i]), (PG8_LAS unsigned*)(lds + (bufoff) + ldsw + _i * 8192), 16, 0, 0); } while (0)
; #define PG8_LDA(dst, b, h) do { _Pragma("unroll") for (int m = 0; m < 4; ++m) _Pragma("unroll") for (int k = 0; k < 2; ++k) dst[m][k] = *(const PG8_LAS bf16x8*)(lds + PG8_SA(b, h) + aoff + m * 2048 + k * 1024); } while (0)
; #define PG8_LDB(dst, b, h) do { _Pragma("unroll") for (int n = 0; n < 2; ++n) _Pragma("unroll") for (int k = 0; k < 2; ++k) dst[n][k] = *(const PG8_LAS bf16x8*)(lds + PG8_SB(b, h) + boff + n * 2048 + k * 1024); } while (0)
; #define PG8_MMA(ai, bj, At, Bt) do { __builtin_amdgcn_s_setprio(1); _Pragma("unroll") for (int m = 0; m < 4; ++m) _Pragma("unroll") for (int n = 0; n < 2; ++n) _Pragma("unroll") for (int k = 0; k < 2; ++k) \
;         acc[ai][bj][m][n] = __builtin_amdgcn_mfma_f32_16x16x32_bf16(Bt[n][k], At[m][k], acc[ai][bj][m][n], 0, 0, 0); __builtin_amdgcn_s_setprio(0); } while (0)
; #define PG8_WAIT_V(n) asm volatile("s_waitcnt vmcnt(" #n ")" ::: "memory")
; #define PG8_WAIT_L(n) asm volatile("s_waitcnt lgkmcnt(" #n ")" ::: "memory")
; #define PG8_BAR __builtin_amdgcn_s_barrier()
; #define PG8_SCHED __builtin_amdgcn_sched_barrier(0)
; template <class Epi, class Sched, bool ALIGN_EPI = false, bool SP2 = false>
; __device__ __forceinline__ void gemm_phase(PG8_LAS unsigned char* lds, const Gemm g, const Sched& S, const Epi& E) {
;     ...
;             PG8_WAIT_V(8); PG8_WAIT_L(0); PG8_BAR; PG8_MMA(1, 0, At, B0); PG8_MMA(1, 1, At, B1); PG8_BAR; PG8_SCHED;
;             PG8_LDB(B0, 1, 0); PG8_LDB(B1, 1, 1); PG8_SCHED; PG8_LDA(At, 1, 0); PG8_STAGE(PG8_SA(0, 1), a2 + hstep, voffA);
;             PG8_WAIT_V(8); PG8_WAIT_L(0); PG8_BAR; PG8_MMA(0, 0, At, B0); PG8_MMA(0, 1, At, B1); PG8_BAR; PG8_SCHED;
	s_setprio 1
	s_waitcnt lgkmcnt(0)
	v_mfma_f32_16x16x32_bf16 v[60:63], v[166:169], v[198:201], v[60:63]
	v_mfma_f32_16x16x32_bf16 v[56:59], v[174:177], v[198:201], v[56:59]
	v_mfma_f32_16x16x32_bf16 v[52:55], v[166:169], v[206:209], v[52:55]
	v_mfma_f32_16x16x32_bf16 v[44:47], v[174:177], v[206:209], v[44:47]
	v_mfma_f32_16x16x32_bf16 v[36:39], v[166:169], v[214:217], v[36:39]
	v_mfma_f32_16x16x32_bf16 v[28:31], v[174:177], v[214:217], v[28:31]
	v_mfma_f32_16x16x32_bf16 v[20:23], v[166:169], v[222:225], v[20:23]
	v_mfma_f32_16x16x32_bf16 v[12:15], v[174:177], v[222:225], v[12:15]
	v_mfma_f32_16x16x32_bf16 v[60:63], v[170:173], v[202:205], v[60:63]
	v_mfma_f32_16x16x32_bf16 v[56:59], v[178:181], v[202:205], v[56:59]
	v_mfma_f32_16x16x32_bf16 v[52:55], v[170:173], v[210:213], v[52:55]
	v_mfma_f32_16x16x32_bf16 v[44:47], v[178:181], v[210:213], v[44:47]
	v_mfma_f32_16x16x32_bf16 v[36:39], v[170:173], v[218:221], v[36:39]
	v_mfma_f32_16x16x32_bf16 v[28:31], v[178:181], v[218:221], v[28:31]
	v_mfma_f32_16x16x32_bf16 v[20:23], v[170:173], v[226:229], v[20:23]
	v_mfma_f32_16x16x32_bf16 v[12:15], v[178:181], v[226:229], v[12:15]
	s_setprio 0
	s_setprio 1
	v_mfma_f32_16x16x32_bf16 v[48:51], v[182:185], v[198:201], v[48:51]
	v_mfma_f32_16x16x32_bf16 v[40:43], v[190:193], v[198:201], v[40:43]
	v_mfma_f32_16x16x32_bf16 v[32:35], v[182:185], v[206:209], v[32:35]
	v_mfma_f32_16x16x32_bf16 v[24:27], v[190:193], v[206:209], v[24:27]
	v_mfma_f32_16x16x32_bf16 v[16:19], v[182:185], v[214:217], v[16:19]
	v_mfma_f32_16x16x32_bf16 v[8:11], v[190:193], v[214:217], v[8:11]
	v_mfma_f32_16x16x32_bf16 v[4:7], v[182:185], v[222:225], v[4:7]
	v_mfma_f32_16x16x32_bf16 v[0:3], v[190:193], v[222:225], v[0:3]
	v_mfma_f32_16x16x32_bf16 v[48:51], v[186:189], v[202:205], v[48:51]
	v_mfma_f32_16x16x32_bf16 v[40:43], v[194:197], v[202:205], v[40:43]
	v_mfma_f32_16x16x32_bf16 v[32:35], v[186:189], v[210:213], v[32:35]
	v_mfma_f32_16x16x32_bf16 v[24:27], v[194:197], v[210:213], v[24:27]
	v_mfma_f32_16x16x32_bf16 v[16:19], v[186:189], v[218:221], v[16:19]
	s_setprio 2
	s_barrier
	v_mfma_f32_16x16x32_bf16 v[8:11], v[194:197], v[218:221], v[8:11]
	v_mfma_f32_16x16x32_bf16 v[4:7], v[186:189], v[226:229], v[4:7]
	v_mfma_f32_16x16x32_bf16 v[0:3], v[194:197], v[226:229], v[0:3]
	s_setprio 0
	ds_read_b128 v[166:169], v148
	ds_read_b128 v[170:173], v148 offset:1024
	ds_read_b128 v[174:177], v148 offset:2048
	ds_read_b128 v[178:181], v148 offset:3072
	ds_read_b128 v[182:185], v165
	ds_read_b128 v[186:189], v165 offset:1024
	ds_read_b128 v[190:193], v165 offset:2048
	ds_read_b128 v[194:197], v165 offset:3072
	s_add_u32 s52, s78, 0x80000
	s_addc_u32 s53, s79, 0
	s_mov_b32 m0, s28
	v_lshl_add_u64 v[238:239], s[52:53], 0, v[136:137]
	ds_read_b128 v[198:201], v164 offset:32768
	ds_read_b128 v[202:205], v164 offset:33792
	ds_read_b128 v[206:209], v164 offset:34816
	ds_read_b128 v[210:213], v164 offset:35840
	ds_read_b128 v[214:217], v164 offset:36864
	ds_read_b128 v[218:221], v164 offset:37888
	ds_read_b128 v[222:225], v164 offset:38912
	ds_read_b128 v[226:229], v164 offset:39936
	global_load_lds_dwordx4 v[238:239], off
	v_lshl_add_u64 v[238:239], s[52:53], 0, v[140:141]
	s_mov_b32 m0, s29
	s_nop 0
	global_load_lds_dwordx4 v[238:239], off
	s_waitcnt vmcnt(8)
	s_waitcnt lgkmcnt(0)
	s_barrier
	s_setprio 1
	s_waitcnt lgkmcnt(0)
	v_mfma_f32_16x16x32_bf16 v[124:127], v[166:169], v[198:201], v[124:127]
	v_mfma_f32_16x16x32_bf16 v[120:123], v[174:177], v[198:201], v[120:123]
	v_mfma_f32_16x16x32_bf16 v[116:119], v[166:169], v[206:209], v[116:119]
	v_mfma_f32_16x16x32_bf16 v[108:111], v[174:177], v[206:209], v[108:111]
	v_mfma_f32_16x16x32_bf16 v[100:103], v[166:169], v[214:217], v[100:103]
	v_mfma_f32_16x16x32_bf16 v[92:95], v[174:177], v[214:217], v[92:95]
	v_mfma_f32_16x16x32_bf16 v[84:87], v[166:169], v[222:225], v[84:87]
	v_mfma_f32_16x16x32_bf16 v[76:79], v[174:177], v[222:225], v[76:79]
	v_mfma_f32_16x16x32_bf16 v[124:127], v[170:173], v[202:205], v[124:127]
	v_mfma_f32_16x16x32_bf16 v[120:123], v[178:181], v[202:205], v[120:123]
	v_mfma_f32_16x16x32_bf16 v[116:119], v[170:173], v[210:213], v[116:119]
	v_mfma_f32_16x16x32_bf16 v[108:111], v[178:181], v[210:213], v[108:111]
	v_mfma_f32_16x16x32_bf16 v[100:103], v[170:173], v[218:221], v[100:103]
	v_mfma_f32_16x16x32_bf16 v[92:95], v[178:181], v[218:221], v[92:95]
	v_mfma_f32_16x16x32_bf16 v[84:87], v[170:173], v[226:229], v[84:87]
	v_mfma_f32_16x16x32_bf16 v[76:79], v[178:181], v[226:229], v[76:79]
	s_setprio 0
	s_setprio 1
	v_mfma_f32_16x16x32_bf16 v[112:115], v[182:185], v[198:201], v[112:115]
	v_mfma_f32_16x16x32_bf16 v[104:107], v[190:193], v[198:201], v[104:107]
	v_mfma_f32_16x16x32_bf16 v[96:99], v[182:185], v[206:209], v[96:99]
	v_mfma_f32_16x16x32_bf16 v[88:91], v[190:193], v[206:209], v[88:91]
	v_mfma_f32_16x16x32_bf16 v[80:83], v[182:185], v[214:217], v[80:83]
	v_mfma_f32_16x16x32_bf16 v[72:75], v[190:193], v[214:217], v[72:75]
	v_mfma_f32_16x16x32_bf16 v[68:71], v[182:185], v[222:225], v[68:71]
	v_mfma_f32_16x16x32_bf16 v[64:67], v[190:193], v[222:225], v[64:67]
	v_mfma_f32_16x16x32_bf16 v[112:115], v[186:189], v[202:205], v[112:115]
	v_mfma_f32_16x16x32_bf16 v[104:107], v[194:197], v[202:205], v[104:107]
	v_mfma_f32_16x16x32_bf16 v[96:99], v[186:189], v[210:213], v[96:99]
	v_mfma_f32_16x16x32_bf16 v[88:91], v[194:197], v[210:213], v[88:91]
	v_mfma_f32_16x16x32_bf16 v[80:83], v[186:189], v[218:221], v[80:83]
	s_setprio 2
	s_barrier
; #define PG8_STAGE(bufoff, gbase, voff) do { _Pragma("unroll") for (int _i = 0; _i < 2; ++_i) \
;         __builtin_amdgcn_global_load_lds((const unsigned*)((const char*)(gbase) + (voff)[_i]), (PG8_LAS unsigned*)(lds + (bufoff) + ldsw + _i * 8192), 16, 0, 0); } while (0)
; #define PG8_LDA(dst, b, h) do { _Pragma("unroll") for (int m = 0; m < 4; ++m) _Pragma("unroll") for (int k = 0; k < 2; ++k) dst[m][k] = *(const PG8_LAS bf16x8*)(lds + PG8_SA(b, h) + aoff + m * 2048 + k * 1024); } while (0)
; #define PG8_MMA(ai, bj, At, Bt) do { __builtin_amdgcn_s_setprio(1); _Pragma("unroll") for (int m = 0; m < 4; ++m) _Pragma("unroll") for (int n = 0; n < 2; ++n) _Pragma("unroll") for (int k = 0; k < 2; ++k) \
;         acc[ai][bj][m][n] = __builtin_amdgcn_mfma_f32_16x16x32_bf16(Bt[n][k], At[m][k], acc[ai][bj][m][n], 0, 0, 0); __builtin_amdgcn_s_setprio(0); } while (0)
; #define PG8_WAIT_V(n) asm volatile("s_waitcnt vmcnt(" #n ")" ::: "memory")
; #define PG8_WAIT_L(n) asm volatile("s_waitcnt lgkmcnt(" #n ")" ::: "memory")
; #define PG8_BAR __builtin_amdgcn_s_barrier()
; #define PG8_SCHED __builtin_amdgcn_sched_barrier(0)
; template <class Epi, class Sched, bool ALIGN_EPI = false, bool SP2 = false>
; __device__ __forceinline__ void gemm_phase(PG8_LAS unsigned char* lds, const Gemm g, const Sched& S, const Epi& E) {
;     ...
;             PG8_WAIT_V(8); PG8_WAIT_L(0); PG8_BAR; PG8_MMA(0, 0, At, B0); PG8_MMA(0, 1, At, B1); PG8_BAR; PG8_SCHED;
;             PG8_LDA(At, 1, 1); PG8_STAGE(PG8_SB(1, 0), b3, voffB); PG8_STAGE(PG8_SB(1, 1), b3 + hstep, voffB); PG8_STAGE(PG8_SA(1, 0), a3, voffA);
;             PG8_WAIT_V(8); PG8_WAIT_L(0); PG8_BAR; PG8_MMA(1, 0, At, B0); PG8_MMA(1, 1, At, B1); PG8_BAR; PG8_SCHED;
	v_mfma_f32_16x16x32_bf16 v[72:75], v[194:197], v[218:221], v[72:75]
	v_mfma_f32_16x16x32_bf16 v[68:71], v[186:189], v[226:229], v[68:71]
	v_mfma_f32_16x16x32_bf16 v[64:67], v[194:197], v[226:229], v[64:67]
	s_setprio 0
	s_mov_b32 m0, s89
	v_lshl_add_u64 v[230:231], v[230:231], 0, s[12:13]
	ds_read_b128 v[198:201], v164 offset:49152
	ds_read_b128 v[202:205], v164 offset:50176
	ds_read_b128 v[206:209], v164 offset:51200
	ds_read_b128 v[210:213], v164 offset:52224
	ds_read_b128 v[214:217], v164 offset:53248
	ds_read_b128 v[218:221], v164 offset:54272
	ds_read_b128 v[222:225], v164 offset:55296
	ds_read_b128 v[226:229], v164 offset:56320
	global_load_lds_dwordx4 v[230:231], off
	s_add_i32 m0, s89, 0x2000
	s_add_u32 s52, s76, 0x80080
	v_lshl_add_u64 v[230:231], v[232:233], 0, s[12:13]
	s_addc_u32 s53, s77, 0
	s_add_i32 s56, s88, s3
	global_load_lds_dwordx4 v[230:231], off
	v_lshl_add_u64 v[230:231], s[52:53], 0, v[138:139]
	s_mov_b32 m0, s56
	s_nop 0
	global_load_lds_dwordx4 v[230:231], off
	v_lshl_add_u64 v[230:231], s[52:53], 0, v[142:143]
	s_add_i32 m0, s56, 0x2000
	s_nop 0
	global_load_lds_dwordx4 v[230:231], off
	v_lshl_add_u64 v[230:231], v[234:235], 0, s[12:13]
	s_mov_b32 m0, s38
	s_nop 0
	global_load_lds_dwordx4 v[230:231], off
	v_lshl_add_u64 v[230:231], v[236:237], 0, s[12:13]
	s_mov_b32 m0, s39
	s_nop 0
	global_load_lds_dwordx4 v[230:231], off
	s_waitcnt vmcnt(8)
	s_waitcnt lgkmcnt(0)
	s_barrier
	s_setprio 1
	s_waitcnt lgkmcnt(0)
	v_mfma_f32_16x16x32_bf16 v[60:63], v[166:169], v[198:201], v[60:63]
	v_mfma_f32_16x16x32_bf16 v[56:59], v[174:177], v[198:201], v[56:59]
	v_mfma_f32_16x16x32_bf16 v[52:55], v[166:169], v[206:209], v[52:55]
	v_mfma_f32_16x16x32_bf16 v[44:47], v[174:177], v[206:209], v[44:47]
	v_mfma_f32_16x16x32_bf16 v[36:39], v[166:169], v[214:217], v[36:39]
	v_mfma_f32_16x16x32_bf16 v[28:31], v[174:177], v[214:217], v[28:31]
	v_mfma_f32_16x16x32_bf16 v[20:23], v[166:169], v[222:225], v[20:23]
	v_mfma_f32_16x16x32_bf16 v[12:15], v[174:177], v[222:225], v[12:15]
	v_mfma_f32_16x16x32_bf16 v[60:63], v[170:173], v[202:205], v[60:63]
	v_mfma_f32_16x16x32_bf16 v[56:59], v[178:181], v[202:205], v[56:59]
	v_mfma_f32_16x16x32_bf16 v[52:55], v[170:173], v[210:213], v[52:55]
	v_mfma_f32_16x16x32_bf16 v[44:47], v[178:181], v[210:213], v[44:47]
	v_mfma_f32_16x16x32_bf16 v[36:39], v[170:173], v[218:221], v[36:39]
	v_mfma_f32_16x16x32_bf16 v[28:31], v[178:181], v[218:221], v[28:31]
	v_mfma_f32_16x16x32_bf16 v[20:23], v[170:173], v[226:229], v[20:23]
	v_mfma_f32_16x16x32_bf16 v[12:15], v[178:181], v[226:229], v[12:15]
	s_setprio 0
	s_setprio 1
	v_mfma_f32_16x16x32_bf16 v[48:51], v[182:185], v[198:201], v[48:51]
	v_mfma_f32_16x16x32_bf16 v[40:43], v[190:193], v[198:201], v[40:43]
	v_mfma_f32_16x16x32_bf16 v[32:35], v[182:185], v[206:209], v[32:35]
	v_mfma_f32_16x16x32_bf16 v[24:27], v[190:193], v[206:209], v[24:27]
	v_mfma_f32_16x16x32_bf16 v[16:19], v[182:185], v[214:217], v[16:19]
	v_mfma_f32_16x16x32_bf16 v[8:11], v[190:193], v[214:217], v[8:11]
	v_mfma_f32_16x16x32_bf16 v[4:7], v[182:185], v[222:225], v[4:7]
	v_mfma_f32_16x16x32_bf16 v[0:3], v[190:193], v[222:225], v[0:3]
	v_mfma_f32_16x16x32_bf16 v[48:51], v[186:189], v[202:205], v[48:51]
	v_mfma_f32_16x16x32_bf16 v[40:43], v[194:197], v[202:205], v[40:43]
	v_mfma_f32_16x16x32_bf16 v[32:35], v[186:189], v[210:213], v[32:35]
	v_mfma_f32_16x16x32_bf16 v[24:27], v[194:197], v[210:213], v[24:27]
	v_mfma_f32_16x16x32_bf16 v[16:19], v[186:189], v[218:221], v[16:19]
	s_setprio 2
	s_barrier
	v_mfma_f32_16x16x32_bf16 v[8:11], v[194:197], v[218:221], v[8:11]
	v_mfma_f32_16x16x32_bf16 v[4:7], v[186:189], v[226:229], v[4:7]
	v_mfma_f32_16x16x32_bf16 v[0:3], v[194:197], v[226:229], v[0:3]
	s_setprio 0
	s_add_i32 s51, s51, 2
	s_add_u32 s74, s74, 0x100
	s_addc_u32 s75, s75, 0
	s_add_u32 s37, s37, 0x100
	s_addc_u32 s49, s49, 0
	s_cmp_gt_u32 s51, 5
	s_cbranch_scc0 .LBB0_410
	s_and_b64 vcc, exec, s[14:15]
	s_cbranch_vccz .LBB0_413
	s_barrier

; #define PG8_STAGE(bufoff, gbase, voff) do { _Pragma("unroll") for (int _i = 0; _i < 2; ++_i) \
;         __builtin_amdgcn_global_load_lds((const unsigned*)((const char*)(gbase) + (voff)[_i]), (PG8_LAS unsigned*)(lds + (bufoff) + ldsw + _i * 8192), 16, 0, 0); } while (0)
; #define PG8_LDA(dst, b, h) do { _Pragma("unroll") for (int m = 0; m < 4; ++m) _Pragma("unroll") for (int k = 0; k < 2; ++k) dst[m][k] = *(const PG8_LAS bf16x8*)(lds + PG8_SA(b, h) + aoff + m * 2048 + k * 1024); } while (0)
; #define PG8_LDB(dst, b, h) do { _Pragma("unroll") for (int n = 0; n < 2; ++n) _Pragma("unroll") for (int k = 0; k < 2; ++k) dst[n][k] = *(const PG8_LAS bf16x8*)(lds + PG8_SB(b, h) + boff + n * 2048 + k * 1024); } while (0)
; #define PG8_MMA(ai, bj, At, Bt) do { __builtin_amdgcn_s_setprio(1); _Pragma("unroll") for (int m = 0; m < 4; ++m) _Pragma("unroll") for (int n = 0; n < 2; ++n) _Pragma("unroll") for (int k = 0; k < 2; ++k) \
;         acc[ai][bj][m][n] = __builtin_amdgcn_mfma_f32_16x16x32_bf16(Bt[n][k], At[m][k], acc[ai][bj][m][n], 0, 0, 0); __builtin_amdgcn_s_setprio(0); } while (0)
; #define PG8_WAIT_V(n) asm volatile("s_waitcnt vmcnt(" #n ")" ::: "memory")
; #define PG8_WAIT_L(n) asm volatile("s_waitcnt lgkmcnt(" #n ")" ::: "memory")
; #define PG8_BAR __builtin_amdgcn_s_barrier()
; template <class Epi, class Sched, bool ALIGN_EPI = false, bool SP2 = false>
; __device__ __forceinline__ void gemm_phase(PG8_LAS unsigned char* lds, const Gemm g, const Sched& S, const Epi& E) {
;     ...
;             const bool last = (t == nt - 2);
;             const char* a1 = cA + (size_t)(t + 1) * kstep;
;             const char* a2 = last ? nA : cA + (size_t)(t + 2) * kstep; const char* b2 = last ? nB : cB + (size_t)(t + 2) * kstep;
;             const char* a3 = a2 + kstep; const char* b3 = b2 + kstep;
;             if constexpr (SP2) {
;             PG8_LDB(B0, 0, 0); PG8_LDB(B1, 0, 1); PG8_SCHED; PG8_LDA(At, 0, 0); PG8_STAGE(PG8_SA(1, 1), a1 + hstep, voffA);
;             PG8_WAIT_V(8); PG8_WAIT_L(0); PG8_BAR; PG8_MMA(0, 0, At, B0); PG8_MMA(0, 1, At, B1); PG8_BAR; PG8_SCHED;
;             PG8_LDA(At, 0, 1); PG8_STAGE(PG8_SB(0, 0), b2, voffB); PG8_STAGE(PG8_SB(0, 1), b2 + hstep, voffB); PG8_STAGE(PG8_SA(0, 0), a2, voffA);
;             PG8_WAIT_V(8); PG8_WAIT_L(0); PG8_BAR; PG8_MMA(1, 0, At, B0); PG8_MMA(1, 1, At, B1); PG8_BAR; PG8_SCHED;
.LBB0_545:
	ds_read_b128 v[112:115], v174
	ds_read_b128 v[116:119], v174 offset:1024
	ds_read_b128 v[120:123], v174 offset:2048
	ds_read_b128 v[124:127], v174 offset:3072
	ds_read_b128 v[164:167], v175
	ds_read_b128 v[168:171], v175 offset:1024
	ds_read_b128 v[178:181], v175 offset:2048
	ds_read_b128 v[182:185], v175 offset:3072
	s_add_u32 s52, s68, 0xfff80080
	s_addc_u32 s53, s69, -1
	s_cmp_eq_u32 s88, 28
	s_cselect_b32 s73, s41, s53
	s_cselect_b32 s72, s84, s52
	s_cselect_b32 s71, s37, s87
	s_cselect_b32 s70, s85, s86
	v_lshl_add_u64 v[218:219], s[68:69], 0, v[156:157]
	s_add_i32 m0, s39, 0xc000
	ds_read_b128 v[186:189], v176
	ds_read_b128 v[190:193], v176 offset:1024
	ds_read_b128 v[194:197], v176 offset:2048
	ds_read_b128 v[198:201], v176 offset:3072
	ds_read_b128 v[202:205], v176 offset:4096
	ds_read_b128 v[206:209], v176 offset:5120
	ds_read_b128 v[210:213], v176 offset:6144
	ds_read_b128 v[214:217], v176 offset:7168
	global_load_lds_dwordx4 v[218:219], off
	v_lshl_add_u64 v[218:219], s[68:69], 0, v[158:159]
	s_add_i32 m0, s39, 0xe000
	s_nop 0
	global_load_lds_dwordx4 v[218:219], off
	s_waitcnt vmcnt(8)
	s_waitcnt lgkmcnt(0)
	s_barrier
	s_setprio 1
	s_waitcnt lgkmcnt(0)
	v_mfma_f32_16x16x32_bf16 v[140:143], v[112:115], v[186:189], v[140:143]
	v_mfma_f32_16x16x32_bf16 v[136:139], v[120:123], v[186:189], v[136:139]
	v_mfma_f32_16x16x32_bf16 v[108:111], v[112:115], v[194:197], v[108:111]
	v_mfma_f32_16x16x32_bf16 v[104:107], v[120:123], v[194:197], v[104:107]
	v_mfma_f32_16x16x32_bf16 v[92:95], v[112:115], v[202:205], v[92:95]
	v_mfma_f32_16x16x32_bf16 v[88:91], v[120:123], v[202:205], v[88:91]
	v_mfma_f32_16x16x32_bf16 v[76:79], v[112:115], v[210:213], v[76:79]
	v_mfma_f32_16x16x32_bf16 v[72:75], v[120:123], v[210:213], v[72:75]
	v_mfma_f32_16x16x32_bf16 v[140:143], v[116:119], v[190:193], v[140:143]
	v_mfma_f32_16x16x32_bf16 v[136:139], v[124:127], v[190:193], v[136:139]
	v_mfma_f32_16x16x32_bf16 v[108:111], v[116:119], v[198:201], v[108:111]
	v_mfma_f32_16x16x32_bf16 v[104:107], v[124:127], v[198:201], v[104:107]
	v_mfma_f32_16x16x32_bf16 v[92:95], v[116:119], v[206:209], v[92:95]
	v_mfma_f32_16x16x32_bf16 v[88:91], v[124:127], v[206:209], v[88:91]
	v_mfma_f32_16x16x32_bf16 v[76:79], v[116:119], v[214:217], v[76:79]
	v_mfma_f32_16x16x32_bf16 v[72:75], v[124:127], v[214:217], v[72:75]
	s_setprio 0
	s_setprio 1
	v_mfma_f32_16x16x32_bf16 v[132:135], v[164:167], v[186:189], v[132:135]
	v_mfma_f32_16x16x32_bf16 v[128:131], v[178:181], v[186:189], v[128:131]
	v_mfma_f32_16x16x32_bf16 v[100:103], v[164:167], v[194:197], v[100:103]
	v_mfma_f32_16x16x32_bf16 v[96:99], v[178:181], v[194:197], v[96:99]
	v_mfma_f32_16x16x32_bf16 v[84:87], v[164:167], v[202:205], v[84:87]
	v_mfma_f32_16x16x32_bf16 v[80:83], v[178:181], v[202:205], v[80:83]
	v_mfma_f32_16x16x32_bf16 v[68:71], v[164:167], v[210:213], v[68:71]
	v_mfma_f32_16x16x32_bf16 v[64:67], v[178:181], v[210:213], v[64:67]
	v_mfma_f32_16x16x32_bf16 v[132:135], v[168:171], v[190:193], v[132:135]
	v_mfma_f32_16x16x32_bf16 v[128:131], v[182:185], v[190:193], v[128:131]
	v_mfma_f32_16x16x32_bf16 v[100:103], v[168:171], v[198:201], v[100:103]
	v_mfma_f32_16x16x32_bf16 v[96:99], v[182:185], v[198:201], v[96:99]
	v_mfma_f32_16x16x32_bf16 v[84:87], v[168:171], v[206:209], v[84:87]
	s_setprio 2
	s_barrier
	v_mfma_f32_16x16x32_bf16 v[80:83], v[182:185], v[206:209], v[80:83]
	v_mfma_f32_16x16x32_bf16 v[68:71], v[168:171], v[214:217], v[68:71]
	v_mfma_f32_16x16x32_bf16 v[64:67], v[182:185], v[214:217], v[64:67]
	s_setprio 0
	s_add_i32 s52, s81, s29
	v_lshl_add_u64 v[218:219], s[70:71], 0, v[152:153]
	s_mov_b32 m0, s52
	ds_read_b128 v[186:189], v176 offset:16384
	ds_read_b128 v[190:193], v176 offset:17408
	ds_read_b128 v[194:197], v176 offset:18432
	ds_read_b128 v[198:201], v176 offset:19456
	ds_read_b128 v[202:205], v176 offset:20480
	ds_read_b128 v[206:209], v176 offset:21504
	ds_read_b128 v[210:213], v176 offset:22528
	ds_read_b128 v[214:217], v176 offset:23552
	global_load_lds_dwordx4 v[218:219], off
	s_add_i32 m0, s52, 0x2000
	s_add_u32 s52, s70, 0x80000
	v_lshl_add_u64 v[220:221], s[70:71], 0, v[148:149]
	s_addc_u32 s53, s71, 0
	s_add_i32 s56, s82, s29
	global_load_lds_dwordx4 v[220:221], off
	v_lshl_add_u64 v[222:223], s[52:53], 0, v[152:153]
	s_mov_b32 m0, s56
	v_lshl_add_u64 v[224:225], s[72:73], 0, v[150:151]
	global_load_lds_dwordx4 v[222:223], off
	v_lshl_add_u64 v[222:223], s[52:53], 0, v[148:149]
	s_add_i32 m0, s56, 0x2000
	s_nop 0
	global_load_lds_dwordx4 v[222:223], off
	v_lshl_add_u64 v[222:223], s[72:73], 0, v[154:155]
	s_mov_b32 m0, s39
	s_nop 0
	global_load_lds_dwordx4 v[222:223], off
	s_mov_b32 m0, s55
	s_nop 0
	global_load_lds_dwordx4 v[224:225], off
	s_waitcnt vmcnt(8)
	s_waitcnt lgkmcnt(0)
	s_barrier
; #define PG8_STAGE(bufoff, gbase, voff) do { _Pragma("unroll") for (int _i = 0; _i < 2; ++_i) \
;         __builtin_amdgcn_global_load_lds((const unsigned*)((const char*)(gbase) + (voff)[_i]), (PG8_LAS unsigned*)(lds + (bufoff) + ldsw + _i * 8192), 16, 0, 0); } while (0)
; #define PG8_LDA(dst, b, h) do { _Pragma("unroll") for (int m = 0; m < 4; ++m) _Pragma("unroll") for (int k = 0; k < 2; ++k) dst[m][k] = *(const PG8_LAS bf16x8*)(lds + PG8_SA(b, h) + aoff + m * 2048 + k * 1024); } while (0)
; #define PG8_LDB(dst, b, h) do { _Pragma("unroll") for (int n = 0; n < 2; ++n) _Pragma("unroll") for (int k = 0; k < 2; ++k) dst[n][k] = *(const PG8_LAS bf16x8*)(lds + PG8_SB(b, h) + boff + n * 2048 + k * 1024); } while (0)
; #define PG8_MMA(ai, bj, At, Bt) do { __builtin_amdgcn_s_setprio(1); _Pragma("unroll") for (int m = 0; m < 4; ++m) _Pragma("unroll") for (int n = 0; n < 2; ++n) _Pragma("unroll") for (int k = 0; k < 2; ++k) \
;         acc[ai][bj][m][n] = __builtin_amdgcn_mfma_f32_16x16x32_bf16(Bt[n][k], At[m][k], acc[ai][bj][m][n], 0, 0, 0); __builtin_amdgcn_s_setprio(0); } while (0)
; #define PG8_WAIT_V(n) asm volatile("s_waitcnt vmcnt(" #n ")" ::: "memory")
; #define PG8_WAIT_L(n) asm volatile("s_waitcnt lgkmcnt(" #n ")" ::: "memory")
; #define PG8_BAR __builtin_amdgcn_s_barrier()
; #define PG8_SCHED __builtin_amdgcn_sched_barrier(0)
; template <class Epi, class Sched, bool ALIGN_EPI = false, bool SP2 = false>
; __device__ __forceinline__ void gemm_phase(PG8_LAS unsigned char* lds, const Gemm g, const Sched& S, const Epi& E) {
;     ...
;             PG8_WAIT_V(8); PG8_WAIT_L(0); PG8_BAR; PG8_MMA(1, 0, At, B0); PG8_MMA(1, 1, At, B1); PG8_BAR; PG8_SCHED;
;             PG8_LDB(B0, 1, 0); PG8_LDB(B1, 1, 1); PG8_SCHED; PG8_LDA(At, 1, 0); PG8_STAGE(PG8_SA(0, 1), a2 + hstep, voffA);
;             PG8_WAIT_V(8); PG8_WAIT_L(0); PG8_BAR; PG8_MMA(0, 0, At, B0); PG8_MMA(0, 1, At, B1); PG8_BAR; PG8_SCHED;
	s_setprio 1
	s_waitcnt lgkmcnt(0)
	v_mfma_f32_16x16x32_bf16 v[60:63], v[112:115], v[186:189], v[60:63]
	v_mfma_f32_16x16x32_bf16 v[56:59], v[120:123], v[186:189], v[56:59]
	v_mfma_f32_16x16x32_bf16 v[44:47], v[112:115], v[194:197], v[44:47]
	v_mfma_f32_16x16x32_bf16 v[40:43], v[120:123], v[194:197], v[40:43]
	v_mfma_f32_16x16x32_bf16 v[28:31], v[112:115], v[202:205], v[28:31]
	v_mfma_f32_16x16x32_bf16 v[24:27], v[120:123], v[202:205], v[24:27]
	v_mfma_f32_16x16x32_bf16 v[12:15], v[112:115], v[210:213], v[12:15]
	v_mfma_f32_16x16x32_bf16 v[8:11], v[120:123], v[210:213], v[8:11]
	v_mfma_f32_16x16x32_bf16 v[60:63], v[116:119], v[190:193], v[60:63]
	v_mfma_f32_16x16x32_bf16 v[56:59], v[124:127], v[190:193], v[56:59]
	v_mfma_f32_16x16x32_bf16 v[44:47], v[116:119], v[198:201], v[44:47]
	v_mfma_f32_16x16x32_bf16 v[40:43], v[124:127], v[198:201], v[40:43]
	v_mfma_f32_16x16x32_bf16 v[28:31], v[116:119], v[206:209], v[28:31]
	v_mfma_f32_16x16x32_bf16 v[24:27], v[124:127], v[206:209], v[24:27]
	v_mfma_f32_16x16x32_bf16 v[12:15], v[116:119], v[214:217], v[12:15]
	v_mfma_f32_16x16x32_bf16 v[8:11], v[124:127], v[214:217], v[8:11]
	s_setprio 0
	s_setprio 1
	v_mfma_f32_16x16x32_bf16 v[52:55], v[164:167], v[186:189], v[52:55]
	v_mfma_f32_16x16x32_bf16 v[48:51], v[178:181], v[186:189], v[48:51]
	v_mfma_f32_16x16x32_bf16 v[36:39], v[164:167], v[194:197], v[36:39]
	v_mfma_f32_16x16x32_bf16 v[32:35], v[178:181], v[194:197], v[32:35]
	v_mfma_f32_16x16x32_bf16 v[20:23], v[164:167], v[202:205], v[20:23]
	v_mfma_f32_16x16x32_bf16 v[16:19], v[178:181], v[202:205], v[16:19]
	v_mfma_f32_16x16x32_bf16 v[4:7], v[164:167], v[210:213], v[4:7]
	v_mfma_f32_16x16x32_bf16 v[0:3], v[178:181], v[210:213], v[0:3]
	v_mfma_f32_16x16x32_bf16 v[52:55], v[168:171], v[190:193], v[52:55]
	v_mfma_f32_16x16x32_bf16 v[48:51], v[182:185], v[190:193], v[48:51]
	v_mfma_f32_16x16x32_bf16 v[36:39], v[168:171], v[198:201], v[36:39]
	v_mfma_f32_16x16x32_bf16 v[32:35], v[182:185], v[198:201], v[32:35]
	v_mfma_f32_16x16x32_bf16 v[20:23], v[168:171], v[206:209], v[20:23]
	s_setprio 2
	s_barrier
	v_mfma_f32_16x16x32_bf16 v[16:19], v[182:185], v[206:209], v[16:19]
	v_mfma_f32_16x16x32_bf16 v[4:7], v[168:171], v[214:217], v[4:7]
	v_mfma_f32_16x16x32_bf16 v[0:3], v[182:185], v[214:217], v[0:3]
	s_setprio 0
	s_add_i32 s56, 0, 0x18000
	s_add_i32 s57, 0, 0x1c000
	v_add_u32_e32 v124, s56, v172
	v_add_u32_e32 v177, s57, v172
	ds_read_b128 v[112:115], v124
	ds_read_b128 v[116:119], v124 offset:1024
	ds_read_b128 v[120:123], v124 offset:2048
	ds_read_b128 v[124:127], v124 offset:3072
	ds_read_b128 v[164:167], v177
	ds_read_b128 v[168:171], v177 offset:1024
	ds_read_b128 v[178:181], v177 offset:2048
	ds_read_b128 v[182:185], v177 offset:3072
	s_add_u32 s52, s72, 0x80000
	s_addc_u32 s53, s73, 0
	s_mov_b32 m0, s74
	v_lshl_add_u64 v[226:227], s[52:53], 0, v[154:155]
	ds_read_b128 v[186:189], v176 offset:32768
	ds_read_b128 v[190:193], v176 offset:33792
	ds_read_b128 v[194:197], v176 offset:34816
	ds_read_b128 v[198:201], v176 offset:35840
	ds_read_b128 v[202:205], v176 offset:36864
	ds_read_b128 v[206:209], v176 offset:37888
	ds_read_b128 v[210:213], v176 offset:38912
	ds_read_b128 v[214:217], v176 offset:39936
	global_load_lds_dwordx4 v[226:227], off
	v_lshl_add_u64 v[226:227], s[52:53], 0, v[150:151]
	s_mov_b32 m0, s75
	s_nop 0
	global_load_lds_dwordx4 v[226:227], off
	s_waitcnt vmcnt(8)
	s_waitcnt lgkmcnt(0)
	s_barrier
	s_setprio 1
	s_waitcnt lgkmcnt(0)
	v_mfma_f32_16x16x32_bf16 v[140:143], v[112:115], v[186:189], v[140:143]
	v_mfma_f32_16x16x32_bf16 v[136:139], v[120:123], v[186:189], v[136:139]
	v_mfma_f32_16x16x32_bf16 v[108:111], v[112:115], v[194:197], v[108:111]
	v_mfma_f32_16x16x32_bf16 v[104:107], v[120:123], v[194:197], v[104:107]
	v_mfma_f32_16x16x32_bf16 v[92:95], v[112:115], v[202:205], v[92:95]
	v_mfma_f32_16x16x32_bf16 v[88:91], v[120:123], v[202:205], v[88:91]
	v_mfma_f32_16x16x32_bf16 v[76:79], v[112:115], v[210:213], v[76:79]
	v_mfma_f32_16x16x32_bf16 v[72:75], v[120:123], v[210:213], v[72:75]
	v_mfma_f32_16x16x32_bf16 v[140:143], v[116:119], v[190:193], v[140:143]
	v_mfma_f32_16x16x32_bf16 v[136:139], v[124:127], v[190:193], v[136:139]
	v_mfma_f32_16x16x32_bf16 v[108:111], v[116:119], v[198:201], v[108:111]
	v_mfma_f32_16x16x32_bf16 v[104:107], v[124:127], v[198:201], v[104:107]
	v_mfma_f32_16x16x32_bf16 v[92:95], v[116:119], v[206:209], v[92:95]
	v_mfma_f32_16x16x32_bf16 v[88:91], v[124:127], v[206:209], v[88:91]
	v_mfma_f32_16x16x32_bf16 v[76:79], v[116:119], v[214:217], v[76:79]
	v_mfma_f32_16x16x32_bf16 v[72:75], v[124:127], v[214:217], v[72:75]
	s_setprio 0
	s_setprio 1
	v_mfma_f32_16x16x32_bf16 v[132:135], v[164:167], v[186:189], v[132:135]
	v_mfma_f32_16x16x32_bf16 v[128:131], v[178:181], v[186:189], v[128:131]
	v_mfma_f32_16x16x32_bf16 v[100:103], v[164:167], v[194:197], v[100:103]
	v_mfma_f32_16x16x32_bf16 v[96:99], v[178:181], v[194:197], v[96:99]
	v_mfma_f32_16x16x32_bf16 v[84:87], v[164:167], v[202:205], v[84:87]
	v_mfma_f32_16x16x32_bf16 v[80:83], v[178:181], v[202:205], v[80:83]
	v_mfma_f32_16x16x32_bf16 v[68:71], v[164:167], v[210:213], v[68:71]
	v_mfma_f32_16x16x32_bf16 v[64:67], v[178:181], v[210:213], v[64:67]
	v_mfma_f32_16x16x32_bf16 v[132:135], v[168:171], v[190:193], v[132:135]
	v_mfma_f32_16x16x32_bf16 v[128:131], v[182:185], v[190:193], v[128:131]
	v_mfma_f32_16x16x32_bf16 v[100:103], v[168:171], v[198:201], v[100:103]
	v_mfma_f32_16x16x32_bf16 v[96:99], v[182:185], v[198:201], v[96:99]
	v_mfma_f32_16x16x32_bf16 v[84:87], v[168:171], v[206:209], v[84:87]
	s_setprio 2
	s_barrier
; #define PG8_STAGE(bufoff, gbase, voff) do { _Pragma("unroll") for (int _i = 0; _i < 2; ++_i) \
;         __builtin_amdgcn_global_load_lds((const unsigned*)((const char*)(gbase) + (voff)[_i]), (PG8_LAS unsigned*)(lds + (bufoff) + ldsw + _i * 8192), 16, 0, 0); } while (0)
; #define PG8_LDA(dst, b, h) do { _Pragma("unroll") for (int m = 0; m < 4; ++m) _Pragma("unroll") for (int k = 0; k < 2; ++k) dst[m][k] = *(const PG8_LAS bf16x8*)(lds + PG8_SA(b, h) + aoff + m * 2048 + k * 1024); } while (0)
; #define PG8_MMA(ai, bj, At, Bt) do { __builtin_amdgcn_s_setprio(1); _Pragma("unroll") for (int m = 0; m < 4; ++m) _Pragma("unroll") for (int n = 0; n < 2; ++n) _Pragma("unroll") for (int k = 0; k < 2; ++k) \
;         acc[ai][bj][m][n] = __builtin_amdgcn_mfma_f32_16x16x32_bf16(Bt[n][k], At[m][k], acc[ai][bj][m][n], 0, 0, 0); __builtin_amdgcn_s_setprio(0); } while (0)
; #define PG8_WAIT_V(n) asm volatile("s_waitcnt vmcnt(" #n ")" ::: "memory")
; #define PG8_WAIT_L(n) asm volatile("s_waitcnt lgkmcnt(" #n ")" ::: "memory")
; #define PG8_BAR __builtin_amdgcn_s_barrier()
; #define PG8_SCHED __builtin_amdgcn_sched_barrier(0)
; template <class Epi, class Sched, bool ALIGN_EPI = false, bool SP2 = false>
; __device__ __forceinline__ void gemm_phase(PG8_LAS unsigned char* lds, const Gemm g, const Sched& S, const Epi& E) {
;     ...
;             PG8_WAIT_V(8); PG8_WAIT_L(0); PG8_BAR; PG8_MMA(0, 0, At, B0); PG8_MMA(0, 1, At, B1); PG8_BAR; PG8_SCHED;
;             PG8_LDA(At, 1, 1); PG8_STAGE(PG8_SB(1, 0), b3, voffB); PG8_STAGE(PG8_SB(1, 1), b3 + hstep, voffB); PG8_STAGE(PG8_SA(1, 0), a3, voffA);
;             PG8_WAIT_V(8); PG8_WAIT_L(0); PG8_BAR; PG8_MMA(1, 0, At, B0); PG8_MMA(1, 1, At, B1); PG8_BAR; PG8_SCHED;
;     ...
;         if constexpr (ALIGN_EPI) { if (wr == 0) PG8_BAR; }
	v_mfma_f32_16x16x32_bf16 v[80:83], v[182:185], v[206:209], v[80:83]
	v_mfma_f32_16x16x32_bf16 v[68:71], v[168:171], v[214:217], v[68:71]
	v_mfma_f32_16x16x32_bf16 v[64:67], v[182:185], v[214:217], v[64:67]
	s_setprio 0
	s_add_i32 s52, s56, s29
	v_lshl_add_u64 v[218:219], v[218:219], 0, s[12:13]
	s_mov_b32 m0, s52
	ds_read_b128 v[186:189], v176 offset:49152
	ds_read_b128 v[190:193], v176 offset:50176
	ds_read_b128 v[194:197], v176 offset:51200
	ds_read_b128 v[198:201], v176 offset:52224
	ds_read_b128 v[202:205], v176 offset:53248
	ds_read_b128 v[206:209], v176 offset:54272
	ds_read_b128 v[210:213], v176 offset:55296
	ds_read_b128 v[214:217], v176 offset:56320
	global_load_lds_dwordx4 v[218:219], off
	s_add_i32 m0, s52, 0x2000
	s_add_u32 s52, s70, 0x80080
	v_lshl_add_u64 v[218:219], v[220:221], 0, s[12:13]
	s_addc_u32 s53, s71, 0
	s_add_i32 s56, s57, s29
	global_load_lds_dwordx4 v[218:219], off
	v_lshl_add_u64 v[218:219], s[52:53], 0, v[152:153]
	s_mov_b32 m0, s56
	s_nop 0
	global_load_lds_dwordx4 v[218:219], off
	v_lshl_add_u64 v[218:219], s[52:53], 0, v[148:149]
	s_add_i32 m0, s56, 0x2000
	s_nop 0
	global_load_lds_dwordx4 v[218:219], off
	v_lshl_add_u64 v[218:219], v[222:223], 0, s[12:13]
	s_mov_b32 m0, s77
	s_nop 0
	global_load_lds_dwordx4 v[218:219], off
	v_lshl_add_u64 v[218:219], v[224:225], 0, s[12:13]
	s_mov_b32 m0, s78
	s_nop 0
	global_load_lds_dwordx4 v[218:219], off
	s_waitcnt vmcnt(8)
	s_waitcnt lgkmcnt(0)
	s_barrier
	s_setprio 1
	s_waitcnt lgkmcnt(0)
	v_mfma_f32_16x16x32_bf16 v[60:63], v[112:115], v[186:189], v[60:63]
	v_mfma_f32_16x16x32_bf16 v[56:59], v[120:123], v[186:189], v[56:59]
	v_mfma_f32_16x16x32_bf16 v[44:47], v[112:115], v[194:197], v[44:47]
	v_mfma_f32_16x16x32_bf16 v[40:43], v[120:123], v[194:197], v[40:43]
	v_mfma_f32_16x16x32_bf16 v[28:31], v[112:115], v[202:205], v[28:31]
	v_mfma_f32_16x16x32_bf16 v[24:27], v[120:123], v[202:205], v[24:27]
	v_mfma_f32_16x16x32_bf16 v[12:15], v[112:115], v[210:213], v[12:15]
	v_mfma_f32_16x16x32_bf16 v[8:11], v[120:123], v[210:213], v[8:11]
	v_mfma_f32_16x16x32_bf16 v[60:63], v[116:119], v[190:193], v[60:63]
	v_mfma_f32_16x16x32_bf16 v[56:59], v[124:127], v[190:193], v[56:59]
	v_mfma_f32_16x16x32_bf16 v[44:47], v[116:119], v[198:201], v[44:47]
	v_mfma_f32_16x16x32_bf16 v[40:43], v[124:127], v[198:201], v[40:43]
	v_mfma_f32_16x16x32_bf16 v[28:31], v[116:119], v[206:209], v[28:31]
	v_mfma_f32_16x16x32_bf16 v[24:27], v[124:127], v[206:209], v[24:27]
	v_mfma_f32_16x16x32_bf16 v[12:15], v[116:119], v[214:217], v[12:15]
	v_mfma_f32_16x16x32_bf16 v[8:11], v[124:127], v[214:217], v[8:11]
	s_setprio 0
	s_setprio 1
	v_mfma_f32_16x16x32_bf16 v[52:55], v[164:167], v[186:189], v[52:55]
	v_mfma_f32_16x16x32_bf16 v[48:51], v[178:181], v[186:189], v[48:51]
	v_mfma_f32_16x16x32_bf16 v[36:39], v[164:167], v[194:197], v[36:39]
	v_mfma_f32_16x16x32_bf16 v[32:35], v[178:181], v[194:197], v[32:35]
	v_mfma_f32_16x16x32_bf16 v[20:23], v[164:167], v[202:205], v[20:23]
	v_mfma_f32_16x16x32_bf16 v[16:19], v[178:181], v[202:205], v[16:19]
	v_mfma_f32_16x16x32_bf16 v[4:7], v[164:167], v[210:213], v[4:7]
	v_mfma_f32_16x16x32_bf16 v[0:3], v[178:181], v[210:213], v[0:3]
	v_mfma_f32_16x16x32_bf16 v[52:55], v[168:171], v[190:193], v[52:55]
	v_mfma_f32_16x16x32_bf16 v[48:51], v[182:185], v[190:193], v[48:51]
	v_mfma_f32_16x16x32_bf16 v[36:39], v[168:171], v[198:201], v[36:39]
	v_mfma_f32_16x16x32_bf16 v[32:35], v[182:185], v[198:201], v[32:35]
	v_mfma_f32_16x16x32_bf16 v[20:23], v[168:171], v[206:209], v[20:23]
	s_setprio 2
	s_barrier
	v_mfma_f32_16x16x32_bf16 v[16:19], v[182:185], v[206:209], v[16:19]
	v_mfma_f32_16x16x32_bf16 v[4:7], v[168:171], v[214:217], v[4:7]
	v_mfma_f32_16x16x32_bf16 v[0:3], v[182:185], v[214:217], v[0:3]
	s_setprio 0
	s_add_i32 s88, s88, 2
	s_add_u32 s68, s68, 0x100
	s_addc_u32 s69, s69, 0
	s_add_u32 s86, s86, 0x100
	s_addc_u32 s87, s87, 0
	s_cmp_gt_u32 s88, 29
	s_cbranch_scc0 .LBB0_545
	s_and_b64 vcc, exec, s[14:15]
	s_cbranch_vccz .LBB0_548
	s_barrier

; #define PG8_STAGE(bufoff, gbase, voff) do { _Pragma("unroll") for (int _i = 0; _i < 2; ++_i) \
;         __builtin_amdgcn_global_load_lds((const unsigned*)((const char*)(gbase) + (voff)[_i]), (PG8_LAS unsigned*)(lds + (bufoff) + ldsw + _i * 8192), 16, 0, 0); } while (0)
; #define PG8_LDA(dst, b, h) do { _Pragma("unroll") for (int m = 0; m < 4; ++m) _Pragma("unroll") for (int k = 0; k < 2; ++k) dst[m][k] = *(const PG8_LAS bf16x8*)(lds + PG8_SA(b, h) + aoff + m * 2048 + k * 1024); } while (0)
; #define PG8_LDB(dst, b, h) do { _Pragma("unroll") for (int n = 0; n < 2; ++n) _Pragma("unroll") for (int k = 0; k < 2; ++k) dst[n][k] = *(const PG8_LAS bf16x8*)(lds + PG8_SB(b, h) + boff + n * 2048 + k * 1024); } while (0)
; #define PG8_MMA(ai, bj, At, Bt) do { __builtin_amdgcn_s_setprio(1); _Pragma("unroll") for (int m = 0; m < 4; ++m) _Pragma("unroll") for (int n = 0; n < 2; ++n) _Pragma("unroll") for (int k = 0; k < 2; ++k) \
;         acc[ai][bj][m][n] = __builtin_amdgcn_mfma_f32_16x16x32_bf16(Bt[n][k], At[m][k], acc[ai][bj][m][n], 0, 0, 0); __builtin_amdgcn_s_setprio(0); } while (0)
; #define PG8_WAIT_V(n) asm volatile("s_waitcnt vmcnt(" #n ")" ::: "memory")
; #define PG8_WAIT_L(n) asm volatile("s_waitcnt lgkmcnt(" #n ")" ::: "memory")
; #define PG8_BAR __builtin_amdgcn_s_barrier()
; template <class Epi, class Sched, bool ALIGN_EPI = false, bool SP2 = false>
; __device__ __forceinline__ void gemm_phase(PG8_LAS unsigned char* lds, const Gemm g, const Sched& S, const Epi& E) {
;     ...
;             const bool last = (t == nt - 2);
;             const char* a1 = cA + (size_t)(t + 1) * kstep;
;             const char* a2 = last ? nA : cA + (size_t)(t + 2) * kstep; const char* b2 = last ? nB : cB + (size_t)(t + 2) * kstep;
;             const char* a3 = a2 + kstep; const char* b3 = b2 + kstep;
;             if constexpr (SP2) {
;             PG8_LDB(B0, 0, 0); PG8_LDB(B1, 0, 1); PG8_SCHED; PG8_LDA(At, 0, 0); PG8_STAGE(PG8_SA(1, 1), a1 + hstep, voffA);
;             PG8_WAIT_V(8); PG8_WAIT_L(0); PG8_BAR; PG8_MMA(0, 0, At, B0); PG8_MMA(0, 1, At, B1); PG8_BAR; PG8_SCHED;
;             PG8_LDA(At, 0, 1); PG8_STAGE(PG8_SB(0, 0), b2, voffB); PG8_STAGE(PG8_SB(0, 1), b2 + hstep, voffB); PG8_STAGE(PG8_SA(0, 0), a2, voffA);
;             PG8_WAIT_V(8); PG8_WAIT_L(0); PG8_BAR; PG8_MMA(1, 0, At, B0); PG8_MMA(1, 1, At, B1); PG8_BAR; PG8_SCHED;
.LBB0_624:
	ds_read_b128 v[128:131], v214
	ds_read_b128 v[132:135], v214 offset:1024
	ds_read_b128 v[158:161], v214 offset:2048
	ds_read_b128 v[162:165], v214 offset:3072
	ds_read_b128 v[166:169], v215
	ds_read_b128 v[170:173], v215 offset:1024
	ds_read_b128 v[174:177], v215 offset:2048
	ds_read_b128 v[178:181], v215 offset:3072
	s_add_u32 s52, s74, 0xffe00080
	s_addc_u32 s53, s75, -1
	s_cmpk_eq_i32 vcc_hi, 0x7c
	s_cselect_b32 s79, s51, s53
	s_cselect_b32 s78, s71, s52
	s_cselect_b32 s77, s49, vcc_lo
	s_cselect_b32 s76, s73, s93
	v_lshl_add_u64 v[226:227], s[74:75], 0, v[150:151]
	s_add_i32 m0, s83, 0xc000
	ds_read_b128 v[182:185], v216
	ds_read_b128 v[186:189], v216 offset:1024
	ds_read_b128 v[190:193], v216 offset:2048
	ds_read_b128 v[194:197], v216 offset:3072
	ds_read_b128 v[198:201], v216 offset:4096
	ds_read_b128 v[202:205], v216 offset:5120
	ds_read_b128 v[218:221], v216 offset:6144
	ds_read_b128 v[222:225], v216 offset:7168
	global_load_lds_dwordx4 v[226:227], off
	v_lshl_add_u64 v[226:227], s[74:75], 0, v[152:153]
	s_add_i32 m0, s83, 0xe000
	s_nop 0
	global_load_lds_dwordx4 v[226:227], off
	s_waitcnt vmcnt(8)
	s_waitcnt lgkmcnt(0)
	s_barrier
	s_setprio 1
	s_waitcnt lgkmcnt(0)
	v_mfma_f32_16x16x32_bf16 v[124:127], v[128:131], v[182:185], v[124:127]
	v_mfma_f32_16x16x32_bf16 v[120:123], v[158:161], v[182:185], v[120:123]
	v_mfma_f32_16x16x32_bf16 v[116:119], v[128:131], v[190:193], v[116:119]
	v_mfma_f32_16x16x32_bf16 v[112:115], v[158:161], v[190:193], v[112:115]
	v_mfma_f32_16x16x32_bf16 v[108:111], v[128:131], v[198:201], v[108:111]
	v_mfma_f32_16x16x32_bf16 v[104:107], v[158:161], v[198:201], v[104:107]
	v_mfma_f32_16x16x32_bf16 v[100:103], v[128:131], v[218:221], v[100:103]
	v_mfma_f32_16x16x32_bf16 v[96:99], v[158:161], v[218:221], v[96:99]
	v_mfma_f32_16x16x32_bf16 v[124:127], v[132:135], v[186:189], v[124:127]
	v_mfma_f32_16x16x32_bf16 v[120:123], v[162:165], v[186:189], v[120:123]
	v_mfma_f32_16x16x32_bf16 v[116:119], v[132:135], v[194:197], v[116:119]
	v_mfma_f32_16x16x32_bf16 v[112:115], v[162:165], v[194:197], v[112:115]
	v_mfma_f32_16x16x32_bf16 v[108:111], v[132:135], v[202:205], v[108:111]
	v_mfma_f32_16x16x32_bf16 v[104:107], v[162:165], v[202:205], v[104:107]
	v_mfma_f32_16x16x32_bf16 v[100:103], v[132:135], v[222:225], v[100:103]
	v_mfma_f32_16x16x32_bf16 v[96:99], v[162:165], v[222:225], v[96:99]
	s_setprio 0
	s_setprio 1
	v_mfma_f32_16x16x32_bf16 v[60:63], v[166:169], v[182:185], v[60:63]
	v_mfma_f32_16x16x32_bf16 v[56:59], v[174:177], v[182:185], v[56:59]
	v_mfma_f32_16x16x32_bf16 v[52:55], v[166:169], v[190:193], v[52:55]
	v_mfma_f32_16x16x32_bf16 v[48:51], v[174:177], v[190:193], v[48:51]
	v_mfma_f32_16x16x32_bf16 v[44:47], v[166:169], v[198:201], v[44:47]
	v_mfma_f32_16x16x32_bf16 v[40:43], v[174:177], v[198:201], v[40:43]
	v_mfma_f32_16x16x32_bf16 v[36:39], v[166:169], v[218:221], v[36:39]
	v_mfma_f32_16x16x32_bf16 v[32:35], v[174:177], v[218:221], v[32:35]
	v_mfma_f32_16x16x32_bf16 v[60:63], v[170:173], v[186:189], v[60:63]
	v_mfma_f32_16x16x32_bf16 v[56:59], v[178:181], v[186:189], v[56:59]
	v_mfma_f32_16x16x32_bf16 v[52:55], v[170:173], v[194:197], v[52:55]
	v_mfma_f32_16x16x32_bf16 v[48:51], v[178:181], v[194:197], v[48:51]
	v_mfma_f32_16x16x32_bf16 v[44:47], v[170:173], v[202:205], v[44:47]
	s_setprio 2
	s_barrier
	v_mfma_f32_16x16x32_bf16 v[40:43], v[178:181], v[202:205], v[40:43]
	v_mfma_f32_16x16x32_bf16 v[36:39], v[170:173], v[222:225], v[36:39]
	v_mfma_f32_16x16x32_bf16 v[32:35], v[178:181], v[222:225], v[32:35]
	s_setprio 0
	s_add_i32 s52, s33, s82
	v_lshl_add_u64 v[226:227], s[76:77], 0, v[138:139]
	s_mov_b32 m0, s52
	ds_read_b128 v[182:185], v216 offset:16384
	ds_read_b128 v[186:189], v216 offset:17408
	ds_read_b128 v[190:193], v216 offset:18432
	ds_read_b128 v[194:197], v216 offset:19456
	ds_read_b128 v[198:201], v216 offset:20480
	ds_read_b128 v[202:205], v216 offset:21504
	ds_read_b128 v[218:221], v216 offset:22528
	ds_read_b128 v[222:225], v216 offset:23552
	global_load_lds_dwordx4 v[226:227], off
	s_add_i32 m0, s52, 0x2000
	s_add_u32 s52, s76, 0x200000
	v_lshl_add_u64 v[228:229], s[76:77], 0, v[142:143]
	s_addc_u32 s53, s77, 0
	s_add_i32 s56, s92, s82
	global_load_lds_dwordx4 v[228:229], off
	v_lshl_add_u64 v[230:231], s[52:53], 0, v[138:139]
	s_mov_b32 m0, s56
	v_lshl_add_u64 v[232:233], s[78:79], 0, v[140:141]
	global_load_lds_dwordx4 v[230:231], off
	v_lshl_add_u64 v[230:231], s[52:53], 0, v[142:143]
	s_add_i32 m0, s56, 0x2000
	s_nop 0
	global_load_lds_dwordx4 v[230:231], off
	v_lshl_add_u64 v[230:231], s[78:79], 0, v[136:137]
	s_mov_b32 m0, s83
	s_nop 0
	global_load_lds_dwordx4 v[230:231], off
	s_mov_b32 m0, s84
	s_nop 0
	global_load_lds_dwordx4 v[232:233], off
	s_waitcnt vmcnt(8)
	s_waitcnt lgkmcnt(0)
	s_barrier
; #define PG8_STAGE(bufoff, gbase, voff) do { _Pragma("unroll") for (int _i = 0; _i < 2; ++_i) \
;         __builtin_amdgcn_global_load_lds((const unsigned*)((const char*)(gbase) + (voff)[_i]), (PG8_LAS unsigned*)(lds + (bufoff) + ldsw + _i * 8192), 16, 0, 0); } while (0)
; #define PG8_LDA(dst, b, h) do { _Pragma("unroll") for (int m = 0; m < 4; ++m) _Pragma("unroll") for (int k = 0; k < 2; ++k) dst[m][k] = *(const PG8_LAS bf16x8*)(lds + PG8_SA(b, h) + aoff + m * 2048 + k * 1024); } while (0)
; #define PG8_LDB(dst, b, h) do { _Pragma("unroll") for (int n = 0; n < 2; ++n) _Pragma("unroll") for (int k = 0; k < 2; ++k) dst[n][k] = *(const PG8_LAS bf16x8*)(lds + PG8_SB(b, h) + boff + n * 2048 + k * 1024); } while (0)
; #define PG8_MMA(ai, bj, At, Bt) do { __builtin_amdgcn_s_setprio(1); _Pragma("unroll") for (int m = 0; m < 4; ++m) _Pragma("unroll") for (int n = 0; n < 2; ++n) _Pragma("unroll") for (int k = 0; k < 2; ++k) \
;         acc[ai][bj][m][n] = __builtin_amdgcn_mfma_f32_16x16x32_bf16(Bt[n][k], At[m][k], acc[ai][bj][m][n], 0, 0, 0); __builtin_amdgcn_s_setprio(0); } while (0)
; #define PG8_WAIT_V(n) asm volatile("s_waitcnt vmcnt(" #n ")" ::: "memory")
; #define PG8_WAIT_L(n) asm volatile("s_waitcnt lgkmcnt(" #n ")" ::: "memory")
; #define PG8_BAR __builtin_amdgcn_s_barrier()
; #define PG8_SCHED __builtin_amdgcn_sched_barrier(0)
; template <class Epi, class Sched, bool ALIGN_EPI = false, bool SP2 = false>
; __device__ __forceinline__ void gemm_phase(PG8_LAS unsigned char* lds, const Gemm g, const Sched& S, const Epi& E) {
;     ...
;             PG8_WAIT_V(8); PG8_WAIT_L(0); PG8_BAR; PG8_MMA(1, 0, At, B0); PG8_MMA(1, 1, At, B1); PG8_BAR; PG8_SCHED;
;             PG8_LDB(B0, 1, 0); PG8_LDB(B1, 1, 1); PG8_SCHED; PG8_LDA(At, 1, 0); PG8_STAGE(PG8_SA(0, 1), a2 + hstep, voffA);
;             PG8_WAIT_V(8); PG8_WAIT_L(0); PG8_BAR; PG8_MMA(0, 0, At, B0); PG8_MMA(0, 1, At, B1); PG8_BAR; PG8_SCHED;
	s_setprio 1
	s_waitcnt lgkmcnt(0)
	v_mfma_f32_16x16x32_bf16 v[92:95], v[128:131], v[182:185], v[92:95]
	v_mfma_f32_16x16x32_bf16 v[88:91], v[158:161], v[182:185], v[88:91]
	v_mfma_f32_16x16x32_bf16 v[84:87], v[128:131], v[190:193], v[84:87]
	v_mfma_f32_16x16x32_bf16 v[80:83], v[158:161], v[190:193], v[80:83]
	v_mfma_f32_16x16x32_bf16 v[76:79], v[128:131], v[198:201], v[76:79]
	v_mfma_f32_16x16x32_bf16 v[72:75], v[158:161], v[198:201], v[72:75]
	v_mfma_f32_16x16x32_bf16 v[68:71], v[128:131], v[218:221], v[68:71]
	v_mfma_f32_16x16x32_bf16 v[64:67], v[158:161], v[218:221], v[64:67]
	v_mfma_f32_16x16x32_bf16 v[92:95], v[132:135], v[186:189], v[92:95]
	v_mfma_f32_16x16x32_bf16 v[88:91], v[162:165], v[186:189], v[88:91]
	v_mfma_f32_16x16x32_bf16 v[84:87], v[132:135], v[194:197], v[84:87]
	v_mfma_f32_16x16x32_bf16 v[80:83], v[162:165], v[194:197], v[80:83]
	v_mfma_f32_16x16x32_bf16 v[76:79], v[132:135], v[202:205], v[76:79]
	v_mfma_f32_16x16x32_bf16 v[72:75], v[162:165], v[202:205], v[72:75]
	v_mfma_f32_16x16x32_bf16 v[68:71], v[132:135], v[222:225], v[68:71]
	v_mfma_f32_16x16x32_bf16 v[64:67], v[162:165], v[222:225], v[64:67]
	s_setprio 0
	s_setprio 1
	v_mfma_f32_16x16x32_bf16 v[28:31], v[166:169], v[182:185], v[28:31]
	v_mfma_f32_16x16x32_bf16 v[24:27], v[174:177], v[182:185], v[24:27]
	v_mfma_f32_16x16x32_bf16 v[20:23], v[166:169], v[190:193], v[20:23]
	v_mfma_f32_16x16x32_bf16 v[16:19], v[174:177], v[190:193], v[16:19]
	v_mfma_f32_16x16x32_bf16 v[12:15], v[166:169], v[198:201], v[12:15]
	v_mfma_f32_16x16x32_bf16 v[8:11], v[174:177], v[198:201], v[8:11]
	v_mfma_f32_16x16x32_bf16 v[4:7], v[166:169], v[218:221], v[4:7]
	v_mfma_f32_16x16x32_bf16 v[0:3], v[174:177], v[218:221], v[0:3]
	v_mfma_f32_16x16x32_bf16 v[28:31], v[170:173], v[186:189], v[28:31]
	v_mfma_f32_16x16x32_bf16 v[24:27], v[178:181], v[186:189], v[24:27]
	v_mfma_f32_16x16x32_bf16 v[20:23], v[170:173], v[194:197], v[20:23]
	v_mfma_f32_16x16x32_bf16 v[16:19], v[178:181], v[194:197], v[16:19]
	v_mfma_f32_16x16x32_bf16 v[12:15], v[170:173], v[202:205], v[12:15]
	s_setprio 2
	s_barrier
	v_mfma_f32_16x16x32_bf16 v[8:11], v[178:181], v[202:205], v[8:11]
	v_mfma_f32_16x16x32_bf16 v[4:7], v[170:173], v[222:225], v[4:7]
	v_mfma_f32_16x16x32_bf16 v[0:3], v[178:181], v[222:225], v[0:3]
	s_setprio 0
	s_add_i32 s56, 0, 0x18000
	s_add_i32 s57, 0, 0x1c000
	v_add_u32_e32 v162, s56, v212
	v_add_u32_e32 v178, s57, v212
	ds_read_b128 v[128:131], v162
	ds_read_b128 v[132:135], v162 offset:1024
	ds_read_b128 v[158:161], v162 offset:2048
	ds_read_b128 v[162:165], v162 offset:3072
	ds_read_b128 v[166:169], v178
	ds_read_b128 v[170:173], v178 offset:1024
	ds_read_b128 v[174:177], v178 offset:2048
	ds_read_b128 v[178:181], v178 offset:3072
	s_add_u32 s52, s78, 0x200000
	s_addc_u32 s53, s79, 0
	s_mov_b32 m0, s85
	v_lshl_add_u64 v[234:235], s[52:53], 0, v[136:137]
	ds_read_b128 v[182:185], v216 offset:32768
	ds_read_b128 v[186:189], v216 offset:33792
	ds_read_b128 v[190:193], v216 offset:34816
	ds_read_b128 v[194:197], v216 offset:35840
	ds_read_b128 v[198:201], v216 offset:36864
	ds_read_b128 v[202:205], v216 offset:37888
	ds_read_b128 v[218:221], v216 offset:38912
	ds_read_b128 v[222:225], v216 offset:39936
	global_load_lds_dwordx4 v[234:235], off
	v_lshl_add_u64 v[234:235], s[52:53], 0, v[140:141]
	s_mov_b32 m0, s86
	s_nop 0
	global_load_lds_dwordx4 v[234:235], off
	s_waitcnt vmcnt(8)
	s_waitcnt lgkmcnt(0)
	s_barrier
	s_setprio 1
	s_waitcnt lgkmcnt(0)
	v_mfma_f32_16x16x32_bf16 v[124:127], v[128:131], v[182:185], v[124:127]
	v_mfma_f32_16x16x32_bf16 v[120:123], v[158:161], v[182:185], v[120:123]
	v_mfma_f32_16x16x32_bf16 v[116:119], v[128:131], v[190:193], v[116:119]
	v_mfma_f32_16x16x32_bf16 v[112:115], v[158:161], v[190:193], v[112:115]
	v_mfma_f32_16x16x32_bf16 v[108:111], v[128:131], v[198:201], v[108:111]
	v_mfma_f32_16x16x32_bf16 v[104:107], v[158:161], v[198:201], v[104:107]
	v_mfma_f32_16x16x32_bf16 v[100:103], v[128:131], v[218:221], v[100:103]
	v_mfma_f32_16x16x32_bf16 v[96:99], v[158:161], v[218:221], v[96:99]
	v_mfma_f32_16x16x32_bf16 v[124:127], v[132:135], v[186:189], v[124:127]
	v_mfma_f32_16x16x32_bf16 v[120:123], v[162:165], v[186:189], v[120:123]
	v_mfma_f32_16x16x32_bf16 v[116:119], v[132:135], v[194:197], v[116:119]
	v_mfma_f32_16x16x32_bf16 v[112:115], v[162:165], v[194:197], v[112:115]
	v_mfma_f32_16x16x32_bf16 v[108:111], v[132:135], v[202:205], v[108:111]
	v_mfma_f32_16x16x32_bf16 v[104:107], v[162:165], v[202:205], v[104:107]
	v_mfma_f32_16x16x32_bf16 v[100:103], v[132:135], v[222:225], v[100:103]
	v_mfma_f32_16x16x32_bf16 v[96:99], v[162:165], v[222:225], v[96:99]
	s_setprio 0
	s_setprio 1
	v_mfma_f32_16x16x32_bf16 v[60:63], v[166:169], v[182:185], v[60:63]
	v_mfma_f32_16x16x32_bf16 v[56:59], v[174:177], v[182:185], v[56:59]
	v_mfma_f32_16x16x32_bf16 v[52:55], v[166:169], v[190:193], v[52:55]
	v_mfma_f32_16x16x32_bf16 v[48:51], v[174:177], v[190:193], v[48:51]
	v_mfma_f32_16x16x32_bf16 v[44:47], v[166:169], v[198:201], v[44:47]
	v_mfma_f32_16x16x32_bf16 v[40:43], v[174:177], v[198:201], v[40:43]
	v_mfma_f32_16x16x32_bf16 v[36:39], v[166:169], v[218:221], v[36:39]
	v_mfma_f32_16x16x32_bf16 v[32:35], v[174:177], v[218:221], v[32:35]
	v_mfma_f32_16x16x32_bf16 v[60:63], v[170:173], v[186:189], v[60:63]
	v_mfma_f32_16x16x32_bf16 v[56:59], v[178:181], v[186:189], v[56:59]
	v_mfma_f32_16x16x32_bf16 v[52:55], v[170:173], v[194:197], v[52:55]
	v_mfma_f32_16x16x32_bf16 v[48:51], v[178:181], v[194:197], v[48:51]
	v_mfma_f32_16x16x32_bf16 v[44:47], v[170:173], v[202:205], v[44:47]
	s_setprio 2
	s_barrier
; #define PG8_STAGE(bufoff, gbase, voff) do { _Pragma("unroll") for (int _i = 0; _i < 2; ++_i) \
;         __builtin_amdgcn_global_load_lds((const unsigned*)((const char*)(gbase) + (voff)[_i]), (PG8_LAS unsigned*)(lds + (bufoff) + ldsw + _i * 8192), 16, 0, 0); } while (0)
; #define PG8_LDA(dst, b, h) do { _Pragma("unroll") for (int m = 0; m < 4; ++m) _Pragma("unroll") for (int k = 0; k < 2; ++k) dst[m][k] = *(const PG8_LAS bf16x8*)(lds + PG8_SA(b, h) + aoff + m * 2048 + k * 1024); } while (0)
; #define PG8_MMA(ai, bj, At, Bt) do { __builtin_amdgcn_s_setprio(1); _Pragma("unroll") for (int m = 0; m < 4; ++m) _Pragma("unroll") for (int n = 0; n < 2; ++n) _Pragma("unroll") for (int k = 0; k < 2; ++k) \
;         acc[ai][bj][m][n] = __builtin_amdgcn_mfma_f32_16x16x32_bf16(Bt[n][k], At[m][k], acc[ai][bj][m][n], 0, 0, 0); __builtin_amdgcn_s_setprio(0); } while (0)
; #define PG8_WAIT_V(n) asm volatile("s_waitcnt vmcnt(" #n ")" ::: "memory")
; #define PG8_WAIT_L(n) asm volatile("s_waitcnt lgkmcnt(" #n ")" ::: "memory")
; #define PG8_BAR __builtin_amdgcn_s_barrier()
; #define PG8_SCHED __builtin_amdgcn_sched_barrier(0)
; template <class Epi, class Sched, bool ALIGN_EPI = false, bool SP2 = false>
; __device__ __forceinline__ void gemm_phase(PG8_LAS unsigned char* lds, const Gemm g, const Sched& S, const Epi& E) {
;     ...
;             PG8_WAIT_V(8); PG8_WAIT_L(0); PG8_BAR; PG8_MMA(0, 0, At, B0); PG8_MMA(0, 1, At, B1); PG8_BAR; PG8_SCHED;
;             PG8_LDA(At, 1, 1); PG8_STAGE(PG8_SB(1, 0), b3, voffB); PG8_STAGE(PG8_SB(1, 1), b3 + hstep, voffB); PG8_STAGE(PG8_SA(1, 0), a3, voffA);
;             PG8_WAIT_V(8); PG8_WAIT_L(0); PG8_BAR; PG8_MMA(1, 0, At, B0); PG8_MMA(1, 1, At, B1); PG8_BAR; PG8_SCHED;
;     ...
;         if constexpr (ALIGN_EPI) { if (wr == 0) PG8_BAR; }
	v_mfma_f32_16x16x32_bf16 v[40:43], v[178:181], v[202:205], v[40:43]
	v_mfma_f32_16x16x32_bf16 v[36:39], v[170:173], v[222:225], v[36:39]
	v_mfma_f32_16x16x32_bf16 v[32:35], v[178:181], v[222:225], v[32:35]
	s_setprio 0
	s_add_i32 s52, s56, s82
	v_lshl_add_u64 v[226:227], v[226:227], 0, s[36:37]
	s_mov_b32 m0, s52
	ds_read_b128 v[182:185], v216 offset:49152
	ds_read_b128 v[186:189], v216 offset:50176
	ds_read_b128 v[190:193], v216 offset:51200
	ds_read_b128 v[194:197], v216 offset:52224
	ds_read_b128 v[198:201], v216 offset:53248
	ds_read_b128 v[202:205], v216 offset:54272
	ds_read_b128 v[218:221], v216 offset:55296
	ds_read_b128 v[222:225], v216 offset:56320
	global_load_lds_dwordx4 v[226:227], off
	s_add_i32 m0, s52, 0x2000
	s_add_u32 s52, s76, 0x200080
	v_lshl_add_u64 v[226:227], v[228:229], 0, s[36:37]
	s_addc_u32 s53, s77, 0
	s_add_i32 s56, s57, s82
	global_load_lds_dwordx4 v[226:227], off
	v_lshl_add_u64 v[226:227], s[52:53], 0, v[138:139]
	s_mov_b32 m0, s56
	s_nop 0
	global_load_lds_dwordx4 v[226:227], off
	v_lshl_add_u64 v[226:227], s[52:53], 0, v[142:143]
	s_add_i32 m0, s56, 0x2000
	s_nop 0
	global_load_lds_dwordx4 v[226:227], off
	v_lshl_add_u64 v[226:227], v[230:231], 0, s[36:37]
	s_mov_b32 m0, s94
	s_nop 0
	global_load_lds_dwordx4 v[226:227], off
	v_lshl_add_u64 v[226:227], v[232:233], 0, s[36:37]
	s_mov_b32 m0, s95
	s_nop 0
	global_load_lds_dwordx4 v[226:227], off
	s_waitcnt vmcnt(8)
	s_waitcnt lgkmcnt(0)
	s_barrier
	s_setprio 1
	s_waitcnt lgkmcnt(0)
	v_mfma_f32_16x16x32_bf16 v[92:95], v[128:131], v[182:185], v[92:95]
	v_mfma_f32_16x16x32_bf16 v[88:91], v[158:161], v[182:185], v[88:91]
	v_mfma_f32_16x16x32_bf16 v[84:87], v[128:131], v[190:193], v[84:87]
	v_mfma_f32_16x16x32_bf16 v[80:83], v[158:161], v[190:193], v[80:83]
	v_mfma_f32_16x16x32_bf16 v[76:79], v[128:131], v[198:201], v[76:79]
	v_mfma_f32_16x16x32_bf16 v[72:75], v[158:161], v[198:201], v[72:75]
	v_mfma_f32_16x16x32_bf16 v[68:71], v[128:131], v[218:221], v[68:71]
	v_mfma_f32_16x16x32_bf16 v[64:67], v[158:161], v[218:221], v[64:67]
	v_mfma_f32_16x16x32_bf16 v[92:95], v[132:135], v[186:189], v[92:95]
	v_mfma_f32_16x16x32_bf16 v[88:91], v[162:165], v[186:189], v[88:91]
	v_mfma_f32_16x16x32_bf16 v[84:87], v[132:135], v[194:197], v[84:87]
	v_mfma_f32_16x16x32_bf16 v[80:83], v[162:165], v[194:197], v[80:83]
	v_mfma_f32_16x16x32_bf16 v[76:79], v[132:135], v[202:205], v[76:79]
	v_mfma_f32_16x16x32_bf16 v[72:75], v[162:165], v[202:205], v[72:75]
	v_mfma_f32_16x16x32_bf16 v[68:71], v[132:135], v[222:225], v[68:71]
	v_mfma_f32_16x16x32_bf16 v[64:67], v[162:165], v[222:225], v[64:67]
	s_setprio 0
	s_setprio 1
	v_mfma_f32_16x16x32_bf16 v[28:31], v[166:169], v[182:185], v[28:31]
	v_mfma_f32_16x16x32_bf16 v[24:27], v[174:177], v[182:185], v[24:27]
	v_mfma_f32_16x16x32_bf16 v[20:23], v[166:169], v[190:193], v[20:23]
	v_mfma_f32_16x16x32_bf16 v[16:19], v[174:177], v[190:193], v[16:19]
	v_mfma_f32_16x16x32_bf16 v[12:15], v[166:169], v[198:201], v[12:15]
	v_mfma_f32_16x16x32_bf16 v[8:11], v[174:177], v[198:201], v[8:11]
	v_mfma_f32_16x16x32_bf16 v[4:7], v[166:169], v[218:221], v[4:7]
	v_mfma_f32_16x16x32_bf16 v[0:3], v[174:177], v[218:221], v[0:3]
	v_mfma_f32_16x16x32_bf16 v[28:31], v[170:173], v[186:189], v[28:31]
	v_mfma_f32_16x16x32_bf16 v[24:27], v[178:181], v[186:189], v[24:27]
	v_mfma_f32_16x16x32_bf16 v[20:23], v[170:173], v[194:197], v[20:23]
	v_mfma_f32_16x16x32_bf16 v[16:19], v[178:181], v[194:197], v[16:19]
	v_mfma_f32_16x16x32_bf16 v[12:15], v[170:173], v[202:205], v[12:15]
	s_setprio 2
	s_barrier
	v_mfma_f32_16x16x32_bf16 v[8:11], v[178:181], v[202:205], v[8:11]
	v_mfma_f32_16x16x32_bf16 v[4:7], v[170:173], v[222:225], v[4:7]
	v_mfma_f32_16x16x32_bf16 v[0:3], v[178:181], v[222:225], v[0:3]
	s_setprio 0
	s_add_i32 vcc_hi, vcc_hi, 2
	s_add_u32 s74, s74, 0x100
	s_addc_u32 s75, s75, 0
	s_add_u32 s93, s93, 0x100
	s_addc_u32 vcc_lo, vcc_lo, 0
	s_cmpk_gt_u32 vcc_hi, 0x7d
	s_cbranch_scc0 .LBB0_624
	s_and_b64 vcc, exec, s[40:41]
	s_cbranch_vccz .LBB0_627
	s_barrier

; #define PG8_STAGE(bufoff, gbase, voff) do { _Pragma("unroll") for (int _i = 0; _i < 2; ++_i) \
;         __builtin_amdgcn_global_load_lds((const unsigned*)((const char*)(gbase) + (voff)[_i]), (PG8_LAS unsigned*)(lds + (bufoff) + ldsw + _i * 8192), 16, 0, 0); } while (0)
; #define PG8_LDA(dst, b, h) do { _Pragma("unroll") for (int m = 0; m < 4; ++m) _Pragma("unroll") for (int k = 0; k < 2; ++k) dst[m][k] = *(const PG8_LAS bf16x8*)(lds + PG8_SA(b, h) + aoff + m * 2048 + k * 1024); } while (0)
; #define PG8_LDB(dst, b, h) do { _Pragma("unroll") for (int n = 0; n < 2; ++n) _Pragma("unroll") for (int k = 0; k < 2; ++k) dst[n][k] = *(const PG8_LAS bf16x8*)(lds + PG8_SB(b, h) + boff + n * 2048 + k * 1024); } while (0)
; #define PG8_MMA(ai, bj, At, Bt) do { __builtin_amdgcn_s_setprio(1); _Pragma("unroll") for (int m = 0; m < 4; ++m) _Pragma("unroll") for (int n = 0; n < 2; ++n) _Pragma("unroll") for (int k = 0; k < 2; ++k) \
;         acc[ai][bj][m][n] = __builtin_amdgcn_mfma_f32_16x16x32_bf16(Bt[n][k], At[m][k], acc[ai][bj][m][n], 0, 0, 0); __builtin_amdgcn_s_setprio(0); } while (0)
; #define PG8_WAIT_V(n) asm volatile("s_waitcnt vmcnt(" #n ")" ::: "memory")
; #define PG8_WAIT_L(n) asm volatile("s_waitcnt lgkmcnt(" #n ")" ::: "memory")
; #define PG8_BAR __builtin_amdgcn_s_barrier()
; template <class Epi, class Sched, bool ALIGN_EPI = false, bool SP2 = false>
; __device__ __forceinline__ void gemm_phase(PG8_LAS unsigned char* lds, const Gemm g, const Sched& S, const Epi& E) {
;     ...
;             const bool last = (t == nt - 2);
;             const char* a1 = cA + (size_t)(t + 1) * kstep;
;             const char* a2 = last ? nA : cA + (size_t)(t + 2) * kstep; const char* b2 = last ? nB : cB + (size_t)(t + 2) * kstep;
;             const char* a3 = a2 + kstep; const char* b3 = b2 + kstep;
;             if constexpr (SP2) {
;             PG8_LDB(B0, 0, 0); PG8_LDB(B1, 0, 1); PG8_SCHED; PG8_LDA(At, 0, 0); PG8_STAGE(PG8_SA(1, 1), a1 + hstep, voffA);
;             PG8_WAIT_V(8); PG8_WAIT_L(0); PG8_BAR; PG8_MMA(0, 0, At, B0); PG8_MMA(0, 1, At, B1); PG8_BAR; PG8_SCHED;
;             PG8_LDA(At, 0, 1); PG8_STAGE(PG8_SB(0, 0), b2, voffB); PG8_STAGE(PG8_SB(0, 1), b2 + hstep, voffB); PG8_STAGE(PG8_SA(0, 0), a2, voffA);
;             PG8_WAIT_V(8); PG8_WAIT_L(0); PG8_BAR; PG8_MMA(1, 0, At, B0); PG8_MMA(1, 1, At, B1); PG8_BAR; PG8_SCHED;
.LBB0_660:
	ds_read_b128 v[166:169], v145
	ds_read_b128 v[170:173], v145 offset:1024
	ds_read_b128 v[174:177], v145 offset:2048
	ds_read_b128 v[178:181], v145 offset:3072
	ds_read_b128 v[182:185], v149
	ds_read_b128 v[186:189], v149 offset:1024
	ds_read_b128 v[190:193], v149 offset:2048
	ds_read_b128 v[194:197], v149 offset:3072
	s_add_u32 s52, s72, 0xffe00080
	s_addc_u32 s53, s73, -1
	s_cmp_eq_u32 s49, 28
	s_cselect_b32 s77, s51, s53
	s_cselect_b32 s76, s50, s52
	s_cselect_b32 s75, s55, s41
	s_cselect_b32 s74, s54, s37
	s_mov_b32 m0, s82
	v_lshl_add_u64 v[230:231], s[72:73], 0, v[160:161]
	ds_read_b128 v[198:201], v164
	ds_read_b128 v[202:205], v164 offset:1024
	ds_read_b128 v[206:209], v164 offset:2048
	ds_read_b128 v[210:213], v164 offset:3072
	ds_read_b128 v[214:217], v164 offset:4096
	ds_read_b128 v[218:221], v164 offset:5120
	ds_read_b128 v[222:225], v164 offset:6144
	ds_read_b128 v[226:229], v164 offset:7168
	global_load_lds_dwordx4 v[230:231], off
	v_lshl_add_u64 v[230:231], s[72:73], 0, v[162:163]
	s_mov_b32 m0, s83
	s_nop 0
	global_load_lds_dwordx4 v[230:231], off
	s_waitcnt vmcnt(8)
	s_waitcnt lgkmcnt(0)
	s_barrier
	s_setprio 1
	s_waitcnt lgkmcnt(0)
	v_mfma_f32_16x16x32_bf16 v[124:127], v[166:169], v[198:201], v[124:127]
	v_mfma_f32_16x16x32_bf16 v[120:123], v[174:177], v[198:201], v[120:123]
	v_mfma_f32_16x16x32_bf16 v[116:119], v[166:169], v[206:209], v[116:119]
	v_mfma_f32_16x16x32_bf16 v[108:111], v[174:177], v[206:209], v[108:111]
	v_mfma_f32_16x16x32_bf16 v[100:103], v[166:169], v[214:217], v[100:103]
	v_mfma_f32_16x16x32_bf16 v[92:95], v[174:177], v[214:217], v[92:95]
	v_mfma_f32_16x16x32_bf16 v[84:87], v[166:169], v[222:225], v[84:87]
	v_mfma_f32_16x16x32_bf16 v[76:79], v[174:177], v[222:225], v[76:79]
	v_mfma_f32_16x16x32_bf16 v[124:127], v[170:173], v[202:205], v[124:127]
	v_mfma_f32_16x16x32_bf16 v[120:123], v[178:181], v[202:205], v[120:123]
	v_mfma_f32_16x16x32_bf16 v[116:119], v[170:173], v[210:213], v[116:119]
	v_mfma_f32_16x16x32_bf16 v[108:111], v[178:181], v[210:213], v[108:111]
	v_mfma_f32_16x16x32_bf16 v[100:103], v[170:173], v[218:221], v[100:103]
	v_mfma_f32_16x16x32_bf16 v[92:95], v[178:181], v[218:221], v[92:95]
	v_mfma_f32_16x16x32_bf16 v[84:87], v[170:173], v[226:229], v[84:87]
	v_mfma_f32_16x16x32_bf16 v[76:79], v[178:181], v[226:229], v[76:79]
	s_setprio 0
	s_setprio 1
	v_mfma_f32_16x16x32_bf16 v[112:115], v[182:185], v[198:201], v[112:115]
	v_mfma_f32_16x16x32_bf16 v[104:107], v[190:193], v[198:201], v[104:107]
	v_mfma_f32_16x16x32_bf16 v[96:99], v[182:185], v[206:209], v[96:99]
	v_mfma_f32_16x16x32_bf16 v[88:91], v[190:193], v[206:209], v[88:91]
	v_mfma_f32_16x16x32_bf16 v[80:83], v[182:185], v[214:217], v[80:83]
	v_mfma_f32_16x16x32_bf16 v[72:75], v[190:193], v[214:217], v[72:75]
	v_mfma_f32_16x16x32_bf16 v[68:71], v[182:185], v[222:225], v[68:71]
	v_mfma_f32_16x16x32_bf16 v[64:67], v[190:193], v[222:225], v[64:67]
	v_mfma_f32_16x16x32_bf16 v[112:115], v[186:189], v[202:205], v[112:115]
	v_mfma_f32_16x16x32_bf16 v[104:107], v[194:197], v[202:205], v[104:107]
	v_mfma_f32_16x16x32_bf16 v[96:99], v[186:189], v[210:213], v[96:99]
	v_mfma_f32_16x16x32_bf16 v[88:91], v[194:197], v[210:213], v[88:91]
	v_mfma_f32_16x16x32_bf16 v[80:83], v[186:189], v[218:221], v[80:83]
	s_setprio 2
	s_barrier
	v_mfma_f32_16x16x32_bf16 v[72:75], v[194:197], v[218:221], v[72:75]
	v_mfma_f32_16x16x32_bf16 v[68:71], v[186:189], v[226:229], v[68:71]
	v_mfma_f32_16x16x32_bf16 v[64:67], v[194:197], v[226:229], v[64:67]
	s_setprio 0
	s_mov_b32 m0, s84
	v_lshl_add_u64 v[230:231], s[74:75], 0, v[138:139]
	s_add_u32 s52, s74, 0x200000
	ds_read_b128 v[198:201], v164 offset:16384
	ds_read_b128 v[202:205], v164 offset:17408
	ds_read_b128 v[206:209], v164 offset:18432
	ds_read_b128 v[210:213], v164 offset:19456
	ds_read_b128 v[214:217], v164 offset:20480
	ds_read_b128 v[218:221], v164 offset:21504
	ds_read_b128 v[222:225], v164 offset:22528
	ds_read_b128 v[226:229], v164 offset:23552
	global_load_lds_dwordx4 v[230:231], off
	v_lshl_add_u64 v[232:233], s[74:75], 0, v[142:143]
	s_mov_b32 m0, s85
	s_addc_u32 s53, s75, 0
	global_load_lds_dwordx4 v[232:233], off
	v_lshl_add_u64 v[234:235], s[52:53], 0, v[138:139]
	s_mov_b32 m0, s86
	v_lshl_add_u64 v[236:237], s[76:77], 0, v[140:141]
	global_load_lds_dwordx4 v[234:235], off
	v_lshl_add_u64 v[234:235], s[52:53], 0, v[142:143]
	s_mov_b32 m0, s87
	s_nop 0
	global_load_lds_dwordx4 v[234:235], off
	v_lshl_add_u64 v[234:235], s[76:77], 0, v[136:137]
	s_mov_b32 m0, s28
	s_nop 0
	global_load_lds_dwordx4 v[234:235], off
	s_mov_b32 m0, s29
	s_nop 0
	global_load_lds_dwordx4 v[236:237], off
	s_waitcnt vmcnt(8)
	s_waitcnt lgkmcnt(0)
	s_barrier
; #define PG8_STAGE(bufoff, gbase, voff) do { _Pragma("unroll") for (int _i = 0; _i < 2; ++_i) \
;         __builtin_amdgcn_global_load_lds((const unsigned*)((const char*)(gbase) + (voff)[_i]), (PG8_LAS unsigned*)(lds + (bufoff) + ldsw + _i * 8192), 16, 0, 0); } while (0)
; #define PG8_LDA(dst, b, h) do { _Pragma("unroll") for (int m = 0; m < 4; ++m) _Pragma("unroll") for (int k = 0; k < 2; ++k) dst[m][k] = *(const PG8_LAS bf16x8*)(lds + PG8_SA(b, h) + aoff + m * 2048 + k * 1024); } while (0)
; #define PG8_LDB(dst, b, h) do { _Pragma("unroll") for (int n = 0; n < 2; ++n) _Pragma("unroll") for (int k = 0; k < 2; ++k) dst[n][k] = *(const PG8_LAS bf16x8*)(lds + PG8_SB(b, h) + boff + n * 2048 + k * 1024); } while (0)
; #define PG8_MMA(ai, bj, At, Bt) do { __builtin_amdgcn_s_setprio(1); _Pragma("unroll") for (int m = 0; m < 4; ++m) _Pragma("unroll") for (int n = 0; n < 2; ++n) _Pragma("unroll") for (int k = 0; k < 2; ++k) \
;         acc[ai][bj][m][n] = __builtin_amdgcn_mfma_f32_16x16x32_bf16(Bt[n][k], At[m][k], acc[ai][bj][m][n], 0, 0, 0); __builtin_amdgcn_s_setprio(0); } while (0)
; #define PG8_WAIT_V(n) asm volatile("s_waitcnt vmcnt(" #n ")" ::: "memory")
; #define PG8_WAIT_L(n) asm volatile("s_waitcnt lgkmcnt(" #n ")" ::: "memory")
; #define PG8_BAR __builtin_amdgcn_s_barrier()
; #define PG8_SCHED __builtin_amdgcn_sched_barrier(0)
; template <class Epi, class Sched, bool ALIGN_EPI = false, bool SP2 = false>
; __device__ __forceinline__ void gemm_phase(PG8_LAS unsigned char* lds, const Gemm g, const Sched& S, const Epi& E) {
;     ...
;             PG8_WAIT_V(8); PG8_WAIT_L(0); PG8_BAR; PG8_MMA(1, 0, At, B0); PG8_MMA(1, 1, At, B1); PG8_BAR; PG8_SCHED;
;             PG8_LDB(B0, 1, 0); PG8_LDB(B1, 1, 1); PG8_SCHED; PG8_LDA(At, 1, 0); PG8_STAGE(PG8_SA(0, 1), a2 + hstep, voffA);
;             PG8_WAIT_V(8); PG8_WAIT_L(0); PG8_BAR; PG8_MMA(0, 0, At, B0); PG8_MMA(0, 1, At, B1); PG8_BAR; PG8_SCHED;
	s_setprio 1
	s_waitcnt lgkmcnt(0)
	v_mfma_f32_16x16x32_bf16 v[60:63], v[166:169], v[198:201], v[60:63]
	v_mfma_f32_16x16x32_bf16 v[56:59], v[174:177], v[198:201], v[56:59]
	v_mfma_f32_16x16x32_bf16 v[52:55], v[166:169], v[206:209], v[52:55]
	v_mfma_f32_16x16x32_bf16 v[44:47], v[174:177], v[206:209], v[44:47]
	v_mfma_f32_16x16x32_bf16 v[36:39], v[166:169], v[214:217], v[36:39]
	v_mfma_f32_16x16x32_bf16 v[28:31], v[174:177], v[214:217], v[28:31]
	v_mfma_f32_16x16x32_bf16 v[20:23], v[166:169], v[222:225], v[20:23]
	v_mfma_f32_16x16x32_bf16 v[12:15], v[174:177], v[222:225], v[12:15]
	v_mfma_f32_16x16x32_bf16 v[60:63], v[170:173], v[202:205], v[60:63]
	v_mfma_f32_16x16x32_bf16 v[56:59], v[178:181], v[202:205], v[56:59]
	v_mfma_f32_16x16x32_bf16 v[52:55], v[170:173], v[210:213], v[52:55]
	v_mfma_f32_16x16x32_bf16 v[44:47], v[178:181], v[210:213], v[44:47]
	v_mfma_f32_16x16x32_bf16 v[36:39], v[170:173], v[218:221], v[36:39]
	v_mfma_f32_16x16x32_bf16 v[28:31], v[178:181], v[218:221], v[28:31]
	v_mfma_f32_16x16x32_bf16 v[20:23], v[170:173], v[226:229], v[20:23]
	v_mfma_f32_16x16x32_bf16 v[12:15], v[178:181], v[226:229], v[12:15]
	s_setprio 0
	s_setprio 1
	v_mfma_f32_16x16x32_bf16 v[48:51], v[182:185], v[198:201], v[48:51]
	v_mfma_f32_16x16x32_bf16 v[40:43], v[190:193], v[198:201], v[40:43]
	v_mfma_f32_16x16x32_bf16 v[32:35], v[182:185], v[206:209], v[32:35]
	v_mfma_f32_16x16x32_bf16 v[24:27], v[190:193], v[206:209], v[24:27]
	v_mfma_f32_16x16x32_bf16 v[16:19], v[182:185], v[214:217], v[16:19]
	v_mfma_f32_16x16x32_bf16 v[8:11], v[190:193], v[214:217], v[8:11]
	v_mfma_f32_16x16x32_bf16 v[4:7], v[182:185], v[222:225], v[4:7]
	v_mfma_f32_16x16x32_bf16 v[0:3], v[190:193], v[222:225], v[0:3]
	v_mfma_f32_16x16x32_bf16 v[48:51], v[186:189], v[202:205], v[48:51]
	v_mfma_f32_16x16x32_bf16 v[40:43], v[194:197], v[202:205], v[40:43]
	v_mfma_f32_16x16x32_bf16 v[32:35], v[186:189], v[210:213], v[32:35]
	v_mfma_f32_16x16x32_bf16 v[24:27], v[194:197], v[210:213], v[24:27]
	v_mfma_f32_16x16x32_bf16 v[16:19], v[186:189], v[218:221], v[16:19]
	s_setprio 2
	s_barrier
	v_mfma_f32_16x16x32_bf16 v[8:11], v[194:197], v[218:221], v[8:11]
	v_mfma_f32_16x16x32_bf16 v[4:7], v[186:189], v[226:229], v[4:7]
	v_mfma_f32_16x16x32_bf16 v[0:3], v[194:197], v[226:229], v[0:3]
	s_setprio 0
	ds_read_b128 v[166:169], v148
	ds_read_b128 v[170:173], v148 offset:1024
	ds_read_b128 v[174:177], v148 offset:2048
	ds_read_b128 v[178:181], v148 offset:3072
	ds_read_b128 v[182:185], v165
	ds_read_b128 v[186:189], v165 offset:1024
	ds_read_b128 v[190:193], v165 offset:2048
	ds_read_b128 v[194:197], v165 offset:3072
	s_add_u32 s52, s76, 0x200000
	s_addc_u32 s53, s77, 0
	s_mov_b32 m0, s33
	v_lshl_add_u64 v[238:239], s[52:53], 0, v[136:137]
	ds_read_b128 v[198:201], v164 offset:32768
	ds_read_b128 v[202:205], v164 offset:33792
	ds_read_b128 v[206:209], v164 offset:34816
	ds_read_b128 v[210:213], v164 offset:35840
	ds_read_b128 v[214:217], v164 offset:36864
	ds_read_b128 v[218:221], v164 offset:37888
	ds_read_b128 v[222:225], v164 offset:38912
	ds_read_b128 v[226:229], v164 offset:39936
	global_load_lds_dwordx4 v[238:239], off
	v_lshl_add_u64 v[238:239], s[52:53], 0, v[140:141]
	s_mov_b32 m0, s38
	s_nop 0
	global_load_lds_dwordx4 v[238:239], off
	s_waitcnt vmcnt(8)
	s_waitcnt lgkmcnt(0)
	s_barrier
	s_setprio 1
	s_waitcnt lgkmcnt(0)
	v_mfma_f32_16x16x32_bf16 v[124:127], v[166:169], v[198:201], v[124:127]
	v_mfma_f32_16x16x32_bf16 v[120:123], v[174:177], v[198:201], v[120:123]
	v_mfma_f32_16x16x32_bf16 v[116:119], v[166:169], v[206:209], v[116:119]
	v_mfma_f32_16x16x32_bf16 v[108:111], v[174:177], v[206:209], v[108:111]
	v_mfma_f32_16x16x32_bf16 v[100:103], v[166:169], v[214:217], v[100:103]
	v_mfma_f32_16x16x32_bf16 v[92:95], v[174:177], v[214:217], v[92:95]
	v_mfma_f32_16x16x32_bf16 v[84:87], v[166:169], v[222:225], v[84:87]
	v_mfma_f32_16x16x32_bf16 v[76:79], v[174:177], v[222:225], v[76:79]
	v_mfma_f32_16x16x32_bf16 v[124:127], v[170:173], v[202:205], v[124:127]
	v_mfma_f32_16x16x32_bf16 v[120:123], v[178:181], v[202:205], v[120:123]
	v_mfma_f32_16x16x32_bf16 v[116:119], v[170:173], v[210:213], v[116:119]
	v_mfma_f32_16x16x32_bf16 v[108:111], v[178:181], v[210:213], v[108:111]
	v_mfma_f32_16x16x32_bf16 v[100:103], v[170:173], v[218:221], v[100:103]
	v_mfma_f32_16x16x32_bf16 v[92:95], v[178:181], v[218:221], v[92:95]
	v_mfma_f32_16x16x32_bf16 v[84:87], v[170:173], v[226:229], v[84:87]
	v_mfma_f32_16x16x32_bf16 v[76:79], v[178:181], v[226:229], v[76:79]
	s_setprio 0
	s_setprio 1
	v_mfma_f32_16x16x32_bf16 v[112:115], v[182:185], v[198:201], v[112:115]
	v_mfma_f32_16x16x32_bf16 v[104:107], v[190:193], v[198:201], v[104:107]
	v_mfma_f32_16x16x32_bf16 v[96:99], v[182:185], v[206:209], v[96:99]
	v_mfma_f32_16x16x32_bf16 v[88:91], v[190:193], v[206:209], v[88:91]
	v_mfma_f32_16x16x32_bf16 v[80:83], v[182:185], v[214:217], v[80:83]
	v_mfma_f32_16x16x32_bf16 v[72:75], v[190:193], v[214:217], v[72:75]
	v_mfma_f32_16x16x32_bf16 v[68:71], v[182:185], v[222:225], v[68:71]
	v_mfma_f32_16x16x32_bf16 v[64:67], v[190:193], v[222:225], v[64:67]
	v_mfma_f32_16x16x32_bf16 v[112:115], v[186:189], v[202:205], v[112:115]
	v_mfma_f32_16x16x32_bf16 v[104:107], v[194:197], v[202:205], v[104:107]
	v_mfma_f32_16x16x32_bf16 v[96:99], v[186:189], v[210:213], v[96:99]
	v_mfma_f32_16x16x32_bf16 v[88:91], v[194:197], v[210:213], v[88:91]
	v_mfma_f32_16x16x32_bf16 v[80:83], v[186:189], v[218:221], v[80:83]
	s_setprio 2
	s_barrier
; #define PG8_STAGE(bufoff, gbase, voff) do { _Pragma("unroll") for (int _i = 0; _i < 2; ++_i) \
;         __builtin_amdgcn_global_load_lds((const unsigned*)((const char*)(gbase) + (voff)[_i]), (PG8_LAS unsigned*)(lds + (bufoff) + ldsw + _i * 8192), 16, 0, 0); } while (0)
; #define PG8_LDA(dst, b, h) do { _Pragma("unroll") for (int m = 0; m < 4; ++m) _Pragma("unroll") for (int k = 0; k < 2; ++k) dst[m][k] = *(const PG8_LAS bf16x8*)(lds + PG8_SA(b, h) + aoff + m * 2048 + k * 1024); } while (0)
; #define PG8_MMA(ai, bj, At, Bt) do { __builtin_amdgcn_s_setprio(1); _Pragma("unroll") for (int m = 0; m < 4; ++m) _Pragma("unroll") for (int n = 0; n < 2; ++n) _Pragma("unroll") for (int k = 0; k < 2; ++k) \
;         acc[ai][bj][m][n] = __builtin_amdgcn_mfma_f32_16x16x32_bf16(Bt[n][k], At[m][k], acc[ai][bj][m][n], 0, 0, 0); __builtin_amdgcn_s_setprio(0); } while (0)
; #define PG8_WAIT_V(n) asm volatile("s_waitcnt vmcnt(" #n ")" ::: "memory")
; #define PG8_WAIT_L(n) asm volatile("s_waitcnt lgkmcnt(" #n ")" ::: "memory")
; #define PG8_BAR __builtin_amdgcn_s_barrier()
; #define PG8_SCHED __builtin_amdgcn_sched_barrier(0)
; template <class Epi, class Sched, bool ALIGN_EPI = false, bool SP2 = false>
; __device__ __forceinline__ void gemm_phase(PG8_LAS unsigned char* lds, const Gemm g, const Sched& S, const Epi& E) {
;     ...
;             PG8_WAIT_V(8); PG8_WAIT_L(0); PG8_BAR; PG8_MMA(0, 0, At, B0); PG8_MMA(0, 1, At, B1); PG8_BAR; PG8_SCHED;
;             PG8_LDA(At, 1, 1); PG8_STAGE(PG8_SB(1, 0), b3, voffB); PG8_STAGE(PG8_SB(1, 1), b3 + hstep, voffB); PG8_STAGE(PG8_SA(1, 0), a3, voffA);
;             PG8_WAIT_V(8); PG8_WAIT_L(0); PG8_BAR; PG8_MMA(1, 0, At, B0); PG8_MMA(1, 1, At, B1); PG8_BAR; PG8_SCHED;
;     ...
;         if constexpr (ALIGN_EPI) { if (wr == 0) PG8_BAR; }
	v_mfma_f32_16x16x32_bf16 v[72:75], v[194:197], v[218:221], v[72:75]
	v_mfma_f32_16x16x32_bf16 v[68:71], v[186:189], v[226:229], v[68:71]
	v_mfma_f32_16x16x32_bf16 v[64:67], v[194:197], v[226:229], v[64:67]
	s_setprio 0
	s_mov_b32 m0, s89
	v_lshl_add_u64 v[230:231], v[230:231], 0, s[12:13]
	ds_read_b128 v[198:201], v164 offset:49152
	ds_read_b128 v[202:205], v164 offset:50176
	ds_read_b128 v[206:209], v164 offset:51200
	ds_read_b128 v[210:213], v164 offset:52224
	ds_read_b128 v[214:217], v164 offset:53248
	ds_read_b128 v[218:221], v164 offset:54272
	ds_read_b128 v[222:225], v164 offset:55296
	ds_read_b128 v[226:229], v164 offset:56320
	global_load_lds_dwordx4 v[230:231], off
	s_add_i32 m0, s89, 0x2000
	s_add_u32 s52, s74, 0x200080
	v_lshl_add_u64 v[230:231], v[232:233], 0, s[12:13]
	s_addc_u32 s53, s75, 0
	s_add_i32 s56, s88, s3
	global_load_lds_dwordx4 v[230:231], off
	v_lshl_add_u64 v[230:231], s[52:53], 0, v[138:139]
	s_mov_b32 m0, s56
	s_nop 0
	global_load_lds_dwordx4 v[230:231], off
	v_lshl_add_u64 v[230:231], s[52:53], 0, v[142:143]
	s_add_i32 m0, s56, 0x2000
	s_nop 0
	global_load_lds_dwordx4 v[230:231], off
	v_lshl_add_u64 v[230:231], v[234:235], 0, s[12:13]
	s_mov_b32 m0, s71
	s_nop 0
	global_load_lds_dwordx4 v[230:231], off
	v_lshl_add_u64 v[230:231], v[236:237], 0, s[12:13]
	s_mov_b32 m0, s78
	s_nop 0
	global_load_lds_dwordx4 v[230:231], off
	s_waitcnt vmcnt(8)
	s_waitcnt lgkmcnt(0)
	s_barrier
	s_setprio 1
	s_waitcnt lgkmcnt(0)
	v_mfma_f32_16x16x32_bf16 v[60:63], v[166:169], v[198:201], v[60:63]
	v_mfma_f32_16x16x32_bf16 v[56:59], v[174:177], v[198:201], v[56:59]
	v_mfma_f32_16x16x32_bf16 v[52:55], v[166:169], v[206:209], v[52:55]
	v_mfma_f32_16x16x32_bf16 v[44:47], v[174:177], v[206:209], v[44:47]
	v_mfma_f32_16x16x32_bf16 v[36:39], v[166:169], v[214:217], v[36:39]
	v_mfma_f32_16x16x32_bf16 v[28:31], v[174:177], v[214:217], v[28:31]
	v_mfma_f32_16x16x32_bf16 v[20:23], v[166:169], v[222:225], v[20:23]
	v_mfma_f32_16x16x32_bf16 v[12:15], v[174:177], v[222:225], v[12:15]
	v_mfma_f32_16x16x32_bf16 v[60:63], v[170:173], v[202:205], v[60:63]
	v_mfma_f32_16x16x32_bf16 v[56:59], v[178:181], v[202:205], v[56:59]
	v_mfma_f32_16x16x32_bf16 v[52:55], v[170:173], v[210:213], v[52:55]
	v_mfma_f32_16x16x32_bf16 v[44:47], v[178:181], v[210:213], v[44:47]
	v_mfma_f32_16x16x32_bf16 v[36:39], v[170:173], v[218:221], v[36:39]
	v_mfma_f32_16x16x32_bf16 v[28:31], v[178:181], v[218:221], v[28:31]
	v_mfma_f32_16x16x32_bf16 v[20:23], v[170:173], v[226:229], v[20:23]
	v_mfma_f32_16x16x32_bf16 v[12:15], v[178:181], v[226:229], v[12:15]
	s_setprio 0
	s_setprio 1
	v_mfma_f32_16x16x32_bf16 v[48:51], v[182:185], v[198:201], v[48:51]
	v_mfma_f32_16x16x32_bf16 v[40:43], v[190:193], v[198:201], v[40:43]
	v_mfma_f32_16x16x32_bf16 v[32:35], v[182:185], v[206:209], v[32:35]
	v_mfma_f32_16x16x32_bf16 v[24:27], v[190:193], v[206:209], v[24:27]
	v_mfma_f32_16x16x32_bf16 v[16:19], v[182:185], v[214:217], v[16:19]
	v_mfma_f32_16x16x32_bf16 v[8:11], v[190:193], v[214:217], v[8:11]
	v_mfma_f32_16x16x32_bf16 v[4:7], v[182:185], v[222:225], v[4:7]
	v_mfma_f32_16x16x32_bf16 v[0:3], v[190:193], v[222:225], v[0:3]
	v_mfma_f32_16x16x32_bf16 v[48:51], v[186:189], v[202:205], v[48:51]
	v_mfma_f32_16x16x32_bf16 v[40:43], v[194:197], v[202:205], v[40:43]
	v_mfma_f32_16x16x32_bf16 v[32:35], v[186:189], v[210:213], v[32:35]
	v_mfma_f32_16x16x32_bf16 v[24:27], v[194:197], v[210:213], v[24:27]
	v_mfma_f32_16x16x32_bf16 v[16:19], v[186:189], v[218:221], v[16:19]
	s_setprio 2
	s_barrier
	v_mfma_f32_16x16x32_bf16 v[8:11], v[194:197], v[218:221], v[8:11]
	v_mfma_f32_16x16x32_bf16 v[4:7], v[186:189], v[226:229], v[4:7]
	v_mfma_f32_16x16x32_bf16 v[0:3], v[194:197], v[226:229], v[0:3]
	s_setprio 0
	s_add_i32 s49, s49, 2
	s_add_u32 s72, s72, 0x100
	s_addc_u32 s73, s73, 0
	s_add_u32 s37, s37, 0x100
	s_addc_u32 s41, s41, 0
	s_cmp_gt_u32 s49, 29
	s_cbranch_scc0 .LBB0_660
	s_and_b64 vcc, exec, s[14:15]
	s_cbranch_vccz .LBB0_663
	s_barrier

; #define PG8_STAGE(bufoff, gbase, voff) do { _Pragma("unroll") for (int _i = 0; _i < 2; ++_i) \
;         __builtin_amdgcn_global_load_lds((const unsigned*)((const char*)(gbase) + (voff)[_i]), (PG8_LAS unsigned*)(lds + (bufoff) + ldsw + _i * 8192), 16, 0, 0); } while (0)
; #define PG8_LDA(dst, b, h) do { _Pragma("unroll") for (int m = 0; m < 4; ++m) _Pragma("unroll") for (int k = 0; k < 2; ++k) dst[m][k] = *(const PG8_LAS bf16x8*)(lds + PG8_SA(b, h) + aoff + m * 2048 + k * 1024); } while (0)
; #define PG8_LDB(dst, b, h) do { _Pragma("unroll") for (int n = 0; n < 2; ++n) _Pragma("unroll") for (int k = 0; k < 2; ++k) dst[n][k] = *(const PG8_LAS bf16x8*)(lds + PG8_SB(b, h) + boff + n * 2048 + k * 1024); } while (0)
; #define PG8_MMA(ai, bj, At, Bt) do { __builtin_amdgcn_s_setprio(1); _Pragma("unroll") for (int m = 0; m < 4; ++m) _Pragma("unroll") for (int n = 0; n < 2; ++n) _Pragma("unroll") for (int k = 0; k < 2; ++k) \
;         acc[ai][bj][m][n] = __builtin_amdgcn_mfma_f32_16x16x32_bf16(Bt[n][k], At[m][k], acc[ai][bj][m][n], 0, 0, 0); __builtin_amdgcn_s_setprio(0); } while (0)
; #define PG8_WAIT_V(n) asm volatile("s_waitcnt vmcnt(" #n ")" ::: "memory")
; #define PG8_WAIT_L(n) asm volatile("s_waitcnt lgkmcnt(" #n ")" ::: "memory")
; #define PG8_BAR __builtin_amdgcn_s_barrier()
; template <class Epi, class Sched, bool ALIGN_EPI = false, bool SP2 = false>
; __device__ __forceinline__ void gemm_phase(PG8_LAS unsigned char* lds, const Gemm g, const Sched& S, const Epi& E) {
;     ...
;             const bool last = (t == nt - 2);
;             const char* a1 = cA + (size_t)(t + 1) * kstep;
;             const char* a2 = last ? nA : cA + (size_t)(t + 2) * kstep; const char* b2 = last ? nB : cB + (size_t)(t + 2) * kstep;
;             const char* a3 = a2 + kstep; const char* b3 = b2 + kstep;
;             if constexpr (SP2) {
;             PG8_LDB(B0, 0, 0); PG8_LDB(B1, 0, 1); PG8_SCHED; PG8_LDA(At, 0, 0); PG8_STAGE(PG8_SA(1, 1), a1 + hstep, voffA);
;             PG8_WAIT_V(8); PG8_WAIT_L(0); PG8_BAR; PG8_MMA(0, 0, At, B0); PG8_MMA(0, 1, At, B1); PG8_BAR; PG8_SCHED;
;             PG8_LDA(At, 0, 1); PG8_STAGE(PG8_SB(0, 0), b2, voffB); PG8_STAGE(PG8_SB(0, 1), b2 + hstep, voffB); PG8_STAGE(PG8_SA(0, 0), a2, voffA);
;             PG8_WAIT_V(8); PG8_WAIT_L(0); PG8_BAR; PG8_MMA(1, 0, At, B0); PG8_MMA(1, 1, At, B1); PG8_BAR; PG8_SCHED;
.LBB0_809:
	ds_read_b128 v[128:131], v180
	ds_read_b128 v[132:135], v180 offset:1024
	ds_read_b128 v[136:139], v180 offset:2048
	ds_read_b128 v[140:143], v180 offset:3072
	ds_read_b128 v[160:163], v181
	ds_read_b128 v[164:167], v181 offset:1024
	ds_read_b128 v[184:187], v181 offset:2048
	ds_read_b128 v[188:191], v181 offset:3072
	s_add_u32 s52, s72, 0xfff80080
	s_addc_u32 s53, s73, -1
	s_cmp_eq_u32 s92, 28
	s_cselect_b32 s77, s5, s53
	s_cselect_b32 s76, s49, s52
	s_cselect_b32 s75, s45, s91
	s_cselect_b32 s74, s89, s90
	v_lshl_add_u64 v[168:169], s[72:73], 0, v[154:155]
	s_add_i32 m0, s71, 0xc000
	ds_read_b128 v[192:195], v182
	ds_read_b128 v[196:199], v182 offset:1024
	ds_read_b128 v[200:203], v182 offset:2048
	ds_read_b128 v[204:207], v182 offset:3072
	ds_read_b128 v[208:211], v182 offset:4096
	ds_read_b128 v[212:215], v182 offset:5120
	ds_read_b128 v[216:219], v182 offset:6144
	ds_read_b128 v[220:223], v182 offset:7168
	global_load_lds_dwordx4 v[168:169], off
	v_lshl_add_u64 v[168:169], s[72:73], 0, v[156:157]
	s_add_i32 m0, s71, 0xe000
	s_nop 0
	global_load_lds_dwordx4 v[168:169], off
	s_waitcnt vmcnt(8)
	s_waitcnt lgkmcnt(0)
	s_barrier
	s_setprio 1
	s_waitcnt lgkmcnt(0)
	v_mfma_f32_16x16x32_bf16 v[124:127], v[128:131], v[192:195], v[124:127]
	v_mfma_f32_16x16x32_bf16 v[120:123], v[136:139], v[192:195], v[120:123]
	v_mfma_f32_16x16x32_bf16 v[108:111], v[128:131], v[200:203], v[108:111]
	v_mfma_f32_16x16x32_bf16 v[104:107], v[136:139], v[200:203], v[104:107]
	v_mfma_f32_16x16x32_bf16 v[92:95], v[128:131], v[208:211], v[92:95]
	v_mfma_f32_16x16x32_bf16 v[88:91], v[136:139], v[208:211], v[88:91]
	v_mfma_f32_16x16x32_bf16 v[76:79], v[128:131], v[216:219], v[76:79]
	v_mfma_f32_16x16x32_bf16 v[72:75], v[136:139], v[216:219], v[72:75]
	v_mfma_f32_16x16x32_bf16 v[124:127], v[132:135], v[196:199], v[124:127]
	v_mfma_f32_16x16x32_bf16 v[120:123], v[140:143], v[196:199], v[120:123]
	v_mfma_f32_16x16x32_bf16 v[108:111], v[132:135], v[204:207], v[108:111]
	v_mfma_f32_16x16x32_bf16 v[104:107], v[140:143], v[204:207], v[104:107]
	v_mfma_f32_16x16x32_bf16 v[92:95], v[132:135], v[212:215], v[92:95]
	v_mfma_f32_16x16x32_bf16 v[88:91], v[140:143], v[212:215], v[88:91]
	v_mfma_f32_16x16x32_bf16 v[76:79], v[132:135], v[220:223], v[76:79]
	v_mfma_f32_16x16x32_bf16 v[72:75], v[140:143], v[220:223], v[72:75]
	s_setprio 0
	s_setprio 1
	v_mfma_f32_16x16x32_bf16 v[116:119], v[160:163], v[192:195], v[116:119]
	v_mfma_f32_16x16x32_bf16 v[112:115], v[184:187], v[192:195], v[112:115]
	v_mfma_f32_16x16x32_bf16 v[100:103], v[160:163], v[200:203], v[100:103]
	v_mfma_f32_16x16x32_bf16 v[96:99], v[184:187], v[200:203], v[96:99]
	v_mfma_f32_16x16x32_bf16 v[84:87], v[160:163], v[208:211], v[84:87]
	v_mfma_f32_16x16x32_bf16 v[80:83], v[184:187], v[208:211], v[80:83]
	v_mfma_f32_16x16x32_bf16 v[68:71], v[160:163], v[216:219], v[68:71]
	v_mfma_f32_16x16x32_bf16 v[64:67], v[184:187], v[216:219], v[64:67]
	v_mfma_f32_16x16x32_bf16 v[116:119], v[164:167], v[196:199], v[116:119]
	v_mfma_f32_16x16x32_bf16 v[112:115], v[188:191], v[196:199], v[112:115]
	v_mfma_f32_16x16x32_bf16 v[100:103], v[164:167], v[204:207], v[100:103]
	v_mfma_f32_16x16x32_bf16 v[96:99], v[188:191], v[204:207], v[96:99]
	v_mfma_f32_16x16x32_bf16 v[84:87], v[164:167], v[212:215], v[84:87]
	s_setprio 2
	s_barrier
	v_mfma_f32_16x16x32_bf16 v[80:83], v[188:191], v[212:215], v[80:83]
	v_mfma_f32_16x16x32_bf16 v[68:71], v[164:167], v[220:223], v[68:71]
	v_mfma_f32_16x16x32_bf16 v[64:67], v[188:191], v[220:223], v[64:67]
	s_setprio 0
	s_add_i32 s52, s83, s78
	v_lshl_add_u64 v[168:169], s[74:75], 0, v[148:149]
	s_mov_b32 m0, s52
	ds_read_b128 v[192:195], v182 offset:16384
	ds_read_b128 v[196:199], v182 offset:17408
	ds_read_b128 v[200:203], v182 offset:18432
	ds_read_b128 v[204:207], v182 offset:19456
	ds_read_b128 v[208:211], v182 offset:20480
	ds_read_b128 v[212:215], v182 offset:21504
	ds_read_b128 v[216:219], v182 offset:22528
	ds_read_b128 v[220:223], v182 offset:23552
	global_load_lds_dwordx4 v[168:169], off
	s_add_i32 m0, s52, 0x2000
	s_add_u32 s52, s74, 0x80000
	v_lshl_add_u64 v[224:225], s[74:75], 0, v[152:153]
	s_addc_u32 s53, s75, 0
	s_add_i32 s56, s84, s78
	global_load_lds_dwordx4 v[224:225], off
	v_lshl_add_u64 v[226:227], s[52:53], 0, v[148:149]
	s_mov_b32 m0, s56
	v_lshl_add_u64 v[228:229], s[76:77], 0, v[150:151]
	global_load_lds_dwordx4 v[226:227], off
	v_lshl_add_u64 v[226:227], s[52:53], 0, v[152:153]
	s_add_i32 m0, s56, 0x2000
	s_nop 0
	global_load_lds_dwordx4 v[226:227], off
	v_lshl_add_u64 v[226:227], s[76:77], 0, v[144:145]
	s_mov_b32 m0, s71
	s_nop 0
	global_load_lds_dwordx4 v[226:227], off
	s_mov_b32 m0, s79
	s_nop 0
	global_load_lds_dwordx4 v[228:229], off
	s_waitcnt vmcnt(8)
	s_waitcnt lgkmcnt(0)
	s_barrier
; #define PG8_STAGE(bufoff, gbase, voff) do { _Pragma("unroll") for (int _i = 0; _i < 2; ++_i) \
;         __builtin_amdgcn_global_load_lds((const unsigned*)((const char*)(gbase) + (voff)[_i]), (PG8_LAS unsigned*)(lds + (bufoff) + ldsw + _i * 8192), 16, 0, 0); } while (0)
; #define PG8_LDA(dst, b, h) do { _Pragma("unroll") for (int m = 0; m < 4; ++m) _Pragma("unroll") for (int k = 0; k < 2; ++k) dst[m][k] = *(const PG8_LAS bf16x8*)(lds + PG8_SA(b, h) + aoff + m * 2048 + k * 1024); } while (0)
; #define PG8_LDB(dst, b, h) do { _Pragma("unroll") for (int n = 0; n < 2; ++n) _Pragma("unroll") for (int k = 0; k < 2; ++k) dst[n][k] = *(const PG8_LAS bf16x8*)(lds + PG8_SB(b, h) + boff + n * 2048 + k * 1024); } while (0)
; #define PG8_MMA(ai, bj, At, Bt) do { __builtin_amdgcn_s_setprio(1); _Pragma("unroll") for (int m = 0; m < 4; ++m) _Pragma("unroll") for (int n = 0; n < 2; ++n) _Pragma("unroll") for (int k = 0; k < 2; ++k) \
;         acc[ai][bj][m][n] = __builtin_amdgcn_mfma_f32_16x16x32_bf16(Bt[n][k], At[m][k], acc[ai][bj][m][n], 0, 0, 0); __builtin_amdgcn_s_setprio(0); } while (0)
; #define PG8_WAIT_V(n) asm volatile("s_waitcnt vmcnt(" #n ")" ::: "memory")
; #define PG8_WAIT_L(n) asm volatile("s_waitcnt lgkmcnt(" #n ")" ::: "memory")
; #define PG8_BAR __builtin_amdgcn_s_barrier()
; #define PG8_SCHED __builtin_amdgcn_sched_barrier(0)
; template <class Epi, class Sched, bool ALIGN_EPI = false, bool SP2 = false>
; __device__ __forceinline__ void gemm_phase(PG8_LAS unsigned char* lds, const Gemm g, const Sched& S, const Epi& E) {
;     ...
;             PG8_WAIT_V(8); PG8_WAIT_L(0); PG8_BAR; PG8_MMA(1, 0, At, B0); PG8_MMA(1, 1, At, B1); PG8_BAR; PG8_SCHED;
;             PG8_LDB(B0, 1, 0); PG8_LDB(B1, 1, 1); PG8_SCHED; PG8_LDA(At, 1, 0); PG8_STAGE(PG8_SA(0, 1), a2 + hstep, voffA);
;             PG8_WAIT_V(8); PG8_WAIT_L(0); PG8_BAR; PG8_MMA(0, 0, At, B0); PG8_MMA(0, 1, At, B1); PG8_BAR; PG8_SCHED;
	s_setprio 1
	s_waitcnt lgkmcnt(0)
	v_mfma_f32_16x16x32_bf16 v[60:63], v[128:131], v[192:195], v[60:63]
	v_mfma_f32_16x16x32_bf16 v[56:59], v[136:139], v[192:195], v[56:59]
	v_mfma_f32_16x16x32_bf16 v[44:47], v[128:131], v[200:203], v[44:47]
	v_mfma_f32_16x16x32_bf16 v[40:43], v[136:139], v[200:203], v[40:43]
	v_mfma_f32_16x16x32_bf16 v[28:31], v[128:131], v[208:211], v[28:31]
	v_mfma_f32_16x16x32_bf16 v[24:27], v[136:139], v[208:211], v[24:27]
	v_mfma_f32_16x16x32_bf16 v[12:15], v[128:131], v[216:219], v[12:15]
	v_mfma_f32_16x16x32_bf16 v[8:11], v[136:139], v[216:219], v[8:11]
	v_mfma_f32_16x16x32_bf16 v[60:63], v[132:135], v[196:199], v[60:63]
	v_mfma_f32_16x16x32_bf16 v[56:59], v[140:143], v[196:199], v[56:59]
	v_mfma_f32_16x16x32_bf16 v[44:47], v[132:135], v[204:207], v[44:47]
	v_mfma_f32_16x16x32_bf16 v[40:43], v[140:143], v[204:207], v[40:43]
	v_mfma_f32_16x16x32_bf16 v[28:31], v[132:135], v[212:215], v[28:31]
	v_mfma_f32_16x16x32_bf16 v[24:27], v[140:143], v[212:215], v[24:27]
	v_mfma_f32_16x16x32_bf16 v[12:15], v[132:135], v[220:223], v[12:15]
	v_mfma_f32_16x16x32_bf16 v[8:11], v[140:143], v[220:223], v[8:11]
	s_setprio 0
	s_setprio 1
	v_mfma_f32_16x16x32_bf16 v[52:55], v[160:163], v[192:195], v[52:55]
	v_mfma_f32_16x16x32_bf16 v[48:51], v[184:187], v[192:195], v[48:51]
	v_mfma_f32_16x16x32_bf16 v[36:39], v[160:163], v[200:203], v[36:39]
	v_mfma_f32_16x16x32_bf16 v[32:35], v[184:187], v[200:203], v[32:35]
	v_mfma_f32_16x16x32_bf16 v[20:23], v[160:163], v[208:211], v[20:23]
	v_mfma_f32_16x16x32_bf16 v[16:19], v[184:187], v[208:211], v[16:19]
	v_mfma_f32_16x16x32_bf16 v[4:7], v[160:163], v[216:219], v[4:7]
	v_mfma_f32_16x16x32_bf16 v[0:3], v[184:187], v[216:219], v[0:3]
	v_mfma_f32_16x16x32_bf16 v[52:55], v[164:167], v[196:199], v[52:55]
	v_mfma_f32_16x16x32_bf16 v[48:51], v[188:191], v[196:199], v[48:51]
	v_mfma_f32_16x16x32_bf16 v[36:39], v[164:167], v[204:207], v[36:39]
	v_mfma_f32_16x16x32_bf16 v[32:35], v[188:191], v[204:207], v[32:35]
	v_mfma_f32_16x16x32_bf16 v[20:23], v[164:167], v[212:215], v[20:23]
	s_setprio 2
	s_barrier
	v_mfma_f32_16x16x32_bf16 v[16:19], v[188:191], v[212:215], v[16:19]
	v_mfma_f32_16x16x32_bf16 v[4:7], v[164:167], v[220:223], v[4:7]
	v_mfma_f32_16x16x32_bf16 v[0:3], v[188:191], v[220:223], v[0:3]
	s_setprio 0
	s_add_i32 s56, 0, 0x18000
	s_add_i32 s57, 0, 0x1c000
	v_add_u32_e32 v140, s56, v171
	v_add_u32_e32 v188, s57, v171
	ds_read_b128 v[128:131], v140
	ds_read_b128 v[132:135], v140 offset:1024
	ds_read_b128 v[136:139], v140 offset:2048
	ds_read_b128 v[140:143], v140 offset:3072
	ds_read_b128 v[160:163], v188
	ds_read_b128 v[164:167], v188 offset:1024
	ds_read_b128 v[184:187], v188 offset:2048
	ds_read_b128 v[188:191], v188 offset:3072
	s_add_u32 s52, s76, 0x80000
	s_addc_u32 s53, s77, 0
	s_mov_b32 m0, s80
	v_lshl_add_u64 v[230:231], s[52:53], 0, v[144:145]
	ds_read_b128 v[192:195], v182 offset:32768
	ds_read_b128 v[196:199], v182 offset:33792
	ds_read_b128 v[200:203], v182 offset:34816
	ds_read_b128 v[204:207], v182 offset:35840
	ds_read_b128 v[208:211], v182 offset:36864
	ds_read_b128 v[212:215], v182 offset:37888
	ds_read_b128 v[216:219], v182 offset:38912
	ds_read_b128 v[220:223], v182 offset:39936
	global_load_lds_dwordx4 v[230:231], off
	v_lshl_add_u64 v[230:231], s[52:53], 0, v[150:151]
	s_mov_b32 m0, s81
	s_nop 0
	global_load_lds_dwordx4 v[230:231], off
	s_waitcnt vmcnt(8)
	s_waitcnt lgkmcnt(0)
	s_barrier
	s_setprio 1
	s_waitcnt lgkmcnt(0)
	v_mfma_f32_16x16x32_bf16 v[124:127], v[128:131], v[192:195], v[124:127]
	v_mfma_f32_16x16x32_bf16 v[120:123], v[136:139], v[192:195], v[120:123]
	v_mfma_f32_16x16x32_bf16 v[108:111], v[128:131], v[200:203], v[108:111]
	v_mfma_f32_16x16x32_bf16 v[104:107], v[136:139], v[200:203], v[104:107]
	v_mfma_f32_16x16x32_bf16 v[92:95], v[128:131], v[208:211], v[92:95]
	v_mfma_f32_16x16x32_bf16 v[88:91], v[136:139], v[208:211], v[88:91]
	v_mfma_f32_16x16x32_bf16 v[76:79], v[128:131], v[216:219], v[76:79]
	v_mfma_f32_16x16x32_bf16 v[72:75], v[136:139], v[216:219], v[72:75]
	v_mfma_f32_16x16x32_bf16 v[124:127], v[132:135], v[196:199], v[124:127]
	v_mfma_f32_16x16x32_bf16 v[120:123], v[140:143], v[196:199], v[120:123]
	v_mfma_f32_16x16x32_bf16 v[108:111], v[132:135], v[204:207], v[108:111]
	v_mfma_f32_16x16x32_bf16 v[104:107], v[140:143], v[204:207], v[104:107]
	v_mfma_f32_16x16x32_bf16 v[92:95], v[132:135], v[212:215], v[92:95]
	v_mfma_f32_16x16x32_bf16 v[88:91], v[140:143], v[212:215], v[88:91]
	v_mfma_f32_16x16x32_bf16 v[76:79], v[132:135], v[220:223], v[76:79]
	v_mfma_f32_16x16x32_bf16 v[72:75], v[140:143], v[220:223], v[72:75]
	s_setprio 0
	s_setprio 1
	v_mfma_f32_16x16x32_bf16 v[116:119], v[160:163], v[192:195], v[116:119]
	v_mfma_f32_16x16x32_bf16 v[112:115], v[184:187], v[192:195], v[112:115]
	v_mfma_f32_16x16x32_bf16 v[100:103], v[160:163], v[200:203], v[100:103]
	v_mfma_f32_16x16x32_bf16 v[96:99], v[184:187], v[200:203], v[96:99]
	v_mfma_f32_16x16x32_bf16 v[84:87], v[160:163], v[208:211], v[84:87]
	v_mfma_f32_16x16x32_bf16 v[80:83], v[184:187], v[208:211], v[80:83]
	v_mfma_f32_16x16x32_bf16 v[68:71], v[160:163], v[216:219], v[68:71]
	v_mfma_f32_16x16x32_bf16 v[64:67], v[184:187], v[216:219], v[64:67]
	v_mfma_f32_16x16x32_bf16 v[116:119], v[164:167], v[196:199], v[116:119]
	v_mfma_f32_16x16x32_bf16 v[112:115], v[188:191], v[196:199], v[112:115]
	v_mfma_f32_16x16x32_bf16 v[100:103], v[164:167], v[204:207], v[100:103]
	v_mfma_f32_16x16x32_bf16 v[96:99], v[188:191], v[204:207], v[96:99]
	v_mfma_f32_16x16x32_bf16 v[84:87], v[164:167], v[212:215], v[84:87]
	s_setprio 2
	s_barrier
; #define PG8_STAGE(bufoff, gbase, voff) do { _Pragma("unroll") for (int _i = 0; _i < 2; ++_i) \
;         __builtin_amdgcn_global_load_lds((const unsigned*)((const char*)(gbase) + (voff)[_i]), (PG8_LAS unsigned*)(lds + (bufoff) + ldsw + _i * 8192), 16, 0, 0); } while (0)
; #define PG8_LDA(dst, b, h) do { _Pragma("unroll") for (int m = 0; m < 4; ++m) _Pragma("unroll") for (int k = 0; k < 2; ++k) dst[m][k] = *(const PG8_LAS bf16x8*)(lds + PG8_SA(b, h) + aoff + m * 2048 + k * 1024); } while (0)
; #define PG8_MMA(ai, bj, At, Bt) do { __builtin_amdgcn_s_setprio(1); _Pragma("unroll") for (int m = 0; m < 4; ++m) _Pragma("unroll") for (int n = 0; n < 2; ++n) _Pragma("unroll") for (int k = 0; k < 2; ++k) \
;         acc[ai][bj][m][n] = __builtin_amdgcn_mfma_f32_16x16x32_bf16(Bt[n][k], At[m][k], acc[ai][bj][m][n], 0, 0, 0); __builtin_amdgcn_s_setprio(0); } while (0)
; #define PG8_WAIT_V(n) asm volatile("s_waitcnt vmcnt(" #n ")" ::: "memory")
; #define PG8_WAIT_L(n) asm volatile("s_waitcnt lgkmcnt(" #n ")" ::: "memory")
; #define PG8_BAR __builtin_amdgcn_s_barrier()
; #define PG8_SCHED __builtin_amdgcn_sched_barrier(0)
; template <class Epi, class Sched, bool ALIGN_EPI = false, bool SP2 = false>
; __device__ __forceinline__ void gemm_phase(PG8_LAS unsigned char* lds, const Gemm g, const Sched& S, const Epi& E) {
;     ...
;             PG8_WAIT_V(8); PG8_WAIT_L(0); PG8_BAR; PG8_MMA(0, 0, At, B0); PG8_MMA(0, 1, At, B1); PG8_BAR; PG8_SCHED;
;             PG8_LDA(At, 1, 1); PG8_STAGE(PG8_SB(1, 0), b3, voffB); PG8_STAGE(PG8_SB(1, 1), b3 + hstep, voffB); PG8_STAGE(PG8_SA(1, 0), a3, voffA);
;             PG8_WAIT_V(8); PG8_WAIT_L(0); PG8_BAR; PG8_MMA(1, 0, At, B0); PG8_MMA(1, 1, At, B1); PG8_BAR; PG8_SCHED;
;     ...
;         if constexpr (ALIGN_EPI) { if (wr == 0) PG8_BAR; }
	v_mfma_f32_16x16x32_bf16 v[80:83], v[188:191], v[212:215], v[80:83]
	v_mfma_f32_16x16x32_bf16 v[68:71], v[164:167], v[220:223], v[68:71]
	v_mfma_f32_16x16x32_bf16 v[64:67], v[188:191], v[220:223], v[64:67]
	s_setprio 0
	s_add_i32 s52, s56, s78
	v_lshl_add_u64 v[168:169], v[168:169], 0, s[40:41]
	s_mov_b32 m0, s52
	ds_read_b128 v[192:195], v182 offset:49152
	ds_read_b128 v[196:199], v182 offset:50176
	ds_read_b128 v[200:203], v182 offset:51200
	ds_read_b128 v[204:207], v182 offset:52224
	ds_read_b128 v[208:211], v182 offset:53248
	ds_read_b128 v[212:215], v182 offset:54272
	ds_read_b128 v[216:219], v182 offset:55296
	ds_read_b128 v[220:223], v182 offset:56320
	global_load_lds_dwordx4 v[168:169], off
	s_add_i32 m0, s52, 0x2000
	s_add_u32 s52, s74, 0x80080
	v_lshl_add_u64 v[168:169], v[224:225], 0, s[40:41]
	s_addc_u32 s53, s75, 0
	s_add_i32 s56, s57, s78
	global_load_lds_dwordx4 v[168:169], off
	v_lshl_add_u64 v[168:169], s[52:53], 0, v[148:149]
	s_mov_b32 m0, s56
	s_nop 0
	global_load_lds_dwordx4 v[168:169], off
	v_lshl_add_u64 v[168:169], s[52:53], 0, v[152:153]
	s_add_i32 m0, s56, 0x2000
	s_nop 0
	global_load_lds_dwordx4 v[168:169], off
	v_lshl_add_u64 v[168:169], v[226:227], 0, s[40:41]
	s_mov_b32 m0, s3
	s_nop 0
	global_load_lds_dwordx4 v[168:169], off
	v_lshl_add_u64 v[168:169], v[228:229], 0, s[40:41]
	s_mov_b32 m0, s28
	s_nop 0
	global_load_lds_dwordx4 v[168:169], off
	s_waitcnt vmcnt(8)
	s_waitcnt lgkmcnt(0)
	s_barrier
	s_setprio 1
	s_waitcnt lgkmcnt(0)
	v_mfma_f32_16x16x32_bf16 v[60:63], v[128:131], v[192:195], v[60:63]
	v_mfma_f32_16x16x32_bf16 v[56:59], v[136:139], v[192:195], v[56:59]
	v_mfma_f32_16x16x32_bf16 v[44:47], v[128:131], v[200:203], v[44:47]
	v_mfma_f32_16x16x32_bf16 v[40:43], v[136:139], v[200:203], v[40:43]
	v_mfma_f32_16x16x32_bf16 v[28:31], v[128:131], v[208:211], v[28:31]
	v_mfma_f32_16x16x32_bf16 v[24:27], v[136:139], v[208:211], v[24:27]
	v_mfma_f32_16x16x32_bf16 v[12:15], v[128:131], v[216:219], v[12:15]
	v_mfma_f32_16x16x32_bf16 v[8:11], v[136:139], v[216:219], v[8:11]
	v_mfma_f32_16x16x32_bf16 v[60:63], v[132:135], v[196:199], v[60:63]
	v_mfma_f32_16x16x32_bf16 v[56:59], v[140:143], v[196:199], v[56:59]
	v_mfma_f32_16x16x32_bf16 v[44:47], v[132:135], v[204:207], v[44:47]
	v_mfma_f32_16x16x32_bf16 v[40:43], v[140:143], v[204:207], v[40:43]
	v_mfma_f32_16x16x32_bf16 v[28:31], v[132:135], v[212:215], v[28:31]
	v_mfma_f32_16x16x32_bf16 v[24:27], v[140:143], v[212:215], v[24:27]
	v_mfma_f32_16x16x32_bf16 v[12:15], v[132:135], v[220:223], v[12:15]
	v_mfma_f32_16x16x32_bf16 v[8:11], v[140:143], v[220:223], v[8:11]
	s_setprio 0
	s_setprio 1
	v_mfma_f32_16x16x32_bf16 v[52:55], v[160:163], v[192:195], v[52:55]
	v_mfma_f32_16x16x32_bf16 v[48:51], v[184:187], v[192:195], v[48:51]
	v_mfma_f32_16x16x32_bf16 v[36:39], v[160:163], v[200:203], v[36:39]
	v_mfma_f32_16x16x32_bf16 v[32:35], v[184:187], v[200:203], v[32:35]
	v_mfma_f32_16x16x32_bf16 v[20:23], v[160:163], v[208:211], v[20:23]
	v_mfma_f32_16x16x32_bf16 v[16:19], v[184:187], v[208:211], v[16:19]
	v_mfma_f32_16x16x32_bf16 v[4:7], v[160:163], v[216:219], v[4:7]
	v_mfma_f32_16x16x32_bf16 v[0:3], v[184:187], v[216:219], v[0:3]
	v_mfma_f32_16x16x32_bf16 v[52:55], v[164:167], v[196:199], v[52:55]
	v_mfma_f32_16x16x32_bf16 v[48:51], v[188:191], v[196:199], v[48:51]
	v_mfma_f32_16x16x32_bf16 v[36:39], v[164:167], v[204:207], v[36:39]
	v_mfma_f32_16x16x32_bf16 v[32:35], v[188:191], v[204:207], v[32:35]
	v_mfma_f32_16x16x32_bf16 v[20:23], v[164:167], v[212:215], v[20:23]
	s_setprio 2
	s_barrier
	v_mfma_f32_16x16x32_bf16 v[16:19], v[188:191], v[212:215], v[16:19]
	v_mfma_f32_16x16x32_bf16 v[4:7], v[164:167], v[220:223], v[4:7]
	v_mfma_f32_16x16x32_bf16 v[0:3], v[188:191], v[220:223], v[0:3]
	s_setprio 0
	s_add_i32 s92, s92, 2
	s_add_u32 s72, s72, 0x100
	s_addc_u32 s73, s73, 0
	s_add_u32 s90, s90, 0x100
	s_addc_u32 s91, s91, 0
	s_cmp_gt_u32 s92, 29
	s_cbranch_scc0 .LBB0_809
	s_and_b64 vcc, exec, s[42:43]
	s_cbranch_vccz .LBB0_812
	s_barrier

; #define PG8_STAGE(bufoff, gbase, voff) do { _Pragma("unroll") for (int _i = 0; _i < 2; ++_i) \
;         __builtin_amdgcn_global_load_lds((const unsigned*)((const char*)(gbase) + (voff)[_i]), (PG8_LAS unsigned*)(lds + (bufoff) + ldsw + _i * 8192), 16, 0, 0); } while (0)
; #define PG8_LDA(dst, b, h) do { _Pragma("unroll") for (int m = 0; m < 4; ++m) _Pragma("unroll") for (int k = 0; k < 2; ++k) dst[m][k] = *(const PG8_LAS bf16x8*)(lds + PG8_SA(b, h) + aoff + m * 2048 + k * 1024); } while (0)
; #define PG8_LDB(dst, b, h) do { _Pragma("unroll") for (int n = 0; n < 2; ++n) _Pragma("unroll") for (int k = 0; k < 2; ++k) dst[n][k] = *(const PG8_LAS bf16x8*)(lds + PG8_SB(b, h) + boff + n * 2048 + k * 1024); } while (0)
; #define PG8_MMA(ai, bj, At, Bt) do { __builtin_amdgcn_s_setprio(1); _Pragma("unroll") for (int m = 0; m < 4; ++m) _Pragma("unroll") for (int n = 0; n < 2; ++n) _Pragma("unroll") for (int k = 0; k < 2; ++k) \
;         acc[ai][bj][m][n] = __builtin_amdgcn_mfma_f32_16x16x32_bf16(Bt[n][k], At[m][k], acc[ai][bj][m][n], 0, 0, 0); __builtin_amdgcn_s_setprio(0); } while (0)
; #define PG8_WAIT_V(n) asm volatile("s_waitcnt vmcnt(" #n ")" ::: "memory")
; #define PG8_WAIT_L(n) asm volatile("s_waitcnt lgkmcnt(" #n ")" ::: "memory")
; #define PG8_BAR __builtin_amdgcn_s_barrier()
; template <class Epi, class Sched, bool ALIGN_EPI = false, bool SP2 = false>
; __device__ __forceinline__ void gemm_phase(PG8_LAS unsigned char* lds, const Gemm g, const Sched& S, const Epi& E) {
;     ...
;             const bool last = (t == nt - 2);
;             const char* a1 = cA + (size_t)(t + 1) * kstep;
;             const char* a2 = last ? nA : cA + (size_t)(t + 2) * kstep; const char* b2 = last ? nB : cB + (size_t)(t + 2) * kstep;
;             const char* a3 = a2 + kstep; const char* b3 = b2 + kstep;
;             if constexpr (SP2) {
;             PG8_LDB(B0, 0, 0); PG8_LDB(B1, 0, 1); PG8_SCHED; PG8_LDA(At, 0, 0); PG8_STAGE(PG8_SA(1, 1), a1 + hstep, voffA);
;             PG8_WAIT_V(8); PG8_WAIT_L(0); PG8_BAR; PG8_MMA(0, 0, At, B0); PG8_MMA(0, 1, At, B1); PG8_BAR; PG8_SCHED;
;             PG8_LDA(At, 0, 1); PG8_STAGE(PG8_SB(0, 0), b2, voffB); PG8_STAGE(PG8_SB(0, 1), b2 + hstep, voffB); PG8_STAGE(PG8_SA(0, 0), a2, voffA);
;             PG8_WAIT_V(8); PG8_WAIT_L(0); PG8_BAR; PG8_MMA(1, 0, At, B0); PG8_MMA(1, 1, At, B1); PG8_BAR; PG8_SCHED;
.LBB0_1051:
	ds_read_b128 v[128:131], v205
	ds_read_b128 v[132:135], v205 offset:1024
	ds_read_b128 v[154:157], v205 offset:2048
	ds_read_b128 v[158:161], v205 offset:3072
	ds_read_b128 v[162:165], v206
	ds_read_b128 v[166:169], v206 offset:1024
	ds_read_b128 v[170:173], v206 offset:2048
	ds_read_b128 v[174:177], v206 offset:3072
	s_add_u32 s54, s52, 0xfff80080
	s_addc_u32 s55, s53, -1
	s_cmp_eq_u32 s77, 28
	s_cselect_b32 s57, s43, s55
	s_cselect_b32 s56, s49, s54
	s_cselect_b32 s55, s37, s76
	s_cselect_b32 s54, s51, s75
	v_lshl_add_u64 v[218:219], s[52:53], 0, v[144:145]
	s_add_i32 m0, s61, 0xc000
	ds_read_b128 v[178:181], v207
	ds_read_b128 v[182:185], v207 offset:1024
	ds_read_b128 v[186:189], v207 offset:2048
	ds_read_b128 v[190:193], v207 offset:3072
	ds_read_b128 v[194:197], v207 offset:4096
	ds_read_b128 v[198:201], v207 offset:5120
	ds_read_b128 v[210:213], v207 offset:6144
	ds_read_b128 v[214:217], v207 offset:7168
	global_load_lds_dwordx4 v[218:219], off
	v_lshl_add_u64 v[218:219], s[52:53], 0, v[148:149]
	s_add_i32 m0, s61, 0xe000
	s_nop 0
	global_load_lds_dwordx4 v[218:219], off
	s_waitcnt vmcnt(8)
	s_waitcnt lgkmcnt(0)
	s_barrier
	s_setprio 1
	s_waitcnt lgkmcnt(0)
	v_mfma_f32_16x16x32_bf16 v[124:127], v[128:131], v[178:181], v[124:127]
	v_mfma_f32_16x16x32_bf16 v[120:123], v[154:157], v[178:181], v[120:123]
	v_mfma_f32_16x16x32_bf16 v[116:119], v[128:131], v[186:189], v[116:119]
	v_mfma_f32_16x16x32_bf16 v[112:115], v[154:157], v[186:189], v[112:115]
	v_mfma_f32_16x16x32_bf16 v[108:111], v[128:131], v[194:197], v[108:111]
	v_mfma_f32_16x16x32_bf16 v[104:107], v[154:157], v[194:197], v[104:107]
	v_mfma_f32_16x16x32_bf16 v[100:103], v[128:131], v[210:213], v[100:103]
	v_mfma_f32_16x16x32_bf16 v[96:99], v[154:157], v[210:213], v[96:99]
	v_mfma_f32_16x16x32_bf16 v[124:127], v[132:135], v[182:185], v[124:127]
	v_mfma_f32_16x16x32_bf16 v[120:123], v[158:161], v[182:185], v[120:123]
	v_mfma_f32_16x16x32_bf16 v[116:119], v[132:135], v[190:193], v[116:119]
	v_mfma_f32_16x16x32_bf16 v[112:115], v[158:161], v[190:193], v[112:115]
	v_mfma_f32_16x16x32_bf16 v[108:111], v[132:135], v[198:201], v[108:111]
	v_mfma_f32_16x16x32_bf16 v[104:107], v[158:161], v[198:201], v[104:107]
	v_mfma_f32_16x16x32_bf16 v[100:103], v[132:135], v[214:217], v[100:103]
	v_mfma_f32_16x16x32_bf16 v[96:99], v[158:161], v[214:217], v[96:99]
	s_setprio 0
	s_setprio 1
	v_mfma_f32_16x16x32_bf16 v[60:63], v[162:165], v[178:181], v[60:63]
	v_mfma_f32_16x16x32_bf16 v[56:59], v[170:173], v[178:181], v[56:59]
	v_mfma_f32_16x16x32_bf16 v[52:55], v[162:165], v[186:189], v[52:55]
	v_mfma_f32_16x16x32_bf16 v[48:51], v[170:173], v[186:189], v[48:51]
	v_mfma_f32_16x16x32_bf16 v[44:47], v[162:165], v[194:197], v[44:47]
	v_mfma_f32_16x16x32_bf16 v[40:43], v[170:173], v[194:197], v[40:43]
	v_mfma_f32_16x16x32_bf16 v[36:39], v[162:165], v[210:213], v[36:39]
	v_mfma_f32_16x16x32_bf16 v[32:35], v[170:173], v[210:213], v[32:35]
	v_mfma_f32_16x16x32_bf16 v[60:63], v[166:169], v[182:185], v[60:63]
	v_mfma_f32_16x16x32_bf16 v[56:59], v[174:177], v[182:185], v[56:59]
	v_mfma_f32_16x16x32_bf16 v[52:55], v[166:169], v[190:193], v[52:55]
	v_mfma_f32_16x16x32_bf16 v[48:51], v[174:177], v[190:193], v[48:51]
	v_mfma_f32_16x16x32_bf16 v[44:47], v[166:169], v[198:201], v[44:47]
	s_setprio 2
	s_barrier
	v_mfma_f32_16x16x32_bf16 v[40:43], v[174:177], v[198:201], v[40:43]
	v_mfma_f32_16x16x32_bf16 v[36:39], v[166:169], v[214:217], v[36:39]
	v_mfma_f32_16x16x32_bf16 v[32:35], v[174:177], v[214:217], v[32:35]
	s_setprio 0
	s_add_i32 s78, s33, s60
	v_lshl_add_u64 v[218:219], s[54:55], 0, v[138:139]
	s_mov_b32 m0, s78
	ds_read_b128 v[178:181], v207 offset:16384
	ds_read_b128 v[182:185], v207 offset:17408
	ds_read_b128 v[186:189], v207 offset:18432
	ds_read_b128 v[190:193], v207 offset:19456
	ds_read_b128 v[194:197], v207 offset:20480
	ds_read_b128 v[198:201], v207 offset:21504
	ds_read_b128 v[210:213], v207 offset:22528
	ds_read_b128 v[214:217], v207 offset:23552
	global_load_lds_dwordx4 v[218:219], off
	s_add_i32 m0, s78, 0x2000
	s_add_u32 s78, s54, 0x80000
	v_lshl_add_u64 v[220:221], s[54:55], 0, v[142:143]
	s_addc_u32 s79, s55, 0
	s_add_i32 s80, s74, s60
	global_load_lds_dwordx4 v[220:221], off
	v_lshl_add_u64 v[222:223], s[78:79], 0, v[138:139]
	s_mov_b32 m0, s80
	v_lshl_add_u64 v[224:225], s[56:57], 0, v[140:141]
	global_load_lds_dwordx4 v[222:223], off
	v_lshl_add_u64 v[222:223], s[78:79], 0, v[142:143]
	s_add_i32 m0, s80, 0x2000
	s_nop 0
	global_load_lds_dwordx4 v[222:223], off
	v_lshl_add_u64 v[222:223], s[56:57], 0, v[136:137]
	s_mov_b32 m0, s61
	s_nop 0
	global_load_lds_dwordx4 v[222:223], off
	s_mov_b32 m0, s62
	s_nop 0
	global_load_lds_dwordx4 v[224:225], off
	s_waitcnt vmcnt(8)
	s_waitcnt lgkmcnt(0)
	s_barrier
; #define PG8_STAGE(bufoff, gbase, voff) do { _Pragma("unroll") for (int _i = 0; _i < 2; ++_i) \
;         __builtin_amdgcn_global_load_lds((const unsigned*)((const char*)(gbase) + (voff)[_i]), (PG8_LAS unsigned*)(lds + (bufoff) + ldsw + _i * 8192), 16, 0, 0); } while (0)
; #define PG8_LDA(dst, b, h) do { _Pragma("unroll") for (int m = 0; m < 4; ++m) _Pragma("unroll") for (int k = 0; k < 2; ++k) dst[m][k] = *(const PG8_LAS bf16x8*)(lds + PG8_SA(b, h) + aoff + m * 2048 + k * 1024); } while (0)
; #define PG8_LDB(dst, b, h) do { _Pragma("unroll") for (int n = 0; n < 2; ++n) _Pragma("unroll") for (int k = 0; k < 2; ++k) dst[n][k] = *(const PG8_LAS bf16x8*)(lds + PG8_SB(b, h) + boff + n * 2048 + k * 1024); } while (0)
; #define PG8_MMA(ai, bj, At, Bt) do { __builtin_amdgcn_s_setprio(1); _Pragma("unroll") for (int m = 0; m < 4; ++m) _Pragma("unroll") for (int n = 0; n < 2; ++n) _Pragma("unroll") for (int k = 0; k < 2; ++k) \
;         acc[ai][bj][m][n] = __builtin_amdgcn_mfma_f32_16x16x32_bf16(Bt[n][k], At[m][k], acc[ai][bj][m][n], 0, 0, 0); __builtin_amdgcn_s_setprio(0); } while (0)
; #define PG8_WAIT_V(n) asm volatile("s_waitcnt vmcnt(" #n ")" ::: "memory")
; #define PG8_WAIT_L(n) asm volatile("s_waitcnt lgkmcnt(" #n ")" ::: "memory")
; #define PG8_BAR __builtin_amdgcn_s_barrier()
; #define PG8_SCHED __builtin_amdgcn_sched_barrier(0)
; template <class Epi, class Sched, bool ALIGN_EPI = false, bool SP2 = false>
; __device__ __forceinline__ void gemm_phase(PG8_LAS unsigned char* lds, const Gemm g, const Sched& S, const Epi& E) {
;     ...
;             PG8_WAIT_V(8); PG8_WAIT_L(0); PG8_BAR; PG8_MMA(1, 0, At, B0); PG8_MMA(1, 1, At, B1); PG8_BAR; PG8_SCHED;
;             PG8_LDB(B0, 1, 0); PG8_LDB(B1, 1, 1); PG8_SCHED; PG8_LDA(At, 1, 0); PG8_STAGE(PG8_SA(0, 1), a2 + hstep, voffA);
;             PG8_WAIT_V(8); PG8_WAIT_L(0); PG8_BAR; PG8_MMA(0, 0, At, B0); PG8_MMA(0, 1, At, B1); PG8_BAR; PG8_SCHED;
	s_setprio 1
	s_waitcnt lgkmcnt(0)
	v_mfma_f32_16x16x32_bf16 v[92:95], v[128:131], v[178:181], v[92:95]
	v_mfma_f32_16x16x32_bf16 v[88:91], v[154:157], v[178:181], v[88:91]
	v_mfma_f32_16x16x32_bf16 v[84:87], v[128:131], v[186:189], v[84:87]
	v_mfma_f32_16x16x32_bf16 v[80:83], v[154:157], v[186:189], v[80:83]
	v_mfma_f32_16x16x32_bf16 v[76:79], v[128:131], v[194:197], v[76:79]
	v_mfma_f32_16x16x32_bf16 v[72:75], v[154:157], v[194:197], v[72:75]
	v_mfma_f32_16x16x32_bf16 v[68:71], v[128:131], v[210:213], v[68:71]
	v_mfma_f32_16x16x32_bf16 v[64:67], v[154:157], v[210:213], v[64:67]
	v_mfma_f32_16x16x32_bf16 v[92:95], v[132:135], v[182:185], v[92:95]
	v_mfma_f32_16x16x32_bf16 v[88:91], v[158:161], v[182:185], v[88:91]
	v_mfma_f32_16x16x32_bf16 v[84:87], v[132:135], v[190:193], v[84:87]
	v_mfma_f32_16x16x32_bf16 v[80:83], v[158:161], v[190:193], v[80:83]
	v_mfma_f32_16x16x32_bf16 v[76:79], v[132:135], v[198:201], v[76:79]
	v_mfma_f32_16x16x32_bf16 v[72:75], v[158:161], v[198:201], v[72:75]
	v_mfma_f32_16x16x32_bf16 v[68:71], v[132:135], v[214:217], v[68:71]
	v_mfma_f32_16x16x32_bf16 v[64:67], v[158:161], v[214:217], v[64:67]
	s_setprio 0
	s_setprio 1
	v_mfma_f32_16x16x32_bf16 v[28:31], v[162:165], v[178:181], v[28:31]
	v_mfma_f32_16x16x32_bf16 v[24:27], v[170:173], v[178:181], v[24:27]
	v_mfma_f32_16x16x32_bf16 v[20:23], v[162:165], v[186:189], v[20:23]
	v_mfma_f32_16x16x32_bf16 v[16:19], v[170:173], v[186:189], v[16:19]
	v_mfma_f32_16x16x32_bf16 v[12:15], v[162:165], v[194:197], v[12:15]
	v_mfma_f32_16x16x32_bf16 v[8:11], v[170:173], v[194:197], v[8:11]
	v_mfma_f32_16x16x32_bf16 v[4:7], v[162:165], v[210:213], v[4:7]
	v_mfma_f32_16x16x32_bf16 v[0:3], v[170:173], v[210:213], v[0:3]
	v_mfma_f32_16x16x32_bf16 v[28:31], v[166:169], v[182:185], v[28:31]
	v_mfma_f32_16x16x32_bf16 v[24:27], v[174:177], v[182:185], v[24:27]
	v_mfma_f32_16x16x32_bf16 v[20:23], v[166:169], v[190:193], v[20:23]
	v_mfma_f32_16x16x32_bf16 v[16:19], v[174:177], v[190:193], v[16:19]
	v_mfma_f32_16x16x32_bf16 v[12:15], v[166:169], v[198:201], v[12:15]
	s_setprio 2
	s_barrier
	v_mfma_f32_16x16x32_bf16 v[8:11], v[174:177], v[198:201], v[8:11]
	v_mfma_f32_16x16x32_bf16 v[4:7], v[166:169], v[214:217], v[4:7]
	v_mfma_f32_16x16x32_bf16 v[0:3], v[174:177], v[214:217], v[0:3]
	s_setprio 0
	s_add_i32 s78, 0, 0x18000
	s_add_i32 s79, 0, 0x1c000
	v_add_u32_e32 v158, s78, v203
	v_add_u32_e32 v174, s79, v203
	ds_read_b128 v[128:131], v158
	ds_read_b128 v[132:135], v158 offset:1024
	ds_read_b128 v[154:157], v158 offset:2048
	ds_read_b128 v[158:161], v158 offset:3072
	ds_read_b128 v[162:165], v174
	ds_read_b128 v[166:169], v174 offset:1024
	ds_read_b128 v[170:173], v174 offset:2048
	ds_read_b128 v[174:177], v174 offset:3072
	s_add_u32 s56, s56, 0x80000
	s_addc_u32 s57, s57, 0
	s_mov_b32 m0, s63
	v_lshl_add_u64 v[226:227], s[56:57], 0, v[136:137]
	ds_read_b128 v[178:181], v207 offset:32768
	ds_read_b128 v[182:185], v207 offset:33792
	ds_read_b128 v[186:189], v207 offset:34816
	ds_read_b128 v[190:193], v207 offset:35840
	ds_read_b128 v[194:197], v207 offset:36864
	ds_read_b128 v[198:201], v207 offset:37888
	ds_read_b128 v[210:213], v207 offset:38912
	ds_read_b128 v[214:217], v207 offset:39936
	global_load_lds_dwordx4 v[226:227], off
	v_lshl_add_u64 v[226:227], s[56:57], 0, v[140:141]
	s_mov_b32 m0, s64
	s_nop 0
	global_load_lds_dwordx4 v[226:227], off
	s_waitcnt vmcnt(8)
	s_waitcnt lgkmcnt(0)
	s_barrier
	s_setprio 1
	s_waitcnt lgkmcnt(0)
	v_mfma_f32_16x16x32_bf16 v[124:127], v[128:131], v[178:181], v[124:127]
	v_mfma_f32_16x16x32_bf16 v[120:123], v[154:157], v[178:181], v[120:123]
	v_mfma_f32_16x16x32_bf16 v[116:119], v[128:131], v[186:189], v[116:119]
	v_mfma_f32_16x16x32_bf16 v[112:115], v[154:157], v[186:189], v[112:115]
	v_mfma_f32_16x16x32_bf16 v[108:111], v[128:131], v[194:197], v[108:111]
	v_mfma_f32_16x16x32_bf16 v[104:107], v[154:157], v[194:197], v[104:107]
	v_mfma_f32_16x16x32_bf16 v[100:103], v[128:131], v[210:213], v[100:103]
	v_mfma_f32_16x16x32_bf16 v[96:99], v[154:157], v[210:213], v[96:99]
	v_mfma_f32_16x16x32_bf16 v[124:127], v[132:135], v[182:185], v[124:127]
	v_mfma_f32_16x16x32_bf16 v[120:123], v[158:161], v[182:185], v[120:123]
	v_mfma_f32_16x16x32_bf16 v[116:119], v[132:135], v[190:193], v[116:119]
	v_mfma_f32_16x16x32_bf16 v[112:115], v[158:161], v[190:193], v[112:115]
	v_mfma_f32_16x16x32_bf16 v[108:111], v[132:135], v[198:201], v[108:111]
	v_mfma_f32_16x16x32_bf16 v[104:107], v[158:161], v[198:201], v[104:107]
	v_mfma_f32_16x16x32_bf16 v[100:103], v[132:135], v[214:217], v[100:103]
	v_mfma_f32_16x16x32_bf16 v[96:99], v[158:161], v[214:217], v[96:99]
	s_setprio 0
	s_setprio 1
	v_mfma_f32_16x16x32_bf16 v[60:63], v[162:165], v[178:181], v[60:63]
	v_mfma_f32_16x16x32_bf16 v[56:59], v[170:173], v[178:181], v[56:59]
	v_mfma_f32_16x16x32_bf16 v[52:55], v[162:165], v[186:189], v[52:55]
	v_mfma_f32_16x16x32_bf16 v[48:51], v[170:173], v[186:189], v[48:51]
	v_mfma_f32_16x16x32_bf16 v[44:47], v[162:165], v[194:197], v[44:47]
	v_mfma_f32_16x16x32_bf16 v[40:43], v[170:173], v[194:197], v[40:43]
	v_mfma_f32_16x16x32_bf16 v[36:39], v[162:165], v[210:213], v[36:39]
	v_mfma_f32_16x16x32_bf16 v[32:35], v[170:173], v[210:213], v[32:35]
	v_mfma_f32_16x16x32_bf16 v[60:63], v[166:169], v[182:185], v[60:63]
	v_mfma_f32_16x16x32_bf16 v[56:59], v[174:177], v[182:185], v[56:59]
	v_mfma_f32_16x16x32_bf16 v[52:55], v[166:169], v[190:193], v[52:55]
	v_mfma_f32_16x16x32_bf16 v[48:51], v[174:177], v[190:193], v[48:51]
	v_mfma_f32_16x16x32_bf16 v[44:47], v[166:169], v[198:201], v[44:47]
	s_setprio 2
	s_barrier
; #define PG8_STAGE(bufoff, gbase, voff) do { _Pragma("unroll") for (int _i = 0; _i < 2; ++_i) \
;         __builtin_amdgcn_global_load_lds((const unsigned*)((const char*)(gbase) + (voff)[_i]), (PG8_LAS unsigned*)(lds + (bufoff) + ldsw + _i * 8192), 16, 0, 0); } while (0)
; #define PG8_LDA(dst, b, h) do { _Pragma("unroll") for (int m = 0; m < 4; ++m) _Pragma("unroll") for (int k = 0; k < 2; ++k) dst[m][k] = *(const PG8_LAS bf16x8*)(lds + PG8_SA(b, h) + aoff + m * 2048 + k * 1024); } while (0)
; #define PG8_MMA(ai, bj, At, Bt) do { __builtin_amdgcn_s_setprio(1); _Pragma("unroll") for (int m = 0; m < 4; ++m) _Pragma("unroll") for (int n = 0; n < 2; ++n) _Pragma("unroll") for (int k = 0; k < 2; ++k) \
;         acc[ai][bj][m][n] = __builtin_amdgcn_mfma_f32_16x16x32_bf16(Bt[n][k], At[m][k], acc[ai][bj][m][n], 0, 0, 0); __builtin_amdgcn_s_setprio(0); } while (0)
; #define PG8_WAIT_V(n) asm volatile("s_waitcnt vmcnt(" #n ")" ::: "memory")
; #define PG8_WAIT_L(n) asm volatile("s_waitcnt lgkmcnt(" #n ")" ::: "memory")
; #define PG8_BAR __builtin_amdgcn_s_barrier()
; #define PG8_SCHED __builtin_amdgcn_sched_barrier(0)
; template <class Epi, class Sched, bool ALIGN_EPI = false, bool SP2 = false>
; __device__ __forceinline__ void gemm_phase(PG8_LAS unsigned char* lds, const Gemm g, const Sched& S, const Epi& E) {
;     ...
;             PG8_WAIT_V(8); PG8_WAIT_L(0); PG8_BAR; PG8_MMA(0, 0, At, B0); PG8_MMA(0, 1, At, B1); PG8_BAR; PG8_SCHED;
;             PG8_LDA(At, 1, 1); PG8_STAGE(PG8_SB(1, 0), b3, voffB); PG8_STAGE(PG8_SB(1, 1), b3 + hstep, voffB); PG8_STAGE(PG8_SA(1, 0), a3, voffA);
;             PG8_WAIT_V(8); PG8_WAIT_L(0); PG8_BAR; PG8_MMA(1, 0, At, B0); PG8_MMA(1, 1, At, B1); PG8_BAR; PG8_SCHED;
;     ...
;         if constexpr (ALIGN_EPI) { if (wr == 0) PG8_BAR; }
	v_mfma_f32_16x16x32_bf16 v[40:43], v[174:177], v[198:201], v[40:43]
	v_mfma_f32_16x16x32_bf16 v[36:39], v[166:169], v[214:217], v[36:39]
	v_mfma_f32_16x16x32_bf16 v[32:35], v[174:177], v[214:217], v[32:35]
	s_setprio 0
	s_add_i32 s56, s78, s60
	v_lshl_add_u64 v[218:219], v[218:219], 0, s[12:13]
	s_mov_b32 m0, s56
	ds_read_b128 v[178:181], v207 offset:49152
	ds_read_b128 v[182:185], v207 offset:50176
	ds_read_b128 v[186:189], v207 offset:51200
	ds_read_b128 v[190:193], v207 offset:52224
	ds_read_b128 v[194:197], v207 offset:53248
	ds_read_b128 v[198:201], v207 offset:54272
	ds_read_b128 v[210:213], v207 offset:55296
	ds_read_b128 v[214:217], v207 offset:56320
	global_load_lds_dwordx4 v[218:219], off
	s_add_i32 m0, s56, 0x2000
	s_add_u32 s54, s54, 0x80080
	v_lshl_add_u64 v[218:219], v[220:221], 0, s[12:13]
	s_addc_u32 s55, s55, 0
	s_add_i32 s56, s79, s60
	global_load_lds_dwordx4 v[218:219], off
	v_lshl_add_u64 v[218:219], s[54:55], 0, v[138:139]
	s_mov_b32 m0, s56
	s_nop 0
	global_load_lds_dwordx4 v[218:219], off
	v_lshl_add_u64 v[218:219], s[54:55], 0, v[142:143]
	s_add_i32 m0, s56, 0x2000
	s_nop 0
	global_load_lds_dwordx4 v[218:219], off
	v_lshl_add_u64 v[218:219], v[222:223], 0, s[12:13]
	s_mov_b32 m0, s70
	s_nop 0
	global_load_lds_dwordx4 v[218:219], off
	v_lshl_add_u64 v[218:219], v[224:225], 0, s[12:13]
	s_mov_b32 m0, s71
	s_nop 0
	global_load_lds_dwordx4 v[218:219], off
	s_waitcnt vmcnt(8)
	s_waitcnt lgkmcnt(0)
	s_barrier
	s_setprio 1
	s_waitcnt lgkmcnt(0)
	v_mfma_f32_16x16x32_bf16 v[92:95], v[128:131], v[178:181], v[92:95]
	v_mfma_f32_16x16x32_bf16 v[88:91], v[154:157], v[178:181], v[88:91]
	v_mfma_f32_16x16x32_bf16 v[84:87], v[128:131], v[186:189], v[84:87]
	v_mfma_f32_16x16x32_bf16 v[80:83], v[154:157], v[186:189], v[80:83]
	v_mfma_f32_16x16x32_bf16 v[76:79], v[128:131], v[194:197], v[76:79]
	v_mfma_f32_16x16x32_bf16 v[72:75], v[154:157], v[194:197], v[72:75]
	v_mfma_f32_16x16x32_bf16 v[68:71], v[128:131], v[210:213], v[68:71]
	v_mfma_f32_16x16x32_bf16 v[64:67], v[154:157], v[210:213], v[64:67]
	v_mfma_f32_16x16x32_bf16 v[92:95], v[132:135], v[182:185], v[92:95]
	v_mfma_f32_16x16x32_bf16 v[88:91], v[158:161], v[182:185], v[88:91]
	v_mfma_f32_16x16x32_bf16 v[84:87], v[132:135], v[190:193], v[84:87]
	v_mfma_f32_16x16x32_bf16 v[80:83], v[158:161], v[190:193], v[80:83]
	v_mfma_f32_16x16x32_bf16 v[76:79], v[132:135], v[198:201], v[76:79]
	v_mfma_f32_16x16x32_bf16 v[72:75], v[158:161], v[198:201], v[72:75]
	v_mfma_f32_16x16x32_bf16 v[68:71], v[132:135], v[214:217], v[68:71]
	v_mfma_f32_16x16x32_bf16 v[64:67], v[158:161], v[214:217], v[64:67]
	s_setprio 0
	s_setprio 1
	v_mfma_f32_16x16x32_bf16 v[28:31], v[162:165], v[178:181], v[28:31]
	v_mfma_f32_16x16x32_bf16 v[24:27], v[170:173], v[178:181], v[24:27]
	v_mfma_f32_16x16x32_bf16 v[20:23], v[162:165], v[186:189], v[20:23]
	v_mfma_f32_16x16x32_bf16 v[16:19], v[170:173], v[186:189], v[16:19]
	v_mfma_f32_16x16x32_bf16 v[12:15], v[162:165], v[194:197], v[12:15]
	v_mfma_f32_16x16x32_bf16 v[8:11], v[170:173], v[194:197], v[8:11]
	v_mfma_f32_16x16x32_bf16 v[4:7], v[162:165], v[210:213], v[4:7]
	v_mfma_f32_16x16x32_bf16 v[0:3], v[170:173], v[210:213], v[0:3]
	v_mfma_f32_16x16x32_bf16 v[28:31], v[166:169], v[182:185], v[28:31]
	v_mfma_f32_16x16x32_bf16 v[24:27], v[174:177], v[182:185], v[24:27]
	v_mfma_f32_16x16x32_bf16 v[20:23], v[166:169], v[190:193], v[20:23]
	v_mfma_f32_16x16x32_bf16 v[16:19], v[174:177], v[190:193], v[16:19]
	v_mfma_f32_16x16x32_bf16 v[12:15], v[166:169], v[198:201], v[12:15]
	s_setprio 2
	s_barrier
	v_mfma_f32_16x16x32_bf16 v[8:11], v[174:177], v[198:201], v[8:11]
	v_mfma_f32_16x16x32_bf16 v[4:7], v[166:169], v[214:217], v[4:7]
	v_mfma_f32_16x16x32_bf16 v[0:3], v[174:177], v[214:217], v[0:3]
	s_setprio 0
	s_add_i32 s77, s77, 2
	s_add_u32 s52, s52, 0x100
	s_addc_u32 s53, s53, 0
	s_add_u32 s75, s75, 0x100
	s_addc_u32 s76, s76, 0
	s_cmp_gt_u32 s77, 29
	s_cbranch_scc0 .LBB0_1051
	s_and_b64 vcc, exec, s[14:15]
	s_cbranch_vccz .LBB0_1054
	s_barrier

; #define PG8_STAGE(bufoff, gbase, voff) do { _Pragma("unroll") for (int _i = 0; _i < 2; ++_i) \
;         __builtin_amdgcn_global_load_lds((const unsigned*)((const char*)(gbase) + (voff)[_i]), (PG8_LAS unsigned*)(lds + (bufoff) + ldsw + _i * 8192), 16, 0, 0); } while (0)
; #define PG8_LDA(dst, b, h) do { _Pragma("unroll") for (int m = 0; m < 4; ++m) _Pragma("unroll") for (int k = 0; k < 2; ++k) dst[m][k] = *(const PG8_LAS bf16x8*)(lds + PG8_SA(b, h) + aoff + m * 2048 + k * 1024); } while (0)
; #define PG8_LDB(dst, b, h) do { _Pragma("unroll") for (int n = 0; n < 2; ++n) _Pragma("unroll") for (int k = 0; k < 2; ++k) dst[n][k] = *(const PG8_LAS bf16x8*)(lds + PG8_SB(b, h) + boff + n * 2048 + k * 1024); } while (0)
; #define PG8_MMA(ai, bj, At, Bt) do { __builtin_amdgcn_s_setprio(1); _Pragma("unroll") for (int m = 0; m < 4; ++m) _Pragma("unroll") for (int n = 0; n < 2; ++n) _Pragma("unroll") for (int k = 0; k < 2; ++k) \
;         acc[ai][bj][m][n] = __builtin_amdgcn_mfma_f32_16x16x32_bf16(Bt[n][k], At[m][k], acc[ai][bj][m][n], 0, 0, 0); __builtin_amdgcn_s_setprio(0); } while (0)
; #define PG8_WAIT_V(n) asm volatile("s_waitcnt vmcnt(" #n ")" ::: "memory")
; #define PG8_WAIT_L(n) asm volatile("s_waitcnt lgkmcnt(" #n ")" ::: "memory")
; #define PG8_BAR __builtin_amdgcn_s_barrier()
; template <class Epi, class Sched, bool ALIGN_EPI = false, bool SP2 = false>
; __device__ __forceinline__ void gemm_phase(PG8_LAS unsigned char* lds, const Gemm g, const Sched& S, const Epi& E) {
;     ...
;             const bool last = (t == nt - 2);
;             const char* a1 = cA + (size_t)(t + 1) * kstep;
;             const char* a2 = last ? nA : cA + (size_t)(t + 2) * kstep; const char* b2 = last ? nB : cB + (size_t)(t + 2) * kstep;
;             const char* a3 = a2 + kstep; const char* b3 = b2 + kstep;
;             if constexpr (SP2) {
;             PG8_LDB(B0, 0, 0); PG8_LDB(B1, 0, 1); PG8_SCHED; PG8_LDA(At, 0, 0); PG8_STAGE(PG8_SA(1, 1), a1 + hstep, voffA);
;             PG8_WAIT_V(8); PG8_WAIT_L(0); PG8_BAR; PG8_MMA(0, 0, At, B0); PG8_MMA(0, 1, At, B1); PG8_BAR; PG8_SCHED;
;             PG8_LDA(At, 0, 1); PG8_STAGE(PG8_SB(0, 0), b2, voffB); PG8_STAGE(PG8_SB(0, 1), b2 + hstep, voffB); PG8_STAGE(PG8_SA(0, 0), a2, voffA);
;             PG8_WAIT_V(8); PG8_WAIT_L(0); PG8_BAR; PG8_MMA(1, 0, At, B0); PG8_MMA(1, 1, At, B1); PG8_BAR; PG8_SCHED;
.LBB0_1142:
	ds_read_b128 v[80:83], v171
	ds_read_b128 v[84:87], v171 offset:1024
	ds_read_b128 v[88:91], v171 offset:2048
	ds_read_b128 v[92:95], v171 offset:3072
	ds_read_b128 v[164:167], v172
	ds_read_b128 v[176:179], v172 offset:1024
	ds_read_b128 v[180:183], v172 offset:2048
	ds_read_b128 v[184:187], v172 offset:3072
	s_add_u32 s44, s42, 0xfff80080
	s_addc_u32 s45, s43, -1
	s_cmp_eq_u32 s64, 28
	s_cselect_b32 s47, s15, s45
	s_cselect_b32 s46, s60, s44
	s_cselect_b32 s45, s13, s63
	s_cselect_b32 s44, s61, s62
	v_lshl_add_u64 v[220:221], s[42:43], 0, v[156:157]
	s_add_i32 m0, s41, 0xc000
	ds_read_b128 v[188:191], v173
	ds_read_b128 v[192:195], v173 offset:1024
	ds_read_b128 v[196:199], v173 offset:2048
	ds_read_b128 v[200:203], v173 offset:3072
	ds_read_b128 v[204:207], v173 offset:4096
	ds_read_b128 v[208:211], v173 offset:5120
	ds_read_b128 v[212:215], v173 offset:6144
	ds_read_b128 v[216:219], v173 offset:7168
	global_load_lds_dwordx4 v[220:221], off
	v_lshl_add_u64 v[220:221], s[42:43], 0, v[158:159]
	s_add_i32 m0, s41, 0xe000
	s_nop 0
	global_load_lds_dwordx4 v[220:221], off
	s_waitcnt vmcnt(8)
	s_waitcnt lgkmcnt(0)
	s_barrier
	s_setprio 1
	s_waitcnt lgkmcnt(0)
	v_mfma_f32_16x16x32_bf16 v[140:143], v[80:83], v[188:191], v[140:143]
	v_mfma_f32_16x16x32_bf16 v[136:139], v[88:91], v[188:191], v[136:139]
	v_mfma_f32_16x16x32_bf16 v[124:127], v[80:83], v[196:199], v[124:127]
	v_mfma_f32_16x16x32_bf16 v[120:123], v[88:91], v[196:199], v[120:123]
	v_mfma_f32_16x16x32_bf16 v[108:111], v[80:83], v[204:207], v[108:111]
	v_mfma_f32_16x16x32_bf16 v[104:107], v[88:91], v[204:207], v[104:107]
	v_mfma_f32_16x16x32_bf16 v[76:79], v[80:83], v[212:215], v[76:79]
	v_mfma_f32_16x16x32_bf16 v[72:75], v[88:91], v[212:215], v[72:75]
	v_mfma_f32_16x16x32_bf16 v[140:143], v[84:87], v[192:195], v[140:143]
	v_mfma_f32_16x16x32_bf16 v[136:139], v[92:95], v[192:195], v[136:139]
	v_mfma_f32_16x16x32_bf16 v[124:127], v[84:87], v[200:203], v[124:127]
	v_mfma_f32_16x16x32_bf16 v[120:123], v[92:95], v[200:203], v[120:123]
	v_mfma_f32_16x16x32_bf16 v[108:111], v[84:87], v[208:211], v[108:111]
	v_mfma_f32_16x16x32_bf16 v[104:107], v[92:95], v[208:211], v[104:107]
	v_mfma_f32_16x16x32_bf16 v[76:79], v[84:87], v[216:219], v[76:79]
	v_mfma_f32_16x16x32_bf16 v[72:75], v[92:95], v[216:219], v[72:75]
	s_setprio 0
	s_setprio 1
	v_mfma_f32_16x16x32_bf16 v[132:135], v[164:167], v[188:191], v[132:135]
	v_mfma_f32_16x16x32_bf16 v[128:131], v[180:183], v[188:191], v[128:131]
	v_mfma_f32_16x16x32_bf16 v[116:119], v[164:167], v[196:199], v[116:119]
	v_mfma_f32_16x16x32_bf16 v[112:115], v[180:183], v[196:199], v[112:115]
	v_mfma_f32_16x16x32_bf16 v[100:103], v[164:167], v[204:207], v[100:103]
	v_mfma_f32_16x16x32_bf16 v[96:99], v[180:183], v[204:207], v[96:99]
	v_mfma_f32_16x16x32_bf16 v[68:71], v[164:167], v[212:215], v[68:71]
	v_mfma_f32_16x16x32_bf16 v[64:67], v[180:183], v[212:215], v[64:67]
	v_mfma_f32_16x16x32_bf16 v[132:135], v[176:179], v[192:195], v[132:135]
	v_mfma_f32_16x16x32_bf16 v[128:131], v[184:187], v[192:195], v[128:131]
	v_mfma_f32_16x16x32_bf16 v[116:119], v[176:179], v[200:203], v[116:119]
	v_mfma_f32_16x16x32_bf16 v[112:115], v[184:187], v[200:203], v[112:115]
	v_mfma_f32_16x16x32_bf16 v[100:103], v[176:179], v[208:211], v[100:103]
	s_setprio 2
	s_barrier
	v_mfma_f32_16x16x32_bf16 v[96:99], v[184:187], v[208:211], v[96:99]
	v_mfma_f32_16x16x32_bf16 v[68:71], v[176:179], v[216:219], v[68:71]
	v_mfma_f32_16x16x32_bf16 v[64:67], v[184:187], v[216:219], v[64:67]
	s_setprio 0
	s_add_i32 s65, s56, s33
	v_lshl_add_u64 v[220:221], s[44:45], 0, v[148:149]
	s_mov_b32 m0, s65
	ds_read_b128 v[188:191], v173 offset:16384
	ds_read_b128 v[192:195], v173 offset:17408
	ds_read_b128 v[196:199], v173 offset:18432
	ds_read_b128 v[200:203], v173 offset:19456
	ds_read_b128 v[204:207], v173 offset:20480
	ds_read_b128 v[208:211], v173 offset:21504
	ds_read_b128 v[212:215], v173 offset:22528
	ds_read_b128 v[216:219], v173 offset:23552
	global_load_lds_dwordx4 v[220:221], off
	s_add_i32 m0, s65, 0x2000
	s_add_u32 s66, s44, 0x80000
	v_lshl_add_u64 v[222:223], s[44:45], 0, v[152:153]
	s_addc_u32 s67, s45, 0
	s_add_i32 s65, s57, s33
	global_load_lds_dwordx4 v[222:223], off
	v_lshl_add_u64 v[224:225], s[66:67], 0, v[148:149]
	s_mov_b32 m0, s65
	v_lshl_add_u64 v[226:227], s[46:47], 0, v[150:151]
	global_load_lds_dwordx4 v[224:225], off
	v_lshl_add_u64 v[224:225], s[66:67], 0, v[152:153]
	s_add_i32 m0, s65, 0x2000
	s_nop 0
	global_load_lds_dwordx4 v[224:225], off
	v_lshl_add_u64 v[224:225], s[46:47], 0, v[144:145]
	s_mov_b32 m0, s41
	s_nop 0
	global_load_lds_dwordx4 v[224:225], off
	s_mov_b32 m0, s48
	s_nop 0
	global_load_lds_dwordx4 v[226:227], off
	s_waitcnt vmcnt(8)
	s_waitcnt lgkmcnt(0)
	s_barrier
; #define PG8_STAGE(bufoff, gbase, voff) do { _Pragma("unroll") for (int _i = 0; _i < 2; ++_i) \
;         __builtin_amdgcn_global_load_lds((const unsigned*)((const char*)(gbase) + (voff)[_i]), (PG8_LAS unsigned*)(lds + (bufoff) + ldsw + _i * 8192), 16, 0, 0); } while (0)
; #define PG8_LDA(dst, b, h) do { _Pragma("unroll") for (int m = 0; m < 4; ++m) _Pragma("unroll") for (int k = 0; k < 2; ++k) dst[m][k] = *(const PG8_LAS bf16x8*)(lds + PG8_SA(b, h) + aoff + m * 2048 + k * 1024); } while (0)
; #define PG8_LDB(dst, b, h) do { _Pragma("unroll") for (int n = 0; n < 2; ++n) _Pragma("unroll") for (int k = 0; k < 2; ++k) dst[n][k] = *(const PG8_LAS bf16x8*)(lds + PG8_SB(b, h) + boff + n * 2048 + k * 1024); } while (0)
; #define PG8_MMA(ai, bj, At, Bt) do { __builtin_amdgcn_s_setprio(1); _Pragma("unroll") for (int m = 0; m < 4; ++m) _Pragma("unroll") for (int n = 0; n < 2; ++n) _Pragma("unroll") for (int k = 0; k < 2; ++k) \
;         acc[ai][bj][m][n] = __builtin_amdgcn_mfma_f32_16x16x32_bf16(Bt[n][k], At[m][k], acc[ai][bj][m][n], 0, 0, 0); __builtin_amdgcn_s_setprio(0); } while (0)
; #define PG8_WAIT_V(n) asm volatile("s_waitcnt vmcnt(" #n ")" ::: "memory")
; #define PG8_WAIT_L(n) asm volatile("s_waitcnt lgkmcnt(" #n ")" ::: "memory")
; #define PG8_BAR __builtin_amdgcn_s_barrier()
; #define PG8_SCHED __builtin_amdgcn_sched_barrier(0)
; template <class Epi, class Sched, bool ALIGN_EPI = false, bool SP2 = false>
; __device__ __forceinline__ void gemm_phase(PG8_LAS unsigned char* lds, const Gemm g, const Sched& S, const Epi& E) {
;     ...
;             PG8_WAIT_V(8); PG8_WAIT_L(0); PG8_BAR; PG8_MMA(1, 0, At, B0); PG8_MMA(1, 1, At, B1); PG8_BAR; PG8_SCHED;
;             PG8_LDB(B0, 1, 0); PG8_LDB(B1, 1, 1); PG8_SCHED; PG8_LDA(At, 1, 0); PG8_STAGE(PG8_SA(0, 1), a2 + hstep, voffA);
;             PG8_WAIT_V(8); PG8_WAIT_L(0); PG8_BAR; PG8_MMA(0, 0, At, B0); PG8_MMA(0, 1, At, B1); PG8_BAR; PG8_SCHED;
	s_setprio 1
	s_waitcnt lgkmcnt(0)
	v_mfma_f32_16x16x32_bf16 v[60:63], v[80:83], v[188:191], v[60:63]
	v_mfma_f32_16x16x32_bf16 v[56:59], v[88:91], v[188:191], v[56:59]
	v_mfma_f32_16x16x32_bf16 v[44:47], v[80:83], v[196:199], v[44:47]
	v_mfma_f32_16x16x32_bf16 v[40:43], v[88:91], v[196:199], v[40:43]
	v_mfma_f32_16x16x32_bf16 v[28:31], v[80:83], v[204:207], v[28:31]
	v_mfma_f32_16x16x32_bf16 v[24:27], v[88:91], v[204:207], v[24:27]
	v_mfma_f32_16x16x32_bf16 v[12:15], v[80:83], v[212:215], v[12:15]
	v_mfma_f32_16x16x32_bf16 v[8:11], v[88:91], v[212:215], v[8:11]
	v_mfma_f32_16x16x32_bf16 v[60:63], v[84:87], v[192:195], v[60:63]
	v_mfma_f32_16x16x32_bf16 v[56:59], v[92:95], v[192:195], v[56:59]
	v_mfma_f32_16x16x32_bf16 v[44:47], v[84:87], v[200:203], v[44:47]
	v_mfma_f32_16x16x32_bf16 v[40:43], v[92:95], v[200:203], v[40:43]
	v_mfma_f32_16x16x32_bf16 v[28:31], v[84:87], v[208:211], v[28:31]
	v_mfma_f32_16x16x32_bf16 v[24:27], v[92:95], v[208:211], v[24:27]
	v_mfma_f32_16x16x32_bf16 v[12:15], v[84:87], v[216:219], v[12:15]
	v_mfma_f32_16x16x32_bf16 v[8:11], v[92:95], v[216:219], v[8:11]
	s_setprio 0
	s_setprio 1
	v_mfma_f32_16x16x32_bf16 v[52:55], v[164:167], v[188:191], v[52:55]
	v_mfma_f32_16x16x32_bf16 v[48:51], v[180:183], v[188:191], v[48:51]
	v_mfma_f32_16x16x32_bf16 v[36:39], v[164:167], v[196:199], v[36:39]
	v_mfma_f32_16x16x32_bf16 v[32:35], v[180:183], v[196:199], v[32:35]
	v_mfma_f32_16x16x32_bf16 v[20:23], v[164:167], v[204:207], v[20:23]
	v_mfma_f32_16x16x32_bf16 v[16:19], v[180:183], v[204:207], v[16:19]
	v_mfma_f32_16x16x32_bf16 v[4:7], v[164:167], v[212:215], v[4:7]
	v_mfma_f32_16x16x32_bf16 v[0:3], v[180:183], v[212:215], v[0:3]
	v_mfma_f32_16x16x32_bf16 v[52:55], v[176:179], v[192:195], v[52:55]
	v_mfma_f32_16x16x32_bf16 v[48:51], v[184:187], v[192:195], v[48:51]
	v_mfma_f32_16x16x32_bf16 v[36:39], v[176:179], v[200:203], v[36:39]
	v_mfma_f32_16x16x32_bf16 v[32:35], v[184:187], v[200:203], v[32:35]
	v_mfma_f32_16x16x32_bf16 v[20:23], v[176:179], v[208:211], v[20:23]
	s_setprio 2
	s_barrier
	v_mfma_f32_16x16x32_bf16 v[16:19], v[184:187], v[208:211], v[16:19]
	v_mfma_f32_16x16x32_bf16 v[4:7], v[176:179], v[216:219], v[4:7]
	v_mfma_f32_16x16x32_bf16 v[0:3], v[184:187], v[216:219], v[0:3]
	s_setprio 0
	s_add_i32 s65, 0, 0x18000
	s_add_i32 s66, 0, 0x1c000
	v_add_u32_e32 v92, s65, v169
	v_add_u32_e32 v184, s66, v169
	ds_read_b128 v[80:83], v92
	ds_read_b128 v[84:87], v92 offset:1024
	ds_read_b128 v[88:91], v92 offset:2048
	ds_read_b128 v[92:95], v92 offset:3072
	ds_read_b128 v[164:167], v184
	ds_read_b128 v[176:179], v184 offset:1024
	ds_read_b128 v[180:183], v184 offset:2048
	ds_read_b128 v[184:187], v184 offset:3072
	s_add_u32 s46, s46, 0x80000
	s_addc_u32 s47, s47, 0
	s_mov_b32 m0, s49
	v_lshl_add_u64 v[228:229], s[46:47], 0, v[144:145]
	ds_read_b128 v[188:191], v173 offset:32768
	ds_read_b128 v[192:195], v173 offset:33792
	ds_read_b128 v[196:199], v173 offset:34816
	ds_read_b128 v[200:203], v173 offset:35840
	ds_read_b128 v[204:207], v173 offset:36864
	ds_read_b128 v[208:211], v173 offset:37888
	ds_read_b128 v[212:215], v173 offset:38912
	ds_read_b128 v[216:219], v173 offset:39936
	global_load_lds_dwordx4 v[228:229], off
	v_lshl_add_u64 v[228:229], s[46:47], 0, v[150:151]
	s_mov_b32 m0, s50
	s_nop 0
	global_load_lds_dwordx4 v[228:229], off
	s_waitcnt vmcnt(8)
	s_waitcnt lgkmcnt(0)
	s_barrier
	s_setprio 1
	s_waitcnt lgkmcnt(0)
	v_mfma_f32_16x16x32_bf16 v[140:143], v[80:83], v[188:191], v[140:143]
	v_mfma_f32_16x16x32_bf16 v[136:139], v[88:91], v[188:191], v[136:139]
	v_mfma_f32_16x16x32_bf16 v[124:127], v[80:83], v[196:199], v[124:127]
	v_mfma_f32_16x16x32_bf16 v[120:123], v[88:91], v[196:199], v[120:123]
	v_mfma_f32_16x16x32_bf16 v[108:111], v[80:83], v[204:207], v[108:111]
	v_mfma_f32_16x16x32_bf16 v[104:107], v[88:91], v[204:207], v[104:107]
	v_mfma_f32_16x16x32_bf16 v[76:79], v[80:83], v[212:215], v[76:79]
	v_mfma_f32_16x16x32_bf16 v[72:75], v[88:91], v[212:215], v[72:75]
	v_mfma_f32_16x16x32_bf16 v[140:143], v[84:87], v[192:195], v[140:143]
	v_mfma_f32_16x16x32_bf16 v[136:139], v[92:95], v[192:195], v[136:139]
	v_mfma_f32_16x16x32_bf16 v[124:127], v[84:87], v[200:203], v[124:127]
	v_mfma_f32_16x16x32_bf16 v[120:123], v[92:95], v[200:203], v[120:123]
	v_mfma_f32_16x16x32_bf16 v[108:111], v[84:87], v[208:211], v[108:111]
	v_mfma_f32_16x16x32_bf16 v[104:107], v[92:95], v[208:211], v[104:107]
	v_mfma_f32_16x16x32_bf16 v[76:79], v[84:87], v[216:219], v[76:79]
	v_mfma_f32_16x16x32_bf16 v[72:75], v[92:95], v[216:219], v[72:75]
	s_setprio 0
	s_setprio 1
	v_mfma_f32_16x16x32_bf16 v[132:135], v[164:167], v[188:191], v[132:135]
	v_mfma_f32_16x16x32_bf16 v[128:131], v[180:183], v[188:191], v[128:131]
	v_mfma_f32_16x16x32_bf16 v[116:119], v[164:167], v[196:199], v[116:119]
	v_mfma_f32_16x16x32_bf16 v[112:115], v[180:183], v[196:199], v[112:115]
	v_mfma_f32_16x16x32_bf16 v[100:103], v[164:167], v[204:207], v[100:103]
	v_mfma_f32_16x16x32_bf16 v[96:99], v[180:183], v[204:207], v[96:99]
	v_mfma_f32_16x16x32_bf16 v[68:71], v[164:167], v[212:215], v[68:71]
	v_mfma_f32_16x16x32_bf16 v[64:67], v[180:183], v[212:215], v[64:67]
	v_mfma_f32_16x16x32_bf16 v[132:135], v[176:179], v[192:195], v[132:135]
	v_mfma_f32_16x16x32_bf16 v[128:131], v[184:187], v[192:195], v[128:131]
	v_mfma_f32_16x16x32_bf16 v[116:119], v[176:179], v[200:203], v[116:119]
	v_mfma_f32_16x16x32_bf16 v[112:115], v[184:187], v[200:203], v[112:115]
	v_mfma_f32_16x16x32_bf16 v[100:103], v[176:179], v[208:211], v[100:103]
	s_setprio 2
	s_barrier
; #define PG8_STAGE(bufoff, gbase, voff) do { _Pragma("unroll") for (int _i = 0; _i < 2; ++_i) \
;         __builtin_amdgcn_global_load_lds((const unsigned*)((const char*)(gbase) + (voff)[_i]), (PG8_LAS unsigned*)(lds + (bufoff) + ldsw + _i * 8192), 16, 0, 0); } while (0)
; #define PG8_LDA(dst, b, h) do { _Pragma("unroll") for (int m = 0; m < 4; ++m) _Pragma("unroll") for (int k = 0; k < 2; ++k) dst[m][k] = *(const PG8_LAS bf16x8*)(lds + PG8_SA(b, h) + aoff + m * 2048 + k * 1024); } while (0)
; #define PG8_MMA(ai, bj, At, Bt) do { __builtin_amdgcn_s_setprio(1); _Pragma("unroll") for (int m = 0; m < 4; ++m) _Pragma("unroll") for (int n = 0; n < 2; ++n) _Pragma("unroll") for (int k = 0; k < 2; ++k) \
;         acc[ai][bj][m][n] = __builtin_amdgcn_mfma_f32_16x16x32_bf16(Bt[n][k], At[m][k], acc[ai][bj][m][n], 0, 0, 0); __builtin_amdgcn_s_setprio(0); } while (0)
; #define PG8_WAIT_V(n) asm volatile("s_waitcnt vmcnt(" #n ")" ::: "memory")
; #define PG8_WAIT_L(n) asm volatile("s_waitcnt lgkmcnt(" #n ")" ::: "memory")
; #define PG8_BAR __builtin_amdgcn_s_barrier()
; #define PG8_SCHED __builtin_amdgcn_sched_barrier(0)
; template <class Epi, class Sched, bool ALIGN_EPI = false, bool SP2 = false>
; __device__ __forceinline__ void gemm_phase(PG8_LAS unsigned char* lds, const Gemm g, const Sched& S, const Epi& E) {
;     ...
;             PG8_WAIT_V(8); PG8_WAIT_L(0); PG8_BAR; PG8_MMA(0, 0, At, B0); PG8_MMA(0, 1, At, B1); PG8_BAR; PG8_SCHED;
;             PG8_LDA(At, 1, 1); PG8_STAGE(PG8_SB(1, 0), b3, voffB); PG8_STAGE(PG8_SB(1, 1), b3 + hstep, voffB); PG8_STAGE(PG8_SA(1, 0), a3, voffA);
;             PG8_WAIT_V(8); PG8_WAIT_L(0); PG8_BAR; PG8_MMA(1, 0, At, B0); PG8_MMA(1, 1, At, B1); PG8_BAR; PG8_SCHED;
;     ...
;         if constexpr (ALIGN_EPI) { if (wr == 0) PG8_BAR; }
	v_mfma_f32_16x16x32_bf16 v[96:99], v[184:187], v[208:211], v[96:99]
	v_mfma_f32_16x16x32_bf16 v[68:71], v[176:179], v[216:219], v[68:71]
	v_mfma_f32_16x16x32_bf16 v[64:67], v[184:187], v[216:219], v[64:67]
	s_setprio 0
	s_add_i32 s46, s65, s33
	v_lshl_add_u64 v[220:221], v[220:221], 0, s[8:9]
	s_mov_b32 m0, s46
	ds_read_b128 v[188:191], v173 offset:49152
	ds_read_b128 v[192:195], v173 offset:50176
	ds_read_b128 v[196:199], v173 offset:51200
	ds_read_b128 v[200:203], v173 offset:52224
	ds_read_b128 v[204:207], v173 offset:53248
	ds_read_b128 v[208:211], v173 offset:54272
	ds_read_b128 v[212:215], v173 offset:55296
	ds_read_b128 v[216:219], v173 offset:56320
	global_load_lds_dwordx4 v[220:221], off
	s_add_i32 m0, s46, 0x2000
	s_add_u32 s44, s44, 0x80080
	v_lshl_add_u64 v[220:221], v[222:223], 0, s[8:9]
	s_addc_u32 s45, s45, 0
	s_add_i32 s46, s66, s33
	global_load_lds_dwordx4 v[220:221], off
	v_lshl_add_u64 v[220:221], s[44:45], 0, v[148:149]
	s_mov_b32 m0, s46
	s_nop 0
	global_load_lds_dwordx4 v[220:221], off
	v_lshl_add_u64 v[220:221], s[44:45], 0, v[152:153]
	s_add_i32 m0, s46, 0x2000
	s_nop 0
	global_load_lds_dwordx4 v[220:221], off
	v_lshl_add_u64 v[220:221], v[224:225], 0, s[8:9]
	s_mov_b32 m0, s52
	s_nop 0
	global_load_lds_dwordx4 v[220:221], off
	v_lshl_add_u64 v[220:221], v[226:227], 0, s[8:9]
	s_mov_b32 m0, s53
	s_nop 0
	global_load_lds_dwordx4 v[220:221], off
	s_waitcnt vmcnt(8)
	s_waitcnt lgkmcnt(0)
	s_barrier
	s_setprio 1
	s_waitcnt lgkmcnt(0)
	v_mfma_f32_16x16x32_bf16 v[60:63], v[80:83], v[188:191], v[60:63]
	v_mfma_f32_16x16x32_bf16 v[56:59], v[88:91], v[188:191], v[56:59]
	v_mfma_f32_16x16x32_bf16 v[44:47], v[80:83], v[196:199], v[44:47]
	v_mfma_f32_16x16x32_bf16 v[40:43], v[88:91], v[196:199], v[40:43]
	v_mfma_f32_16x16x32_bf16 v[28:31], v[80:83], v[204:207], v[28:31]
	v_mfma_f32_16x16x32_bf16 v[24:27], v[88:91], v[204:207], v[24:27]
	v_mfma_f32_16x16x32_bf16 v[12:15], v[80:83], v[212:215], v[12:15]
	v_mfma_f32_16x16x32_bf16 v[8:11], v[88:91], v[212:215], v[8:11]
	v_mfma_f32_16x16x32_bf16 v[60:63], v[84:87], v[192:195], v[60:63]
	v_mfma_f32_16x16x32_bf16 v[56:59], v[92:95], v[192:195], v[56:59]
	v_mfma_f32_16x16x32_bf16 v[44:47], v[84:87], v[200:203], v[44:47]
	v_mfma_f32_16x16x32_bf16 v[40:43], v[92:95], v[200:203], v[40:43]
	v_mfma_f32_16x16x32_bf16 v[28:31], v[84:87], v[208:211], v[28:31]
	v_mfma_f32_16x16x32_bf16 v[24:27], v[92:95], v[208:211], v[24:27]
	v_mfma_f32_16x16x32_bf16 v[12:15], v[84:87], v[216:219], v[12:15]
	v_mfma_f32_16x16x32_bf16 v[8:11], v[92:95], v[216:219], v[8:11]
	s_setprio 0
	s_setprio 1
	v_mfma_f32_16x16x32_bf16 v[52:55], v[164:167], v[188:191], v[52:55]
	v_mfma_f32_16x16x32_bf16 v[48:51], v[180:183], v[188:191], v[48:51]
	v_mfma_f32_16x16x32_bf16 v[36:39], v[164:167], v[196:199], v[36:39]
	v_mfma_f32_16x16x32_bf16 v[32:35], v[180:183], v[196:199], v[32:35]
	v_mfma_f32_16x16x32_bf16 v[20:23], v[164:167], v[204:207], v[20:23]
	v_mfma_f32_16x16x32_bf16 v[16:19], v[180:183], v[204:207], v[16:19]
	v_mfma_f32_16x16x32_bf16 v[4:7], v[164:167], v[212:215], v[4:7]
	v_mfma_f32_16x16x32_bf16 v[0:3], v[180:183], v[212:215], v[0:3]
	v_mfma_f32_16x16x32_bf16 v[52:55], v[176:179], v[192:195], v[52:55]
	v_mfma_f32_16x16x32_bf16 v[48:51], v[184:187], v[192:195], v[48:51]
	v_mfma_f32_16x16x32_bf16 v[36:39], v[176:179], v[200:203], v[36:39]
	v_mfma_f32_16x16x32_bf16 v[32:35], v[184:187], v[200:203], v[32:35]
	v_mfma_f32_16x16x32_bf16 v[20:23], v[176:179], v[208:211], v[20:23]
	s_setprio 2
	s_barrier
	v_mfma_f32_16x16x32_bf16 v[16:19], v[184:187], v[208:211], v[16:19]
	v_mfma_f32_16x16x32_bf16 v[4:7], v[176:179], v[216:219], v[4:7]
	v_mfma_f32_16x16x32_bf16 v[0:3], v[184:187], v[216:219], v[0:3]
	s_setprio 0
	s_add_i32 s64, s64, 2
	s_add_u32 s42, s42, 0x100
	s_addc_u32 s43, s43, 0
	s_add_u32 s62, s62, 0x100
	s_addc_u32 s63, s63, 0
	s_cmp_gt_u32 s64, 29
	s_cbranch_scc0 .LBB0_1142
	s_and_b64 vcc, exec, s[10:11]
	s_cbranch_vccz .LBB0_1145
	s_barrier

; #define PG8_STAGE(bufoff, gbase, voff) do { _Pragma("unroll") for (int _i = 0; _i < 2; ++_i) \
;         __builtin_amdgcn_global_load_lds((const unsigned*)((const char*)(gbase) + (voff)[_i]), (PG8_LAS unsigned*)(lds + (bufoff) + ldsw + _i * 8192), 16, 0, 0); } while (0)
; #define PG8_LDA(dst, b, h) do { _Pragma("unroll") for (int m = 0; m < 4; ++m) _Pragma("unroll") for (int k = 0; k < 2; ++k) dst[m][k] = *(const PG8_LAS bf16x8*)(lds + PG8_SA(b, h) + aoff + m * 2048 + k * 1024); } while (0)
; #define PG8_LDB(dst, b, h) do { _Pragma("unroll") for (int n = 0; n < 2; ++n) _Pragma("unroll") for (int k = 0; k < 2; ++k) dst[n][k] = *(const PG8_LAS bf16x8*)(lds + PG8_SB(b, h) + boff + n * 2048 + k * 1024); } while (0)
; #define PG8_MMA(ai, bj, At, Bt) do { __builtin_amdgcn_s_setprio(1); _Pragma("unroll") for (int m = 0; m < 4; ++m) _Pragma("unroll") for (int n = 0; n < 2; ++n) _Pragma("unroll") for (int k = 0; k < 2; ++k) \
;         acc[ai][bj][m][n] = __builtin_amdgcn_mfma_f32_16x16x32_bf16(Bt[n][k], At[m][k], acc[ai][bj][m][n], 0, 0, 0); __builtin_amdgcn_s_setprio(0); } while (0)
; #define PG8_WAIT_V(n) asm volatile("s_waitcnt vmcnt(" #n ")" ::: "memory")
; #define PG8_WAIT_L(n) asm volatile("s_waitcnt lgkmcnt(" #n ")" ::: "memory")
; #define PG8_BAR __builtin_amdgcn_s_barrier()
; template <class Epi, class Sched, bool ALIGN_EPI = false, bool SP2 = false>
; __device__ __forceinline__ void gemm_phase(PG8_LAS unsigned char* lds, const Gemm g, const Sched& S, const Epi& E) {
;     ...
;             const bool last = (t == nt - 2);
;             const char* a1 = cA + (size_t)(t + 1) * kstep;
;             const char* a2 = last ? nA : cA + (size_t)(t + 2) * kstep; const char* b2 = last ? nB : cB + (size_t)(t + 2) * kstep;
;             const char* a3 = a2 + kstep; const char* b3 = b2 + kstep;
;             if constexpr (SP2) {
;             PG8_LDB(B0, 0, 0); PG8_LDB(B1, 0, 1); PG8_SCHED; PG8_LDA(At, 0, 0); PG8_STAGE(PG8_SA(1, 1), a1 + hstep, voffA);
;             PG8_WAIT_V(8); PG8_WAIT_L(0); PG8_BAR; PG8_MMA(0, 0, At, B0); PG8_MMA(0, 1, At, B1); PG8_BAR; PG8_SCHED;
;             PG8_LDA(At, 0, 1); PG8_STAGE(PG8_SB(0, 0), b2, voffB); PG8_STAGE(PG8_SB(0, 1), b2 + hstep, voffB); PG8_STAGE(PG8_SA(0, 0), a2, voffA);
;             PG8_WAIT_V(8); PG8_WAIT_L(0); PG8_BAR; PG8_MMA(1, 0, At, B0); PG8_MMA(1, 1, At, B1); PG8_BAR; PG8_SCHED;
.LBB0_1219:
	ds_read_b128 v[128:131], v167
	ds_read_b128 v[132:135], v167 offset:1024
	ds_read_b128 v[154:157], v167 offset:2048
	ds_read_b128 v[158:161], v167 offset:3072
	ds_read_b128 v[170:173], v168
	ds_read_b128 v[174:177], v168 offset:1024
	ds_read_b128 v[178:181], v168 offset:2048
	ds_read_b128 v[182:185], v168 offset:3072
	s_add_u32 s42, s40, 0xffe00080
	s_addc_u32 s43, s41, -1
	s_cmpk_eq_i32 s63, 0x7c
	s_cselect_b32 s45, s15, s43
	s_cselect_b32 s44, s59, s42
	s_cselect_b32 s43, s13, s62
	s_cselect_b32 s42, s60, s61
	v_lshl_add_u64 v[162:163], s[40:41], 0, v[144:145]
	s_add_i32 m0, s39, 0xc000
	ds_read_b128 v[186:189], v169
	ds_read_b128 v[190:193], v169 offset:1024
	ds_read_b128 v[194:197], v169 offset:2048
	ds_read_b128 v[198:201], v169 offset:3072
	ds_read_b128 v[202:205], v169 offset:4096
	ds_read_b128 v[206:209], v169 offset:5120
	ds_read_b128 v[210:213], v169 offset:6144
	ds_read_b128 v[214:217], v169 offset:7168
	global_load_lds_dwordx4 v[162:163], off
	v_lshl_add_u64 v[162:163], s[40:41], 0, v[148:149]
	s_add_i32 m0, s39, 0xe000
	s_nop 0
	global_load_lds_dwordx4 v[162:163], off
	s_waitcnt vmcnt(8)
	s_waitcnt lgkmcnt(0)
	s_barrier
	s_setprio 1
	s_waitcnt lgkmcnt(0)
	v_mfma_f32_16x16x32_bf16 v[124:127], v[128:131], v[186:189], v[124:127]
	v_mfma_f32_16x16x32_bf16 v[120:123], v[154:157], v[186:189], v[120:123]
	v_mfma_f32_16x16x32_bf16 v[116:119], v[128:131], v[194:197], v[116:119]
	v_mfma_f32_16x16x32_bf16 v[112:115], v[154:157], v[194:197], v[112:115]
	v_mfma_f32_16x16x32_bf16 v[108:111], v[128:131], v[202:205], v[108:111]
	v_mfma_f32_16x16x32_bf16 v[104:107], v[154:157], v[202:205], v[104:107]
	v_mfma_f32_16x16x32_bf16 v[100:103], v[128:131], v[210:213], v[100:103]
	v_mfma_f32_16x16x32_bf16 v[96:99], v[154:157], v[210:213], v[96:99]
	v_mfma_f32_16x16x32_bf16 v[124:127], v[132:135], v[190:193], v[124:127]
	v_mfma_f32_16x16x32_bf16 v[120:123], v[158:161], v[190:193], v[120:123]
	v_mfma_f32_16x16x32_bf16 v[116:119], v[132:135], v[198:201], v[116:119]
	v_mfma_f32_16x16x32_bf16 v[112:115], v[158:161], v[198:201], v[112:115]
	v_mfma_f32_16x16x32_bf16 v[108:111], v[132:135], v[206:209], v[108:111]
	v_mfma_f32_16x16x32_bf16 v[104:107], v[158:161], v[206:209], v[104:107]
	v_mfma_f32_16x16x32_bf16 v[100:103], v[132:135], v[214:217], v[100:103]
	v_mfma_f32_16x16x32_bf16 v[96:99], v[158:161], v[214:217], v[96:99]
	s_setprio 0
	s_setprio 1
	v_mfma_f32_16x16x32_bf16 v[68:71], v[170:173], v[186:189], v[68:71]
	v_mfma_f32_16x16x32_bf16 v[60:63], v[178:181], v[186:189], v[60:63]
	v_mfma_f32_16x16x32_bf16 v[52:55], v[170:173], v[194:197], v[52:55]
	v_mfma_f32_16x16x32_bf16 v[48:51], v[178:181], v[194:197], v[48:51]
	v_mfma_f32_16x16x32_bf16 v[44:47], v[170:173], v[202:205], v[44:47]
	v_mfma_f32_16x16x32_bf16 v[40:43], v[178:181], v[202:205], v[40:43]
	v_mfma_f32_16x16x32_bf16 v[36:39], v[170:173], v[210:213], v[36:39]
	v_mfma_f32_16x16x32_bf16 v[32:35], v[178:181], v[210:213], v[32:35]
	v_mfma_f32_16x16x32_bf16 v[68:71], v[174:177], v[190:193], v[68:71]
	v_mfma_f32_16x16x32_bf16 v[60:63], v[182:185], v[190:193], v[60:63]
	v_mfma_f32_16x16x32_bf16 v[52:55], v[174:177], v[198:201], v[52:55]
	v_mfma_f32_16x16x32_bf16 v[48:51], v[182:185], v[198:201], v[48:51]
	v_mfma_f32_16x16x32_bf16 v[44:47], v[174:177], v[206:209], v[44:47]
	s_setprio 2
	s_barrier
	v_mfma_f32_16x16x32_bf16 v[40:43], v[182:185], v[206:209], v[40:43]
	v_mfma_f32_16x16x32_bf16 v[36:39], v[174:177], v[214:217], v[36:39]
	v_mfma_f32_16x16x32_bf16 v[32:35], v[182:185], v[214:217], v[32:35]
	s_setprio 0
	s_add_i32 s64, s56, s33
	v_lshl_add_u64 v[162:163], s[42:43], 0, v[138:139]
	s_mov_b32 m0, s64
	ds_read_b128 v[186:189], v169 offset:16384
	ds_read_b128 v[190:193], v169 offset:17408
	ds_read_b128 v[194:197], v169 offset:18432
	ds_read_b128 v[198:201], v169 offset:19456
	ds_read_b128 v[202:205], v169 offset:20480
	ds_read_b128 v[206:209], v169 offset:21504
	ds_read_b128 v[210:213], v169 offset:22528
	ds_read_b128 v[214:217], v169 offset:23552
	global_load_lds_dwordx4 v[162:163], off
	s_add_i32 m0, s64, 0x2000
	s_add_u32 s64, s42, 0x200000
	v_lshl_add_u64 v[218:219], s[42:43], 0, v[142:143]
	s_addc_u32 s65, s43, 0
	s_add_i32 s66, s57, s33
	global_load_lds_dwordx4 v[218:219], off
	v_lshl_add_u64 v[220:221], s[64:65], 0, v[138:139]
	s_mov_b32 m0, s66
	v_lshl_add_u64 v[222:223], s[44:45], 0, v[140:141]
	global_load_lds_dwordx4 v[220:221], off
	v_lshl_add_u64 v[220:221], s[64:65], 0, v[142:143]
	s_add_i32 m0, s66, 0x2000
	s_nop 0
	global_load_lds_dwordx4 v[220:221], off
	v_lshl_add_u64 v[220:221], s[44:45], 0, v[136:137]
	s_mov_b32 m0, s39
	s_nop 0
	global_load_lds_dwordx4 v[220:221], off
	s_mov_b32 m0, s46
	s_nop 0
	global_load_lds_dwordx4 v[222:223], off
	s_waitcnt vmcnt(8)
	s_waitcnt lgkmcnt(0)
	s_barrier
; #define PG8_STAGE(bufoff, gbase, voff) do { _Pragma("unroll") for (int _i = 0; _i < 2; ++_i) \
;         __builtin_amdgcn_global_load_lds((const unsigned*)((const char*)(gbase) + (voff)[_i]), (PG8_LAS unsigned*)(lds + (bufoff) + ldsw + _i * 8192), 16, 0, 0); } while (0)
; #define PG8_LDA(dst, b, h) do { _Pragma("unroll") for (int m = 0; m < 4; ++m) _Pragma("unroll") for (int k = 0; k < 2; ++k) dst[m][k] = *(const PG8_LAS bf16x8*)(lds + PG8_SA(b, h) + aoff + m * 2048 + k * 1024); } while (0)
; #define PG8_LDB(dst, b, h) do { _Pragma("unroll") for (int n = 0; n < 2; ++n) _Pragma("unroll") for (int k = 0; k < 2; ++k) dst[n][k] = *(const PG8_LAS bf16x8*)(lds + PG8_SB(b, h) + boff + n * 2048 + k * 1024); } while (0)
; #define PG8_MMA(ai, bj, At, Bt) do { __builtin_amdgcn_s_setprio(1); _Pragma("unroll") for (int m = 0; m < 4; ++m) _Pragma("unroll") for (int n = 0; n < 2; ++n) _Pragma("unroll") for (int k = 0; k < 2; ++k) \
;         acc[ai][bj][m][n] = __builtin_amdgcn_mfma_f32_16x16x32_bf16(Bt[n][k], At[m][k], acc[ai][bj][m][n], 0, 0, 0); __builtin_amdgcn_s_setprio(0); } while (0)
; #define PG8_WAIT_V(n) asm volatile("s_waitcnt vmcnt(" #n ")" ::: "memory")
; #define PG8_WAIT_L(n) asm volatile("s_waitcnt lgkmcnt(" #n ")" ::: "memory")
; #define PG8_BAR __builtin_amdgcn_s_barrier()
; #define PG8_SCHED __builtin_amdgcn_sched_barrier(0)
; template <class Epi, class Sched, bool ALIGN_EPI = false, bool SP2 = false>
; __device__ __forceinline__ void gemm_phase(PG8_LAS unsigned char* lds, const Gemm g, const Sched& S, const Epi& E) {
;     ...
;             PG8_WAIT_V(8); PG8_WAIT_L(0); PG8_BAR; PG8_MMA(1, 0, At, B0); PG8_MMA(1, 1, At, B1); PG8_BAR; PG8_SCHED;
;             PG8_LDB(B0, 1, 0); PG8_LDB(B1, 1, 1); PG8_SCHED; PG8_LDA(At, 1, 0); PG8_STAGE(PG8_SA(0, 1), a2 + hstep, voffA);
;             PG8_WAIT_V(8); PG8_WAIT_L(0); PG8_BAR; PG8_MMA(0, 0, At, B0); PG8_MMA(0, 1, At, B1); PG8_BAR; PG8_SCHED;
	s_setprio 1
	s_waitcnt lgkmcnt(0)
	v_mfma_f32_16x16x32_bf16 v[92:95], v[128:131], v[186:189], v[92:95]
	v_mfma_f32_16x16x32_bf16 v[88:91], v[154:157], v[186:189], v[88:91]
	v_mfma_f32_16x16x32_bf16 v[84:87], v[128:131], v[194:197], v[84:87]
	v_mfma_f32_16x16x32_bf16 v[80:83], v[154:157], v[194:197], v[80:83]
	v_mfma_f32_16x16x32_bf16 v[76:79], v[128:131], v[202:205], v[76:79]
	v_mfma_f32_16x16x32_bf16 v[72:75], v[154:157], v[202:205], v[72:75]
	v_mfma_f32_16x16x32_bf16 v[64:67], v[128:131], v[210:213], v[64:67]
	v_mfma_f32_16x16x32_bf16 v[56:59], v[154:157], v[210:213], v[56:59]
	v_mfma_f32_16x16x32_bf16 v[92:95], v[132:135], v[190:193], v[92:95]
	v_mfma_f32_16x16x32_bf16 v[88:91], v[158:161], v[190:193], v[88:91]
	v_mfma_f32_16x16x32_bf16 v[84:87], v[132:135], v[198:201], v[84:87]
	v_mfma_f32_16x16x32_bf16 v[80:83], v[158:161], v[198:201], v[80:83]
	v_mfma_f32_16x16x32_bf16 v[76:79], v[132:135], v[206:209], v[76:79]
	v_mfma_f32_16x16x32_bf16 v[72:75], v[158:161], v[206:209], v[72:75]
	v_mfma_f32_16x16x32_bf16 v[64:67], v[132:135], v[214:217], v[64:67]
	v_mfma_f32_16x16x32_bf16 v[56:59], v[158:161], v[214:217], v[56:59]
	s_setprio 0
	s_setprio 1
	v_mfma_f32_16x16x32_bf16 v[28:31], v[170:173], v[186:189], v[28:31]
	v_mfma_f32_16x16x32_bf16 v[24:27], v[178:181], v[186:189], v[24:27]
	v_mfma_f32_16x16x32_bf16 v[20:23], v[170:173], v[194:197], v[20:23]
	v_mfma_f32_16x16x32_bf16 v[16:19], v[178:181], v[194:197], v[16:19]
	v_mfma_f32_16x16x32_bf16 v[12:15], v[170:173], v[202:205], v[12:15]
	v_mfma_f32_16x16x32_bf16 v[8:11], v[178:181], v[202:205], v[8:11]
	v_mfma_f32_16x16x32_bf16 v[4:7], v[170:173], v[210:213], v[4:7]
	v_mfma_f32_16x16x32_bf16 v[0:3], v[178:181], v[210:213], v[0:3]
	v_mfma_f32_16x16x32_bf16 v[28:31], v[174:177], v[190:193], v[28:31]
	v_mfma_f32_16x16x32_bf16 v[24:27], v[182:185], v[190:193], v[24:27]
	v_mfma_f32_16x16x32_bf16 v[20:23], v[174:177], v[198:201], v[20:23]
	v_mfma_f32_16x16x32_bf16 v[16:19], v[182:185], v[198:201], v[16:19]
	v_mfma_f32_16x16x32_bf16 v[12:15], v[174:177], v[206:209], v[12:15]
	s_setprio 2
	s_barrier
	v_mfma_f32_16x16x32_bf16 v[8:11], v[182:185], v[206:209], v[8:11]
	v_mfma_f32_16x16x32_bf16 v[4:7], v[174:177], v[214:217], v[4:7]
	v_mfma_f32_16x16x32_bf16 v[0:3], v[182:185], v[214:217], v[0:3]
	s_setprio 0
	s_add_i32 s64, 0, 0x18000
	s_add_i32 s65, 0, 0x1c000
	v_add_u32_e32 v158, s64, v165
	v_add_u32_e32 v182, s65, v165
	ds_read_b128 v[128:131], v158
	ds_read_b128 v[132:135], v158 offset:1024
	ds_read_b128 v[154:157], v158 offset:2048
	ds_read_b128 v[158:161], v158 offset:3072
	ds_read_b128 v[170:173], v182
	ds_read_b128 v[174:177], v182 offset:1024
	ds_read_b128 v[178:181], v182 offset:2048
	ds_read_b128 v[182:185], v182 offset:3072
	s_add_u32 s44, s44, 0x200000
	s_addc_u32 s45, s45, 0
	s_mov_b32 m0, s47
	v_lshl_add_u64 v[224:225], s[44:45], 0, v[136:137]
	ds_read_b128 v[186:189], v169 offset:32768
	ds_read_b128 v[190:193], v169 offset:33792
	ds_read_b128 v[194:197], v169 offset:34816
	ds_read_b128 v[198:201], v169 offset:35840
	ds_read_b128 v[202:205], v169 offset:36864
	ds_read_b128 v[206:209], v169 offset:37888
	ds_read_b128 v[210:213], v169 offset:38912
	ds_read_b128 v[214:217], v169 offset:39936
	global_load_lds_dwordx4 v[224:225], off
	v_lshl_add_u64 v[224:225], s[44:45], 0, v[140:141]
	s_mov_b32 m0, s48
	s_nop 0
	global_load_lds_dwordx4 v[224:225], off
	s_waitcnt vmcnt(8)
	s_waitcnt lgkmcnt(0)
	s_barrier
	s_setprio 1
	s_waitcnt lgkmcnt(0)
	v_mfma_f32_16x16x32_bf16 v[124:127], v[128:131], v[186:189], v[124:127]
	v_mfma_f32_16x16x32_bf16 v[120:123], v[154:157], v[186:189], v[120:123]
	v_mfma_f32_16x16x32_bf16 v[116:119], v[128:131], v[194:197], v[116:119]
	v_mfma_f32_16x16x32_bf16 v[112:115], v[154:157], v[194:197], v[112:115]
	v_mfma_f32_16x16x32_bf16 v[108:111], v[128:131], v[202:205], v[108:111]
	v_mfma_f32_16x16x32_bf16 v[104:107], v[154:157], v[202:205], v[104:107]
	v_mfma_f32_16x16x32_bf16 v[100:103], v[128:131], v[210:213], v[100:103]
	v_mfma_f32_16x16x32_bf16 v[96:99], v[154:157], v[210:213], v[96:99]
	v_mfma_f32_16x16x32_bf16 v[124:127], v[132:135], v[190:193], v[124:127]
	v_mfma_f32_16x16x32_bf16 v[120:123], v[158:161], v[190:193], v[120:123]
	v_mfma_f32_16x16x32_bf16 v[116:119], v[132:135], v[198:201], v[116:119]
	v_mfma_f32_16x16x32_bf16 v[112:115], v[158:161], v[198:201], v[112:115]
	v_mfma_f32_16x16x32_bf16 v[108:111], v[132:135], v[206:209], v[108:111]
	v_mfma_f32_16x16x32_bf16 v[104:107], v[158:161], v[206:209], v[104:107]
	v_mfma_f32_16x16x32_bf16 v[100:103], v[132:135], v[214:217], v[100:103]
	v_mfma_f32_16x16x32_bf16 v[96:99], v[158:161], v[214:217], v[96:99]
	s_setprio 0
	s_setprio 1
	v_mfma_f32_16x16x32_bf16 v[68:71], v[170:173], v[186:189], v[68:71]
	v_mfma_f32_16x16x32_bf16 v[60:63], v[178:181], v[186:189], v[60:63]
	v_mfma_f32_16x16x32_bf16 v[52:55], v[170:173], v[194:197], v[52:55]
	v_mfma_f32_16x16x32_bf16 v[48:51], v[178:181], v[194:197], v[48:51]
	v_mfma_f32_16x16x32_bf16 v[44:47], v[170:173], v[202:205], v[44:47]
	v_mfma_f32_16x16x32_bf16 v[40:43], v[178:181], v[202:205], v[40:43]
	v_mfma_f32_16x16x32_bf16 v[36:39], v[170:173], v[210:213], v[36:39]
	v_mfma_f32_16x16x32_bf16 v[32:35], v[178:181], v[210:213], v[32:35]
	v_mfma_f32_16x16x32_bf16 v[68:71], v[174:177], v[190:193], v[68:71]
	v_mfma_f32_16x16x32_bf16 v[60:63], v[182:185], v[190:193], v[60:63]
	v_mfma_f32_16x16x32_bf16 v[52:55], v[174:177], v[198:201], v[52:55]
	v_mfma_f32_16x16x32_bf16 v[48:51], v[182:185], v[198:201], v[48:51]
	v_mfma_f32_16x16x32_bf16 v[44:47], v[174:177], v[206:209], v[44:47]
	s_setprio 2
	s_barrier
; #define PG8_STAGE(bufoff, gbase, voff) do { _Pragma("unroll") for (int _i = 0; _i < 2; ++_i) \
;         __builtin_amdgcn_global_load_lds((const unsigned*)((const char*)(gbase) + (voff)[_i]), (PG8_LAS unsigned*)(lds + (bufoff) + ldsw + _i * 8192), 16, 0, 0); } while (0)
; #define PG8_LDA(dst, b, h) do { _Pragma("unroll") for (int m = 0; m < 4; ++m) _Pragma("unroll") for (int k = 0; k < 2; ++k) dst[m][k] = *(const PG8_LAS bf16x8*)(lds + PG8_SA(b, h) + aoff + m * 2048 + k * 1024); } while (0)
; #define PG8_MMA(ai, bj, At, Bt) do { __builtin_amdgcn_s_setprio(1); _Pragma("unroll") for (int m = 0; m < 4; ++m) _Pragma("unroll") for (int n = 0; n < 2; ++n) _Pragma("unroll") for (int k = 0; k < 2; ++k) \
;         acc[ai][bj][m][n] = __builtin_amdgcn_mfma_f32_16x16x32_bf16(Bt[n][k], At[m][k], acc[ai][bj][m][n], 0, 0, 0); __builtin_amdgcn_s_setprio(0); } while (0)
; #define PG8_WAIT_V(n) asm volatile("s_waitcnt vmcnt(" #n ")" ::: "memory")
; #define PG8_WAIT_L(n) asm volatile("s_waitcnt lgkmcnt(" #n ")" ::: "memory")
; #define PG8_BAR __builtin_amdgcn_s_barrier()
; #define PG8_SCHED __builtin_amdgcn_sched_barrier(0)
; template <class Epi, class Sched, bool ALIGN_EPI = false, bool SP2 = false>
; __device__ __forceinline__ void gemm_phase(PG8_LAS unsigned char* lds, const Gemm g, const Sched& S, const Epi& E) {
;     ...
;             PG8_WAIT_V(8); PG8_WAIT_L(0); PG8_BAR; PG8_MMA(0, 0, At, B0); PG8_MMA(0, 1, At, B1); PG8_BAR; PG8_SCHED;
;             PG8_LDA(At, 1, 1); PG8_STAGE(PG8_SB(1, 0), b3, voffB); PG8_STAGE(PG8_SB(1, 1), b3 + hstep, voffB); PG8_STAGE(PG8_SA(1, 0), a3, voffA);
;             PG8_WAIT_V(8); PG8_WAIT_L(0); PG8_BAR; PG8_MMA(1, 0, At, B0); PG8_MMA(1, 1, At, B1); PG8_BAR; PG8_SCHED;
;     ...
;         if constexpr (ALIGN_EPI) { if (wr == 0) PG8_BAR; }
	v_mfma_f32_16x16x32_bf16 v[40:43], v[182:185], v[206:209], v[40:43]
	v_mfma_f32_16x16x32_bf16 v[36:39], v[174:177], v[214:217], v[36:39]
	v_mfma_f32_16x16x32_bf16 v[32:35], v[182:185], v[214:217], v[32:35]
	s_setprio 0
	s_add_i32 s44, s64, s33
	v_lshl_add_u64 v[162:163], v[162:163], 0, s[8:9]
	s_mov_b32 m0, s44
	ds_read_b128 v[186:189], v169 offset:49152
	ds_read_b128 v[190:193], v169 offset:50176
	ds_read_b128 v[194:197], v169 offset:51200
	ds_read_b128 v[198:201], v169 offset:52224
	ds_read_b128 v[202:205], v169 offset:53248
	ds_read_b128 v[206:209], v169 offset:54272
	ds_read_b128 v[210:213], v169 offset:55296
	ds_read_b128 v[214:217], v169 offset:56320
	global_load_lds_dwordx4 v[162:163], off
	s_add_i32 m0, s44, 0x2000
	s_add_u32 s42, s42, 0x200080
	v_lshl_add_u64 v[162:163], v[218:219], 0, s[8:9]
	s_addc_u32 s43, s43, 0
	s_add_i32 s44, s65, s33
	global_load_lds_dwordx4 v[162:163], off
	v_lshl_add_u64 v[162:163], s[42:43], 0, v[138:139]
	s_mov_b32 m0, s44
	s_nop 0
	global_load_lds_dwordx4 v[162:163], off
	v_lshl_add_u64 v[162:163], s[42:43], 0, v[142:143]
	s_add_i32 m0, s44, 0x2000
	s_nop 0
	global_load_lds_dwordx4 v[162:163], off
	v_lshl_add_u64 v[162:163], v[220:221], 0, s[8:9]
	s_mov_b32 m0, s52
	s_nop 0
	global_load_lds_dwordx4 v[162:163], off
	v_lshl_add_u64 v[162:163], v[222:223], 0, s[8:9]
	s_mov_b32 m0, s53
	s_nop 0
	global_load_lds_dwordx4 v[162:163], off
	s_waitcnt vmcnt(8)
	s_waitcnt lgkmcnt(0)
	s_barrier
	s_setprio 1
	s_waitcnt lgkmcnt(0)
	v_mfma_f32_16x16x32_bf16 v[92:95], v[128:131], v[186:189], v[92:95]
	v_mfma_f32_16x16x32_bf16 v[88:91], v[154:157], v[186:189], v[88:91]
	v_mfma_f32_16x16x32_bf16 v[84:87], v[128:131], v[194:197], v[84:87]
	v_mfma_f32_16x16x32_bf16 v[80:83], v[154:157], v[194:197], v[80:83]
	v_mfma_f32_16x16x32_bf16 v[76:79], v[128:131], v[202:205], v[76:79]
	v_mfma_f32_16x16x32_bf16 v[72:75], v[154:157], v[202:205], v[72:75]
	v_mfma_f32_16x16x32_bf16 v[64:67], v[128:131], v[210:213], v[64:67]
	v_mfma_f32_16x16x32_bf16 v[56:59], v[154:157], v[210:213], v[56:59]
	v_mfma_f32_16x16x32_bf16 v[92:95], v[132:135], v[190:193], v[92:95]
	v_mfma_f32_16x16x32_bf16 v[88:91], v[158:161], v[190:193], v[88:91]
	v_mfma_f32_16x16x32_bf16 v[84:87], v[132:135], v[198:201], v[84:87]
	v_mfma_f32_16x16x32_bf16 v[80:83], v[158:161], v[198:201], v[80:83]
	v_mfma_f32_16x16x32_bf16 v[76:79], v[132:135], v[206:209], v[76:79]
	v_mfma_f32_16x16x32_bf16 v[72:75], v[158:161], v[206:209], v[72:75]
	v_mfma_f32_16x16x32_bf16 v[64:67], v[132:135], v[214:217], v[64:67]
	v_mfma_f32_16x16x32_bf16 v[56:59], v[158:161], v[214:217], v[56:59]
	s_setprio 0
	s_setprio 1
	v_mfma_f32_16x16x32_bf16 v[28:31], v[170:173], v[186:189], v[28:31]
	v_mfma_f32_16x16x32_bf16 v[24:27], v[178:181], v[186:189], v[24:27]
	v_mfma_f32_16x16x32_bf16 v[20:23], v[170:173], v[194:197], v[20:23]
	v_mfma_f32_16x16x32_bf16 v[16:19], v[178:181], v[194:197], v[16:19]
	v_mfma_f32_16x16x32_bf16 v[12:15], v[170:173], v[202:205], v[12:15]
	v_mfma_f32_16x16x32_bf16 v[8:11], v[178:181], v[202:205], v[8:11]
	v_mfma_f32_16x16x32_bf16 v[4:7], v[170:173], v[210:213], v[4:7]
	v_mfma_f32_16x16x32_bf16 v[0:3], v[178:181], v[210:213], v[0:3]
	v_mfma_f32_16x16x32_bf16 v[28:31], v[174:177], v[190:193], v[28:31]
	v_mfma_f32_16x16x32_bf16 v[24:27], v[182:185], v[190:193], v[24:27]
	v_mfma_f32_16x16x32_bf16 v[20:23], v[174:177], v[198:201], v[20:23]
	v_mfma_f32_16x16x32_bf16 v[16:19], v[182:185], v[198:201], v[16:19]
	v_mfma_f32_16x16x32_bf16 v[12:15], v[174:177], v[206:209], v[12:15]
	s_setprio 2
	s_barrier
	v_mfma_f32_16x16x32_bf16 v[8:11], v[182:185], v[206:209], v[8:11]
	v_mfma_f32_16x16x32_bf16 v[4:7], v[174:177], v[214:217], v[4:7]
	v_mfma_f32_16x16x32_bf16 v[0:3], v[182:185], v[214:217], v[0:3]
	s_setprio 0
	s_add_i32 s63, s63, 2
	s_add_u32 s40, s40, 0x100
	s_addc_u32 s41, s41, 0
	s_add_u32 s61, s61, 0x100
	s_addc_u32 s62, s62, 0
	s_cmpk_gt_u32 s63, 0x7d
	s_cbranch_scc0 .LBB0_1219
	s_and_b64 vcc, exec, s[10:11]
	s_cbranch_vccz .LBB0_1222
	s_barrier
